# ResLN epilogues: counted vmcnt at first use of each residual/gain load instead of vmcnt(0) for all, never-taken execz around the stats store dropped, vmcnt(16) before the hoisted second-half copies
# baseline (speedup 1.0000x reference)
; #define LAS __attribute__((address_space(3)))
;     __device__ __forceinline__ void operator()(const f32x4 (&acc)[2][2][4][2], const Unit& u, int wr, int wc, int fr, int fq, const EpiCtx& X) const {
;     ...
;         char* yb = nullptr; char* xb = (char*)(XB + (size_t)u.pm * BM * DM + (size_t)(u.pn * 4 + wc) * (BM * 64));
;         unsigned lo = (unsigned)((wr * 64 + fe) * 64 + o32 + 8 * fq) * 2u; EPI_OPAQUE(lo);
;         const int col = u.pn * BM + wc * 64 + o32 + 8 * fq;
;         f32x4 g0, g1, b0, b1;
;         if (RESN) { ensure_tbl(PSp, sidp, u.pm, X);
;             g0 = *(const f32x4*)(gp + col); g1 = *(const f32x4*)(gp + col + 4); b0 = *(const f32x4*)(bp + col) * ALPHA; b1 = *(const f32x4*)(bp + col + 4) * ALPHA; }
;         const LAS f32x2* tbl = (const LAS f32x2*)(X.lds + TBL_OFF) + wr * 64 + fe;
;         f32x2* ps = PSn + ((size_t)u.pm * BM + wr * 64 + fe) * 64 + u.pn * 4 + wc;
; #pragma unroll
;         for (int ai = 0; ai < 2; ++ai) {
;             u32x4 raw[8];
; #pragma unroll
;             for (int m = 0; m < 4; ++m) { const unsigned off = lo + (unsigned)((ai * HALF + m * 16) * 64) * 2u; raw[2 * m] = *(const u32x4*)(xb + off); raw[2 * m + 1] = *(const u32x4*)(xb + off + 128); }
; #pragma unroll
;             for (int m = 0; m < 4; ++m) {
;                 const int rl = ai * HALF + m * 16; const unsigned off = lo + (unsigned)(rl * 64) * 2u;
;                 const f32x4 o0a = acc[ai][0][m][0], o0b = acc[ai][0][m][1], o1a = acc[ai][1][m][0], o1b = acc[ai][1][m][1];
;                 const f32x4 ra_ = dpp_swap1(odd ? o0a : o1a), rb_ = dpp_swap1(odd ? o0b : o1b);
;                 const f32x4 pa[2] = {odd ? ra_ : o0a, odd ? o1a : ra_}, pb[2] = {odd ? rb_ : o0b, odd ? o1b : rb_};
; #pragma unroll
;                 for (int q = 0; q < 2; ++q) {
;                     const u32x4 w0 = raw[2 * m + q];
;                     const f32x4 r0 = (f32x4){bf_lo(w0.x), bf_hi(w0.x), bf_lo(w0.y), bf_hi(w0.y)}, r1 = (f32x4){bf_lo(w0.z), bf_hi(w0.z), bf_lo(w0.w), bf_hi(w0.w)};
;                     f32x4 y0, y1;
;                     if (RESN) { const f32x2 t = tbl[rl + q]; const float mu = t.x, ra = t.y * ALPHA; y0 = (r0 - mu) * ra * g0 + b0 + pa[q]; y1 = (r1 - mu) * ra * g1 + b1 + pb[q]; }
;                     else { y0 = r0 * ALPHA + pa[q]; y1 = r1 * ALPHA + pb[q]; }
;                     { const u32x4 w = pack8f(y0, y1); *(u32x4*)(xb + off + q * 128) = w;
.LBB0_582:
	s_ashr_i32 s57, s56, 31
	s_lshl_b64 s[52:53], s[56:57], 21
	s_add_u32 s21, s46, s52
	s_addc_u32 s23, s47, s53
	s_lshl_b32 s58, s54, 2
	s_or_b32 s52, s58, s41
	s_ashr_i32 s53, s52, 31
	s_lshl_b64 s[52:53], s[52:53], 15
	s_add_u32 s54, s21, s52
	s_addc_u32 s55, s23, s53
	v_mov_b32_e32 v164, v183
	global_load_dwordx4 v[194:197], v164, s[54:55]
	v_add_u32_e32 v180, 0x800, v164
	v_add_u32_e32 v178, 0x1000, v164
	v_add_u32_e32 v176, 0x1800, v164
	global_load_dwordx4 v[152:155], v164, s[54:55] offset:128
	global_load_dwordx4 v[148:151], v180, s[54:55]
	global_load_dwordx4 v[144:147], v180, s[54:55] offset:128
	global_load_dwordx4 v[140:143], v178, s[54:55]
	global_load_dwordx4 v[136:139], v178, s[54:55] offset:128
	global_load_dwordx4 v[132:135], v176, s[54:55]
	global_load_dwordx4 v[120:123], v176, s[54:55] offset:128
	v_cndmask_b32_e64 v199, v129, v117, s[8:9]
	v_cndmask_b32_e64 v200, v128, v116, s[8:9]
	v_mov_b32_e32 v177, 0
	v_mov_b32_e32 v181, 0
	v_cndmask_b32_e64 v201, v127, v115, s[8:9]
	v_cndmask_b32_e64 v202, v126, v114, s[8:9]
	v_cndmask_b32_e64 v203, v125, v113, s[8:9]
	v_cndmask_b32_e64 v204, v124, v112, s[8:9]
	v_mov_b32_e32 v189, 0
	v_mov_b32_e32 v191, 0
	v_mov_b32_e32 v190, 0
	v_mov_b32_e32 v192, 0
	v_cndmask_b32_e64 v193, v131, v119, s[8:9]
	v_cndmask_b32_e64 v198, v130, v118, s[8:9]
	v_mov_b32_e32 v179, 0
	v_mov_b32_e32 v188, 0
	v_mov_b32_dpp v177, v200 quad_perm:[1,0,3,2] row_mask:0xf bank_mask:0xf
	v_mov_b32_dpp v181, v199 quad_perm:[1,0,3,2] row_mask:0xf bank_mask:0xf
	v_mov_b32_dpp v189, v204 quad_perm:[1,0,3,2] row_mask:0xf bank_mask:0xf
	v_mov_b32_dpp v191, v203 quad_perm:[1,0,3,2] row_mask:0xf bank_mask:0xf
	v_mov_b32_dpp v190, v202 quad_perm:[1,0,3,2] row_mask:0xf bank_mask:0xf
	v_mov_b32_dpp v192, v201 quad_perm:[1,0,3,2] row_mask:0xf bank_mask:0xf
	v_mov_b32_dpp v179, v198 quad_perm:[1,0,3,2] row_mask:0xf bank_mask:0xf
	v_mov_b32_dpp v188, v193 quad_perm:[1,0,3,2] row_mask:0xf bank_mask:0xf
	v_cndmask_b32_e64 v129, v181, v129, s[8:9]
	v_cndmask_b32_e64 v128, v177, v128, s[8:9]
	v_cndmask_b32_e64 v125, v191, v125, s[8:9]
	v_cndmask_b32_e64 v124, v189, v124, s[8:9]
	v_cndmask_b32_e64 v127, v192, v127, s[8:9]
	v_cndmask_b32_e64 v126, v190, v126, s[8:9]
	v_and_b32_e32 v206, 64, v187
	v_cndmask_b32_e64 v131, v188, v131, s[8:9]
	v_cndmask_b32_e64 v130, v179, v130, s[8:9]
	v_xor_b32_e32 v205, 16, v187
	v_add_u32_e32 v193, 64, v206
	v_cmp_lt_i32_e32 vcc, v205, v193
	s_lshl_b64 s[52:53], s[56:57], 17
	v_lshl_add_u64 v[198:199], v[166:167], 0, s[52:53]
	v_cndmask_b32_e32 v210, v187, v205, vcc
	s_ashr_i32 s59, s58, 31
	v_add_u32_e32 v246, 0x4000, v164
	v_add_u32_e32 v247, 0x4800, v164
	global_load_dwordx4 v[230:233], v246, s[54:55]
	global_load_dwordx4 v[234:237], v246, s[54:55] offset:128
	global_load_dwordx4 v[238:241], v247, s[54:55]
	global_load_dwordx4 v[242:245], v247, s[54:55] offset:128
	s_waitcnt vmcnt(11)
	v_lshlrev_b32_e32 v200, 16, v194
	v_and_b32_e32 v201, 0xffff0000, v194
	v_lshlrev_b32_e32 v202, 16, v196
	v_and_b32_e32 v203, 0xffff0000, v196
	v_lshlrev_b32_e32 v196, 16, v197
	v_and_b32_e32 v197, 0xffff0000, v197
	v_lshlrev_b32_e32 v194, 16, v195
	v_and_b32_e32 v195, 0xffff0000, v195
	v_pk_fma_f32 v[128:129], v[200:201], s[18:19], v[128:129] op_sel_hi:[1,0,1]
	v_pk_fma_f32 v[126:127], v[196:197], s[18:19], v[126:127] op_sel_hi:[1,0,1]
	v_pk_fma_f32 v[124:125], v[202:203], s[18:19], v[124:125] op_sel_hi:[1,0,1]
	v_pk_fma_f32 v[130:131], v[194:195], s[18:19], v[130:131] op_sel_hi:[1,0,1]
	v_cvt_pk_bf16_f32 v194, v128, v129
	s_nop 0
	v_cvt_pk_bf16_f32 v195, v130, v131
	v_cvt_pk_bf16_f32 v196, v124, v125
	v_cvt_pk_bf16_f32 v197, v126, v127
	v_lshlrev_b32_e32 v124, 16, v194
	v_and_b32_e32 v126, 0xffff0000, v194
	v_lshlrev_b32_e32 v128, 16, v195
	v_and_b32_e32 v200, 0xffff0000, v195
	v_lshlrev_b32_e32 v202, 16, v196
	v_and_b32_e32 v204, 0xffff0000, v196
	v_lshlrev_b32_e32 v206, 16, v197
	v_and_b32_e32 v208, 0xffff0000, v197
	v_mul_f32_e32 v125, v124, v124
	v_mul_f32_e32 v127, v126, v126
	v_mul_f32_e32 v129, v128, v128
	v_mul_f32_e32 v201, v200, v200
	v_mul_f32_e32 v203, v202, v202
	v_mul_f32_e32 v205, v204, v204
	v_mul_f32_e32 v207, v206, v206
	v_mul_f32_e32 v209, v208, v208
	v_pk_add_f32 v[124:125], v[124:125], v[126:127]
	v_pk_add_f32 v[126:127], v[128:129], v[200:201]
	v_pk_add_f32 v[128:129], v[206:207], v[208:209]
	v_pk_add_f32 v[124:125], v[124:125], v[126:127]
	v_pk_add_f32 v[126:127], v[202:203], v[204:205]
	v_lshlrev_b32_e32 v130, 2, v210
	v_pk_add_f32 v[126:127], v[126:127], v[128:129]
	v_xor_b32_e32 v128, 32, v187
	v_pk_add_f32 v[124:125], v[124:125], v[126:127]
	v_mov_b32_e32 v126, 0
	v_mov_b32_e32 v127, 0
	v_cmp_lt_i32_e32 vcc, v128, v193
	v_mov_b32_dpp v126, v124 quad_perm:[1,0,3,2] row_mask:0xf bank_mask:0xf
	v_mov_b32_dpp v127, v125 quad_perm:[1,0,3,2] row_mask:0xf bank_mask:0xf
	v_pk_add_f32 v[124:125], v[124:125], v[126:127]
	ds_bpermute_b32 v126, v130, v124
	ds_bpermute_b32 v127, v130, v125
	v_cndmask_b32_e32 v128, v187, v128, vcc
	v_lshlrev_b32_e32 v131, 2, v128
	global_store_dwordx4 v164, v[194:197], s[54:55]
	s_waitcnt lgkmcnt(0)
	v_pk_add_f32 v[126:127], v[124:125], v[126:127]
	ds_bpermute_b32 v128, v131, v126
	ds_bpermute_b32 v129, v131, v127
	v_lshl_add_u64 v[124:125], s[58:59], 3, v[198:199]
	v_lshl_add_u64 v[124:125], v[124:125], 0, s[14:15]
	s_and_saveexec_b64 s[52:53], s[10:11]
	s_waitcnt lgkmcnt(0)
	v_pk_add_f32 v[126:127], v[126:127], v[128:129]
	global_store_dwordx2 v[124:125], v[126:127], off
; __device__ __forceinline__ u32x4 pack8f(f32x4 a, f32x4 b) { u32x4 w; w.x = cvt_pk_bf16(a[0], a[1]); w.y = cvt_pk_bf16(a[2], a[3]); w.z = cvt_pk_bf16(b[0], b[1]); w.w = cvt_pk_bf16(b[2], b[3]); return w; }
;     __device__ __forceinline__ void operator()(const f32x4 (&acc)[2][2][4][2], const Unit& u, int wr, int wc, int fr, int fq, const EpiCtx& X) const {
;     ...
;             for (int m = 0; m < 4; ++m) {
;                 const int rl = ai * HALF + m * 16; const unsigned off = lo + (unsigned)(rl * 64) * 2u;
;                 const f32x4 o0a = acc[ai][0][m][0], o0b = acc[ai][0][m][1], o1a = acc[ai][1][m][0], o1b = acc[ai][1][m][1];
;                 const f32x4 ra_ = dpp_swap1(odd ? o0a : o1a), rb_ = dpp_swap1(odd ? o0b : o1b);
;                 const f32x4 pa[2] = {odd ? ra_ : o0a, odd ? o1a : ra_}, pb[2] = {odd ? rb_ : o0b, odd ? o1b : rb_};
; #pragma unroll
;                 for (int q = 0; q < 2; ++q) {
;                     const u32x4 w0 = raw[2 * m + q];
;                     const f32x4 r0 = (f32x4){bf_lo(w0.x), bf_hi(w0.x), bf_lo(w0.y), bf_hi(w0.y)}, r1 = (f32x4){bf_lo(w0.z), bf_hi(w0.z), bf_lo(w0.w), bf_hi(w0.w)};
;                     f32x4 y0, y1;
;                     if (RESN) { const f32x2 t = tbl[rl + q]; const float mu = t.x, ra = t.y * ALPHA; y0 = (r0 - mu) * ra * g0 + b0 + pa[q]; y1 = (r1 - mu) * ra * g1 + b1 + pb[q]; }
;                     else { y0 = r0 * ALPHA + pa[q]; y1 = r1 * ALPHA + pb[q]; }
;                     { const u32x4 w = pack8f(y0, y1); *(u32x4*)(xb + off + q * 128) = w;
;                         y0 = (f32x4){bf_lo(w.x), bf_hi(w.x), bf_lo(w.y), bf_hi(w.y)}; y1 = (f32x4){bf_lo(w.z), bf_hi(w.z), bf_lo(w.w), bf_hi(w.w)}; }
;                     float sa = ((y0[0] + y0[1]) + (y0[2] + y0[3])) + ((y1[0] + y1[1]) + (y1[2] + y1[3]));
;                     float sb = ((y0[0] * y0[0] + y0[1] * y0[1]) + (y0[2] * y0[2] + y0[3] * y0[3])) + ((y1[0] * y1[0] + y1[1] * y1[1]) + (y1[2] * y1[2] + y1[3] * y1[3]));
;                     sa += dpp_x1(sa);
;                     sb += dpp_x1(sb);
;                     sa += __shfl_xor(sa, 16); sa += __shfl_xor(sa, 32); sb += __shfl_xor(sb, 16); sb += __shfl_xor(sb, 32);
;                     if (fq == 0 && !odd) ps[(size_t)(rl + q) * 64] = (f32x2){sa, sb};
.LBB0_584:
	s_or_b64 exec, exec, s[52:53]
	v_cndmask_b32_e64 v117, v117, v181, s[8:9]
	v_cndmask_b32_e64 v116, v116, v177, s[8:9]
	v_cndmask_b32_e64 v119, v119, v188, s[8:9]
	v_cndmask_b32_e64 v118, v118, v179, s[8:9]
	v_cndmask_b32_e64 v113, v113, v191, s[8:9]
	v_cndmask_b32_e64 v112, v112, v189, s[8:9]
	v_cndmask_b32_e64 v115, v115, v192, s[8:9]
	v_cndmask_b32_e64 v114, v114, v190, s[8:9]
	s_waitcnt vmcnt(12)
	v_lshlrev_b32_e32 v126, 16, v152
	v_and_b32_e32 v127, 0xffff0000, v152
	s_waitcnt lgkmcnt(1)
	v_lshlrev_b32_e32 v128, 16, v153
	s_waitcnt lgkmcnt(0)
	v_and_b32_e32 v129, 0xffff0000, v153
	v_lshlrev_b32_e32 v152, 16, v154
	v_and_b32_e32 v153, 0xffff0000, v154
	v_lshlrev_b32_e32 v154, 16, v155
	v_and_b32_e32 v155, 0xffff0000, v155
	v_pk_fma_f32 v[118:119], v[128:129], s[18:19], v[118:119] op_sel_hi:[1,0,1]
	v_pk_fma_f32 v[116:117], v[126:127], s[18:19], v[116:117] op_sel_hi:[1,0,1]
	v_pk_fma_f32 v[114:115], v[154:155], s[18:19], v[114:115] op_sel_hi:[1,0,1]
	v_pk_fma_f32 v[112:113], v[152:153], s[18:19], v[112:113] op_sel_hi:[1,0,1]
	v_cvt_pk_bf16_f32 v116, v116, v117
	v_cvt_pk_bf16_f32 v117, v118, v119
	s_nop 0
	v_cvt_pk_bf16_f32 v118, v112, v113
	v_cvt_pk_bf16_f32 v119, v114, v115
	v_lshlrev_b32_e32 v112, 16, v116
	v_and_b32_e32 v114, 0xffff0000, v116
	v_lshlrev_b32_e32 v126, 16, v117
	v_and_b32_e32 v128, 0xffff0000, v117
	v_lshlrev_b32_e32 v152, 16, v118
	v_and_b32_e32 v154, 0xffff0000, v118
	v_lshlrev_b32_e32 v188, 16, v119
	v_and_b32_e32 v190, 0xffff0000, v119
	v_mul_f32_e32 v113, v112, v112
	v_mul_f32_e32 v115, v114, v114
	v_mul_f32_e32 v127, v126, v126
	v_mul_f32_e32 v129, v128, v128
	v_mul_f32_e32 v153, v152, v152
	v_mul_f32_e32 v155, v154, v154
	v_mul_f32_e32 v189, v188, v188
	v_mul_f32_e32 v191, v190, v190
	v_pk_add_f32 v[112:113], v[112:113], v[114:115]
	v_pk_add_f32 v[114:115], v[126:127], v[128:129]
	v_pk_add_f32 v[126:127], v[188:189], v[190:191]
	v_pk_add_f32 v[112:113], v[112:113], v[114:115]
	v_pk_add_f32 v[114:115], v[152:153], v[154:155]
	s_nop 0
	v_pk_add_f32 v[114:115], v[114:115], v[126:127]
	v_lshl_add_u64 v[126:127], s[54:55], 0, v[164:165]
	v_pk_add_f32 v[112:113], v[112:113], v[114:115]
	v_mov_b32_e32 v114, v165
	v_mov_b32_e32 v115, v165
	global_store_dwordx4 v[126:127], v[116:119], off offset:128
	v_mov_b32_dpp v114, v112 quad_perm:[1,0,3,2] row_mask:0xf bank_mask:0xf
	v_mov_b32_dpp v115, v113 quad_perm:[1,0,3,2] row_mask:0xf bank_mask:0xf
	v_pk_add_f32 v[112:113], v[112:113], v[114:115]
	ds_bpermute_b32 v114, v130, v112
	ds_bpermute_b32 v115, v130, v113
	s_waitcnt lgkmcnt(0)
	v_pk_add_f32 v[112:113], v[112:113], v[114:115]
	ds_bpermute_b32 v114, v131, v112
	ds_bpermute_b32 v115, v131, v113
	s_and_saveexec_b64 s[52:53], s[10:11]
	s_waitcnt lgkmcnt(0)
	v_pk_add_f32 v[112:113], v[112:113], v[114:115]
	global_store_dwordx2 v[124:125], v[112:113], off offset:512
.LBB0_586:
	s_or_b64 exec, exec, s[52:53]
	s_waitcnt lgkmcnt(1)
	v_cndmask_b32_e64 v114, v108, v100, s[8:9]
	v_mov_b32_e32 v112, 0
	v_cndmask_b32_e64 v113, v109, v101, s[8:9]
	s_waitcnt lgkmcnt(0)
	v_cndmask_b32_e64 v115, v110, v102, s[8:9]
	v_mov_b32_dpp v112, v114 quad_perm:[1,0,3,2] row_mask:0xf bank_mask:0xf
	v_mov_b32_e32 v114, 0
	v_cndmask_b32_e64 v116, v111, v103, s[8:9]
	v_cndmask_b32_e64 v118, v104, v96, s[8:9]
	v_mov_b32_dpp v114, v113 quad_perm:[1,0,3,2] row_mask:0xf bank_mask:0xf
	v_mov_b32_e32 v113, 0
	v_cndmask_b32_e64 v117, v105, v97, s[8:9]
	v_cndmask_b32_e64 v119, v106, v98, s[8:9]
	v_mov_b32_dpp v113, v115 quad_perm:[1,0,3,2] row_mask:0xf bank_mask:0xf
	v_mov_b32_e32 v115, 0
	v_cndmask_b32_e64 v126, v107, v99, s[8:9]
	v_cndmask_b32_e64 v109, v114, v109, s[8:9]
	v_mov_b32_dpp v115, v116 quad_perm:[1,0,3,2] row_mask:0xf bank_mask:0xf
	v_mov_b32_e32 v116, 0
	v_cndmask_b32_e64 v108, v112, v108, s[8:9]
	v_cndmask_b32_e64 v111, v115, v111, s[8:9]
	v_mov_b32_dpp v116, v118 quad_perm:[1,0,3,2] row_mask:0xf bank_mask:0xf
	v_mov_b32_e32 v118, 0
	v_cndmask_b32_e64 v110, v113, v110, s[8:9]
	v_cndmask_b32_e64 v104, v116, v104, s[8:9]
	v_mov_b32_dpp v118, v117 quad_perm:[1,0,3,2] row_mask:0xf bank_mask:0xf
	v_mov_b32_e32 v117, 0
	v_cndmask_b32_e64 v105, v118, v105, s[8:9]
	s_waitcnt vmcnt(13)
	v_and_b32_e32 v127, 0xffff0000, v148
	v_mov_b32_dpp v117, v119 quad_perm:[1,0,3,2] row_mask:0xf bank_mask:0xf
	v_mov_b32_e32 v119, 0
	v_cndmask_b32_e64 v106, v117, v106, s[8:9]
	v_lshlrev_b32_e32 v128, 16, v149
	v_mov_b32_dpp v119, v126 quad_perm:[1,0,3,2] row_mask:0xf bank_mask:0xf
	v_cndmask_b32_e64 v107, v119, v107, s[8:9]
	v_lshlrev_b32_e32 v126, 16, v148
	v_and_b32_e32 v129, 0xffff0000, v149
	v_lshlrev_b32_e32 v148, 16, v150
	v_and_b32_e32 v149, 0xffff0000, v150
	v_lshlrev_b32_e32 v150, 16, v151
	v_and_b32_e32 v151, 0xffff0000, v151
	v_pk_fma_f32 v[110:111], v[128:129], s[18:19], v[110:111] op_sel_hi:[1,0,1]
	v_pk_fma_f32 v[108:109], v[126:127], s[18:19], v[108:109] op_sel_hi:[1,0,1]
	v_pk_fma_f32 v[106:107], v[150:151], s[18:19], v[106:107] op_sel_hi:[1,0,1]
	v_pk_fma_f32 v[104:105], v[148:149], s[18:19], v[104:105] op_sel_hi:[1,0,1]
	v_cvt_pk_bf16_f32 v126, v108, v109
	v_cvt_pk_bf16_f32 v127, v110, v111
	v_mov_b32_e32 v181, v165
	v_cvt_pk_bf16_f32 v128, v104, v105
	v_cvt_pk_bf16_f32 v129, v106, v107
	v_lshlrev_b32_e32 v104, 16, v126
	v_and_b32_e32 v106, 0xffff0000, v126
	v_lshlrev_b32_e32 v108, 16, v127
	v_and_b32_e32 v110, 0xffff0000, v127
	v_lshlrev_b32_e32 v148, 16, v128
	v_and_b32_e32 v150, 0xffff0000, v128
	v_lshlrev_b32_e32 v152, 16, v129
	v_and_b32_e32 v154, 0xffff0000, v129
	v_mul_f32_e32 v105, v104, v104
	v_mul_f32_e32 v107, v106, v106
	v_mul_f32_e32 v109, v108, v108
	v_mul_f32_e32 v111, v110, v110
	v_mul_f32_e32 v149, v148, v148
	v_mul_f32_e32 v151, v150, v150
	v_mul_f32_e32 v153, v152, v152
	v_mul_f32_e32 v155, v154, v154
	v_pk_add_f32 v[104:105], v[104:105], v[106:107]
	v_pk_add_f32 v[106:107], v[108:109], v[110:111]
	v_pk_add_f32 v[108:109], v[152:153], v[154:155]
	v_pk_add_f32 v[104:105], v[104:105], v[106:107]
	v_pk_add_f32 v[106:107], v[148:149], v[150:151]
	s_nop 0
	v_pk_add_f32 v[106:107], v[106:107], v[108:109]
	s_nop 0
	v_pk_add_f32 v[104:105], v[104:105], v[106:107]
	v_mov_b32_e32 v106, v165
	v_mov_b32_e32 v107, v165
	s_nop 0
	v_mov_b32_dpp v106, v104 quad_perm:[1,0,3,2] row_mask:0xf bank_mask:0xf
	v_mov_b32_dpp v107, v105 quad_perm:[1,0,3,2] row_mask:0xf bank_mask:0xf
	v_pk_add_f32 v[104:105], v[104:105], v[106:107]
	ds_bpermute_b32 v106, v130, v104
	ds_bpermute_b32 v107, v130, v105
	s_waitcnt lgkmcnt(0)
	v_pk_add_f32 v[106:107], v[104:105], v[106:107]
	ds_bpermute_b32 v108, v131, v106
	ds_bpermute_b32 v109, v131, v107
	v_lshl_add_u64 v[104:105], s[54:55], 0, v[180:181]
	global_store_dwordx4 v[104:105], v[126:129], off
	s_and_saveexec_b64 s[56:57], s[10:11]
	s_waitcnt lgkmcnt(0)
	v_pk_add_f32 v[106:107], v[106:107], v[108:109]
	v_add_co_u32_e32 v108, vcc, 0x2000, v124
	s_nop 1
	v_addc_co_u32_e32 v109, vcc, 0, v125, vcc
	global_store_dwordx2 v[108:109], v[106:107], off
; __device__ __forceinline__ u32x4 pack8f(f32x4 a, f32x4 b) { u32x4 w; w.x = cvt_pk_bf16(a[0], a[1]); w.y = cvt_pk_bf16(a[2], a[3]); w.z = cvt_pk_bf16(b[0], b[1]); w.w = cvt_pk_bf16(b[2], b[3]); return w; }
;     __device__ __forceinline__ void operator()(const f32x4 (&acc)[2][2][4][2], const Unit& u, int wr, int wc, int fr, int fq, const EpiCtx& X) const {
;     ...
;             for (int m = 0; m < 4; ++m) {
;                 const int rl = ai * HALF + m * 16; const unsigned off = lo + (unsigned)(rl * 64) * 2u;
;                 const f32x4 o0a = acc[ai][0][m][0], o0b = acc[ai][0][m][1], o1a = acc[ai][1][m][0], o1b = acc[ai][1][m][1];
;                 const f32x4 ra_ = dpp_swap1(odd ? o0a : o1a), rb_ = dpp_swap1(odd ? o0b : o1b);
;                 const f32x4 pa[2] = {odd ? ra_ : o0a, odd ? o1a : ra_}, pb[2] = {odd ? rb_ : o0b, odd ? o1b : rb_};
; #pragma unroll
;                 for (int q = 0; q < 2; ++q) {
;                     const u32x4 w0 = raw[2 * m + q];
;                     const f32x4 r0 = (f32x4){bf_lo(w0.x), bf_hi(w0.x), bf_lo(w0.y), bf_hi(w0.y)}, r1 = (f32x4){bf_lo(w0.z), bf_hi(w0.z), bf_lo(w0.w), bf_hi(w0.w)};
;                     f32x4 y0, y1;
;                     if (RESN) { const f32x2 t = tbl[rl + q]; const float mu = t.x, ra = t.y * ALPHA; y0 = (r0 - mu) * ra * g0 + b0 + pa[q]; y1 = (r1 - mu) * ra * g1 + b1 + pb[q]; }
;                     else { y0 = r0 * ALPHA + pa[q]; y1 = r1 * ALPHA + pb[q]; }
;                     { const u32x4 w = pack8f(y0, y1); *(u32x4*)(xb + off + q * 128) = w;
;                         y0 = (f32x4){bf_lo(w.x), bf_hi(w.x), bf_lo(w.y), bf_hi(w.y)}; y1 = (f32x4){bf_lo(w.z), bf_hi(w.z), bf_lo(w.w), bf_hi(w.w)}; }
;                     float sa = ((y0[0] + y0[1]) + (y0[2] + y0[3])) + ((y1[0] + y1[1]) + (y1[2] + y1[3]));
;                     float sb = ((y0[0] * y0[0] + y0[1] * y0[1]) + (y0[2] * y0[2] + y0[3] * y0[3])) + ((y1[0] * y1[0] + y1[1] * y1[1]) + (y1[2] * y1[2] + y1[3] * y1[3]));
;                     sa += dpp_x1(sa);
;                     sb += dpp_x1(sb);
;                     sa += __shfl_xor(sa, 16); sa += __shfl_xor(sa, 32); sb += __shfl_xor(sb, 16); sb += __shfl_xor(sb, 32);
;                     if (fq == 0 && !odd) ps[(size_t)(rl + q) * 64] = (f32x2){sa, sb};
.LBB0_588:
	s_or_b64 exec, exec, s[56:57]
	v_cndmask_b32_e64 v101, v101, v114, s[8:9]
	v_cndmask_b32_e64 v100, v100, v112, s[8:9]
	v_cndmask_b32_e64 v103, v103, v115, s[8:9]
	v_cndmask_b32_e64 v102, v102, v113, s[8:9]
	v_cndmask_b32_e64 v97, v97, v118, s[8:9]
	v_cndmask_b32_e64 v96, v96, v116, s[8:9]
	v_cndmask_b32_e64 v99, v99, v119, s[8:9]
	v_cndmask_b32_e64 v98, v98, v117, s[8:9]
	s_waitcnt vmcnt(14)
	v_lshlrev_b32_e32 v106, 16, v144
	v_and_b32_e32 v107, 0xffff0000, v144
	s_waitcnt lgkmcnt(1)
	v_lshlrev_b32_e32 v108, 16, v145
	s_waitcnt lgkmcnt(0)
	v_and_b32_e32 v109, 0xffff0000, v145
	v_lshlrev_b32_e32 v110, 16, v146
	v_and_b32_e32 v111, 0xffff0000, v146
	v_lshlrev_b32_e32 v112, 16, v147
	v_and_b32_e32 v113, 0xffff0000, v147
	v_pk_fma_f32 v[102:103], v[108:109], s[18:19], v[102:103] op_sel_hi:[1,0,1]
	v_pk_fma_f32 v[100:101], v[106:107], s[18:19], v[100:101] op_sel_hi:[1,0,1]
	v_pk_fma_f32 v[98:99], v[112:113], s[18:19], v[98:99] op_sel_hi:[1,0,1]
	v_pk_fma_f32 v[96:97], v[110:111], s[18:19], v[96:97] op_sel_hi:[1,0,1]
	v_cvt_pk_bf16_f32 v100, v100, v101
	v_cvt_pk_bf16_f32 v101, v102, v103
	s_nop 0
	v_cvt_pk_bf16_f32 v102, v96, v97
	v_cvt_pk_bf16_f32 v103, v98, v99
	v_lshlrev_b32_e32 v96, 16, v100
	v_and_b32_e32 v98, 0xffff0000, v100
	v_lshlrev_b32_e32 v106, 16, v101
	v_and_b32_e32 v108, 0xffff0000, v101
	v_lshlrev_b32_e32 v110, 16, v102
	v_and_b32_e32 v112, 0xffff0000, v102
	v_lshlrev_b32_e32 v114, 16, v103
	v_and_b32_e32 v116, 0xffff0000, v103
	v_mul_f32_e32 v97, v96, v96
	v_mul_f32_e32 v99, v98, v98
	v_mul_f32_e32 v107, v106, v106
	v_mul_f32_e32 v109, v108, v108
	v_mul_f32_e32 v111, v110, v110
	v_mul_f32_e32 v113, v112, v112
	v_mul_f32_e32 v115, v114, v114
	v_mul_f32_e32 v117, v116, v116
	v_pk_add_f32 v[96:97], v[96:97], v[98:99]
	v_pk_add_f32 v[98:99], v[106:107], v[108:109]
	v_pk_add_f32 v[106:107], v[114:115], v[116:117]
	v_pk_add_f32 v[96:97], v[96:97], v[98:99]
	v_pk_add_f32 v[98:99], v[110:111], v[112:113]
	global_store_dwordx4 v[104:105], v[100:103], off offset:128
	v_pk_add_f32 v[98:99], v[98:99], v[106:107]
	s_nop 0
	v_pk_add_f32 v[96:97], v[96:97], v[98:99]
	v_mov_b32_e32 v98, v165
	v_mov_b32_e32 v99, v165
	s_nop 0
	v_mov_b32_dpp v98, v96 quad_perm:[1,0,3,2] row_mask:0xf bank_mask:0xf
	v_mov_b32_dpp v99, v97 quad_perm:[1,0,3,2] row_mask:0xf bank_mask:0xf
	v_pk_add_f32 v[96:97], v[96:97], v[98:99]
	ds_bpermute_b32 v98, v130, v96
	ds_bpermute_b32 v99, v130, v97
	s_waitcnt lgkmcnt(0)
	v_pk_add_f32 v[96:97], v[96:97], v[98:99]
	ds_bpermute_b32 v98, v131, v96
	ds_bpermute_b32 v99, v131, v97
	s_and_saveexec_b64 s[56:57], s[10:11]
	s_waitcnt lgkmcnt(0)
	v_pk_add_f32 v[96:97], v[96:97], v[98:99]
	v_add_co_u32_e32 v98, vcc, 0x2000, v124
	s_nop 1
	v_addc_co_u32_e32 v99, vcc, 0, v125, vcc
	global_store_dwordx2 v[98:99], v[96:97], off offset:512
.LBB0_590:
	s_or_b64 exec, exec, s[56:57]
	s_waitcnt lgkmcnt(1)
	v_cndmask_b32_e64 v98, v92, v84, s[8:9]
	v_mov_b32_e32 v96, 0
	v_cndmask_b32_e64 v97, v93, v85, s[8:9]
	s_waitcnt lgkmcnt(0)
	v_cndmask_b32_e64 v99, v94, v86, s[8:9]
	v_mov_b32_dpp v96, v98 quad_perm:[1,0,3,2] row_mask:0xf bank_mask:0xf
	v_mov_b32_e32 v98, 0
	v_cndmask_b32_e64 v100, v95, v87, s[8:9]
	v_cndmask_b32_e64 v102, v88, v80, s[8:9]
	v_mov_b32_dpp v98, v97 quad_perm:[1,0,3,2] row_mask:0xf bank_mask:0xf
	v_mov_b32_e32 v97, 0
	v_cndmask_b32_e64 v101, v89, v81, s[8:9]
	v_cndmask_b32_e64 v103, v90, v82, s[8:9]
	v_mov_b32_dpp v97, v99 quad_perm:[1,0,3,2] row_mask:0xf bank_mask:0xf
	v_mov_b32_e32 v99, 0
	v_cndmask_b32_e64 v104, v91, v83, s[8:9]
	v_cndmask_b32_e64 v93, v98, v93, s[8:9]
	v_mov_b32_dpp v99, v100 quad_perm:[1,0,3,2] row_mask:0xf bank_mask:0xf
	v_mov_b32_e32 v100, 0
	v_cndmask_b32_e64 v92, v96, v92, s[8:9]
	v_cndmask_b32_e64 v95, v99, v95, s[8:9]
	v_mov_b32_dpp v100, v102 quad_perm:[1,0,3,2] row_mask:0xf bank_mask:0xf
	v_mov_b32_e32 v102, 0
	v_cndmask_b32_e64 v94, v97, v94, s[8:9]
	v_cndmask_b32_e64 v88, v100, v88, s[8:9]
	v_mov_b32_dpp v102, v101 quad_perm:[1,0,3,2] row_mask:0xf bank_mask:0xf
	v_mov_b32_e32 v101, 0
	v_cndmask_b32_e64 v89, v102, v89, s[8:9]
	s_waitcnt vmcnt(15)
	v_and_b32_e32 v105, 0xffff0000, v140
	v_mov_b32_dpp v101, v103 quad_perm:[1,0,3,2] row_mask:0xf bank_mask:0xf
	v_mov_b32_e32 v103, 0
	v_cndmask_b32_e64 v90, v101, v90, s[8:9]
	v_lshlrev_b32_e32 v106, 16, v141
	v_mov_b32_dpp v103, v104 quad_perm:[1,0,3,2] row_mask:0xf bank_mask:0xf
	v_cndmask_b32_e64 v91, v103, v91, s[8:9]
	v_lshlrev_b32_e32 v104, 16, v140
	v_and_b32_e32 v107, 0xffff0000, v141
	v_lshlrev_b32_e32 v108, 16, v142
	v_and_b32_e32 v109, 0xffff0000, v142
	v_lshlrev_b32_e32 v110, 16, v143
	v_and_b32_e32 v111, 0xffff0000, v143
	v_pk_fma_f32 v[94:95], v[106:107], s[18:19], v[94:95] op_sel_hi:[1,0,1]
	v_pk_fma_f32 v[92:93], v[104:105], s[18:19], v[92:93] op_sel_hi:[1,0,1]
	v_pk_fma_f32 v[90:91], v[110:111], s[18:19], v[90:91] op_sel_hi:[1,0,1]
	v_pk_fma_f32 v[88:89], v[108:109], s[18:19], v[88:89] op_sel_hi:[1,0,1]
	v_cvt_pk_bf16_f32 v104, v92, v93
	v_cvt_pk_bf16_f32 v105, v94, v95
	v_mov_b32_e32 v179, v165
	v_cvt_pk_bf16_f32 v106, v88, v89
	v_cvt_pk_bf16_f32 v107, v90, v91
	v_lshlrev_b32_e32 v88, 16, v104
	v_and_b32_e32 v90, 0xffff0000, v104
	v_lshlrev_b32_e32 v92, 16, v105
	v_and_b32_e32 v94, 0xffff0000, v105
	v_lshlrev_b32_e32 v108, 16, v106
	v_and_b32_e32 v110, 0xffff0000, v106
	v_lshlrev_b32_e32 v112, 16, v107
	v_and_b32_e32 v114, 0xffff0000, v107
	v_mul_f32_e32 v89, v88, v88
	v_mul_f32_e32 v91, v90, v90
	v_mul_f32_e32 v93, v92, v92
	v_mul_f32_e32 v95, v94, v94
	v_mul_f32_e32 v109, v108, v108
	v_mul_f32_e32 v111, v110, v110
	v_mul_f32_e32 v113, v112, v112
	v_mul_f32_e32 v115, v114, v114
	v_pk_add_f32 v[88:89], v[88:89], v[90:91]
	v_pk_add_f32 v[90:91], v[92:93], v[94:95]
	v_pk_add_f32 v[92:93], v[112:113], v[114:115]
	v_pk_add_f32 v[88:89], v[88:89], v[90:91]
	v_pk_add_f32 v[90:91], v[108:109], v[110:111]
	s_nop 0
	v_pk_add_f32 v[90:91], v[90:91], v[92:93]
	s_nop 0
	v_pk_add_f32 v[88:89], v[88:89], v[90:91]
	v_mov_b32_e32 v90, v165
	v_mov_b32_e32 v91, v165
	s_nop 0
	v_mov_b32_dpp v90, v88 quad_perm:[1,0,3,2] row_mask:0xf bank_mask:0xf
	v_mov_b32_dpp v91, v89 quad_perm:[1,0,3,2] row_mask:0xf bank_mask:0xf
	v_pk_add_f32 v[88:89], v[88:89], v[90:91]
	ds_bpermute_b32 v90, v130, v88
	ds_bpermute_b32 v91, v130, v89
	s_waitcnt lgkmcnt(0)
	v_pk_add_f32 v[90:91], v[88:89], v[90:91]
	ds_bpermute_b32 v92, v131, v90
	ds_bpermute_b32 v93, v131, v91
	v_lshl_add_u64 v[88:89], s[54:55], 0, v[178:179]
	global_store_dwordx4 v[88:89], v[104:107], off
	s_and_saveexec_b64 s[56:57], s[10:11]
	s_waitcnt lgkmcnt(0)
	v_pk_add_f32 v[90:91], v[90:91], v[92:93]
	v_add_co_u32_e32 v92, vcc, 0x4000, v124
	s_nop 1
	v_addc_co_u32_e32 v93, vcc, 0, v125, vcc
	global_store_dwordx2 v[92:93], v[90:91], off
; __device__ __forceinline__ u32x4 pack8f(f32x4 a, f32x4 b) { u32x4 w; w.x = cvt_pk_bf16(a[0], a[1]); w.y = cvt_pk_bf16(a[2], a[3]); w.z = cvt_pk_bf16(b[0], b[1]); w.w = cvt_pk_bf16(b[2], b[3]); return w; }
;     __device__ __forceinline__ void operator()(const f32x4 (&acc)[2][2][4][2], const Unit& u, int wr, int wc, int fr, int fq, const EpiCtx& X) const {
;     ...
;             for (int m = 0; m < 4; ++m) {
;                 const int rl = ai * HALF + m * 16; const unsigned off = lo + (unsigned)(rl * 64) * 2u;
;                 const f32x4 o0a = acc[ai][0][m][0], o0b = acc[ai][0][m][1], o1a = acc[ai][1][m][0], o1b = acc[ai][1][m][1];
;                 const f32x4 ra_ = dpp_swap1(odd ? o0a : o1a), rb_ = dpp_swap1(odd ? o0b : o1b);
;                 const f32x4 pa[2] = {odd ? ra_ : o0a, odd ? o1a : ra_}, pb[2] = {odd ? rb_ : o0b, odd ? o1b : rb_};
; #pragma unroll
;                 for (int q = 0; q < 2; ++q) {
;                     const u32x4 w0 = raw[2 * m + q];
;                     const f32x4 r0 = (f32x4){bf_lo(w0.x), bf_hi(w0.x), bf_lo(w0.y), bf_hi(w0.y)}, r1 = (f32x4){bf_lo(w0.z), bf_hi(w0.z), bf_lo(w0.w), bf_hi(w0.w)};
;                     f32x4 y0, y1;
;                     if (RESN) { const f32x2 t = tbl[rl + q]; const float mu = t.x, ra = t.y * ALPHA; y0 = (r0 - mu) * ra * g0 + b0 + pa[q]; y1 = (r1 - mu) * ra * g1 + b1 + pb[q]; }
;                     else { y0 = r0 * ALPHA + pa[q]; y1 = r1 * ALPHA + pb[q]; }
;                     { const u32x4 w = pack8f(y0, y1); *(u32x4*)(xb + off + q * 128) = w;
;                         y0 = (f32x4){bf_lo(w.x), bf_hi(w.x), bf_lo(w.y), bf_hi(w.y)}; y1 = (f32x4){bf_lo(w.z), bf_hi(w.z), bf_lo(w.w), bf_hi(w.w)}; }
;                     float sa = ((y0[0] + y0[1]) + (y0[2] + y0[3])) + ((y1[0] + y1[1]) + (y1[2] + y1[3]));
;                     float sb = ((y0[0] * y0[0] + y0[1] * y0[1]) + (y0[2] * y0[2] + y0[3] * y0[3])) + ((y1[0] * y1[0] + y1[1] * y1[1]) + (y1[2] * y1[2] + y1[3] * y1[3]));
;                     sa += dpp_x1(sa);
;                     sb += dpp_x1(sb);
;                     sa += __shfl_xor(sa, 16); sa += __shfl_xor(sa, 32); sb += __shfl_xor(sb, 16); sb += __shfl_xor(sb, 32);
;                     if (fq == 0 && !odd) ps[(size_t)(rl + q) * 64] = (f32x2){sa, sb};
.LBB0_592:
	s_or_b64 exec, exec, s[56:57]
	v_cndmask_b32_e64 v85, v85, v98, s[8:9]
	v_cndmask_b32_e64 v84, v84, v96, s[8:9]
	v_cndmask_b32_e64 v87, v87, v99, s[8:9]
	v_cndmask_b32_e64 v86, v86, v97, s[8:9]
	v_cndmask_b32_e64 v81, v81, v102, s[8:9]
	v_cndmask_b32_e64 v80, v80, v100, s[8:9]
	v_cndmask_b32_e64 v83, v83, v103, s[8:9]
	v_cndmask_b32_e64 v82, v82, v101, s[8:9]
	s_waitcnt vmcnt(16)
	v_lshlrev_b32_e32 v90, 16, v136
	v_and_b32_e32 v91, 0xffff0000, v136
	s_waitcnt lgkmcnt(1)
	v_lshlrev_b32_e32 v92, 16, v137
	s_waitcnt lgkmcnt(0)
	v_and_b32_e32 v93, 0xffff0000, v137
	v_lshlrev_b32_e32 v94, 16, v138
	v_and_b32_e32 v95, 0xffff0000, v138
	v_lshlrev_b32_e32 v96, 16, v139
	v_and_b32_e32 v97, 0xffff0000, v139
	v_pk_fma_f32 v[86:87], v[92:93], s[18:19], v[86:87] op_sel_hi:[1,0,1]
	v_pk_fma_f32 v[84:85], v[90:91], s[18:19], v[84:85] op_sel_hi:[1,0,1]
	v_pk_fma_f32 v[82:83], v[96:97], s[18:19], v[82:83] op_sel_hi:[1,0,1]
	v_pk_fma_f32 v[80:81], v[94:95], s[18:19], v[80:81] op_sel_hi:[1,0,1]
	v_cvt_pk_bf16_f32 v84, v84, v85
	v_cvt_pk_bf16_f32 v85, v86, v87
	s_nop 0
	v_cvt_pk_bf16_f32 v86, v80, v81
	v_cvt_pk_bf16_f32 v87, v82, v83
	v_lshlrev_b32_e32 v80, 16, v84
	v_and_b32_e32 v82, 0xffff0000, v84
	v_lshlrev_b32_e32 v90, 16, v85
	v_and_b32_e32 v92, 0xffff0000, v85
	v_lshlrev_b32_e32 v94, 16, v86
	v_and_b32_e32 v96, 0xffff0000, v86
	v_lshlrev_b32_e32 v98, 16, v87
	v_and_b32_e32 v100, 0xffff0000, v87
	v_mul_f32_e32 v81, v80, v80
	v_mul_f32_e32 v83, v82, v82
	v_mul_f32_e32 v91, v90, v90
	v_mul_f32_e32 v93, v92, v92
	v_mul_f32_e32 v95, v94, v94
	v_mul_f32_e32 v97, v96, v96
	v_mul_f32_e32 v99, v98, v98
	v_mul_f32_e32 v101, v100, v100
	v_pk_add_f32 v[80:81], v[80:81], v[82:83]
	v_pk_add_f32 v[82:83], v[90:91], v[92:93]
	v_pk_add_f32 v[90:91], v[98:99], v[100:101]
	v_pk_add_f32 v[80:81], v[80:81], v[82:83]
	v_pk_add_f32 v[82:83], v[94:95], v[96:97]
	global_store_dwordx4 v[88:89], v[84:87], off offset:128
	v_pk_add_f32 v[82:83], v[82:83], v[90:91]
	s_nop 0
	v_pk_add_f32 v[80:81], v[80:81], v[82:83]
	v_mov_b32_e32 v82, v165
	v_mov_b32_e32 v83, v165
	s_nop 0
	v_mov_b32_dpp v82, v80 quad_perm:[1,0,3,2] row_mask:0xf bank_mask:0xf
	v_mov_b32_dpp v83, v81 quad_perm:[1,0,3,2] row_mask:0xf bank_mask:0xf
	v_pk_add_f32 v[80:81], v[80:81], v[82:83]
	ds_bpermute_b32 v82, v130, v80
	ds_bpermute_b32 v83, v130, v81
	s_waitcnt lgkmcnt(0)
	v_pk_add_f32 v[80:81], v[80:81], v[82:83]
	ds_bpermute_b32 v82, v131, v80
	ds_bpermute_b32 v83, v131, v81
	s_and_saveexec_b64 s[56:57], s[10:11]
	s_waitcnt lgkmcnt(0)
	v_pk_add_f32 v[80:81], v[80:81], v[82:83]
	v_add_co_u32_e32 v82, vcc, 0x4000, v124
	s_nop 1
	v_addc_co_u32_e32 v83, vcc, 0, v125, vcc
	global_store_dwordx2 v[82:83], v[80:81], off offset:512
.LBB0_594:
	s_or_b64 exec, exec, s[56:57]
	s_waitcnt lgkmcnt(1)
	v_cndmask_b32_e64 v82, v76, v68, s[8:9]
	v_mov_b32_e32 v80, 0
	v_cndmask_b32_e64 v81, v77, v69, s[8:9]
	s_waitcnt lgkmcnt(0)
	v_cndmask_b32_e64 v83, v78, v70, s[8:9]
	v_mov_b32_dpp v80, v82 quad_perm:[1,0,3,2] row_mask:0xf bank_mask:0xf
	v_mov_b32_e32 v82, 0
	v_cndmask_b32_e64 v84, v79, v71, s[8:9]
	v_cndmask_b32_e64 v86, v72, v64, s[8:9]
	v_mov_b32_dpp v82, v81 quad_perm:[1,0,3,2] row_mask:0xf bank_mask:0xf
	v_mov_b32_e32 v81, 0
	v_cndmask_b32_e64 v85, v73, v65, s[8:9]
	v_cndmask_b32_e64 v87, v74, v66, s[8:9]
	v_mov_b32_dpp v81, v83 quad_perm:[1,0,3,2] row_mask:0xf bank_mask:0xf
	v_mov_b32_e32 v83, 0
	v_cndmask_b32_e64 v88, v75, v67, s[8:9]
	v_cndmask_b32_e64 v77, v82, v77, s[8:9]
	v_mov_b32_dpp v83, v84 quad_perm:[1,0,3,2] row_mask:0xf bank_mask:0xf
	v_mov_b32_e32 v84, 0
	v_cndmask_b32_e64 v76, v80, v76, s[8:9]
	v_cndmask_b32_e64 v79, v83, v79, s[8:9]
	v_mov_b32_dpp v84, v86 quad_perm:[1,0,3,2] row_mask:0xf bank_mask:0xf
	v_mov_b32_e32 v86, 0
	v_cndmask_b32_e64 v78, v81, v78, s[8:9]
	v_cndmask_b32_e64 v72, v84, v72, s[8:9]
	v_mov_b32_dpp v86, v85 quad_perm:[1,0,3,2] row_mask:0xf bank_mask:0xf
	v_mov_b32_e32 v85, 0
	v_cndmask_b32_e64 v73, v86, v73, s[8:9]
	s_waitcnt vmcnt(17)
	v_and_b32_e32 v89, 0xffff0000, v132
	v_mov_b32_dpp v85, v87 quad_perm:[1,0,3,2] row_mask:0xf bank_mask:0xf
	v_mov_b32_e32 v87, 0
	v_cndmask_b32_e64 v74, v85, v74, s[8:9]
	v_lshlrev_b32_e32 v90, 16, v133
	v_mov_b32_dpp v87, v88 quad_perm:[1,0,3,2] row_mask:0xf bank_mask:0xf
	v_cndmask_b32_e64 v75, v87, v75, s[8:9]
	v_lshlrev_b32_e32 v88, 16, v132
	v_and_b32_e32 v91, 0xffff0000, v133
	v_lshlrev_b32_e32 v92, 16, v134
	v_and_b32_e32 v93, 0xffff0000, v134
	v_lshlrev_b32_e32 v94, 16, v135
	v_and_b32_e32 v95, 0xffff0000, v135
	v_pk_fma_f32 v[78:79], v[90:91], s[18:19], v[78:79] op_sel_hi:[1,0,1]
	v_pk_fma_f32 v[76:77], v[88:89], s[18:19], v[76:77] op_sel_hi:[1,0,1]
	v_pk_fma_f32 v[74:75], v[94:95], s[18:19], v[74:75] op_sel_hi:[1,0,1]
	v_pk_fma_f32 v[72:73], v[92:93], s[18:19], v[72:73] op_sel_hi:[1,0,1]
	v_cvt_pk_bf16_f32 v88, v76, v77
	v_cvt_pk_bf16_f32 v89, v78, v79
	v_mov_b32_e32 v177, v165
	v_cvt_pk_bf16_f32 v90, v72, v73
	v_cvt_pk_bf16_f32 v91, v74, v75
	v_lshlrev_b32_e32 v72, 16, v88
	v_and_b32_e32 v74, 0xffff0000, v88
	v_lshlrev_b32_e32 v76, 16, v89
	v_and_b32_e32 v78, 0xffff0000, v89
	v_lshlrev_b32_e32 v92, 16, v90
	v_and_b32_e32 v94, 0xffff0000, v90
	v_lshlrev_b32_e32 v96, 16, v91
	v_and_b32_e32 v98, 0xffff0000, v91
	v_mul_f32_e32 v73, v72, v72
	v_mul_f32_e32 v75, v74, v74
	v_mul_f32_e32 v77, v76, v76
	v_mul_f32_e32 v79, v78, v78
	v_mul_f32_e32 v93, v92, v92
	v_mul_f32_e32 v95, v94, v94
	v_mul_f32_e32 v97, v96, v96
	v_mul_f32_e32 v99, v98, v98
	v_pk_add_f32 v[72:73], v[72:73], v[74:75]
	v_pk_add_f32 v[74:75], v[76:77], v[78:79]
	v_pk_add_f32 v[76:77], v[96:97], v[98:99]
	v_pk_add_f32 v[72:73], v[72:73], v[74:75]
	v_pk_add_f32 v[74:75], v[92:93], v[94:95]
	s_nop 0
	v_pk_add_f32 v[74:75], v[74:75], v[76:77]
	s_nop 0
	v_pk_add_f32 v[72:73], v[72:73], v[74:75]
	v_mov_b32_e32 v74, v165
	v_mov_b32_e32 v75, v165
	s_nop 0
	v_mov_b32_dpp v74, v72 quad_perm:[1,0,3,2] row_mask:0xf bank_mask:0xf
	v_mov_b32_dpp v75, v73 quad_perm:[1,0,3,2] row_mask:0xf bank_mask:0xf
	v_pk_add_f32 v[72:73], v[72:73], v[74:75]
	ds_bpermute_b32 v74, v130, v72
	ds_bpermute_b32 v75, v130, v73
	s_waitcnt lgkmcnt(0)
	v_pk_add_f32 v[74:75], v[72:73], v[74:75]
	ds_bpermute_b32 v76, v131, v74
	ds_bpermute_b32 v77, v131, v75
	v_lshl_add_u64 v[72:73], s[54:55], 0, v[176:177]
	global_store_dwordx4 v[72:73], v[88:91], off
	s_and_saveexec_b64 s[56:57], s[10:11]
	s_waitcnt lgkmcnt(0)
	v_pk_add_f32 v[74:75], v[74:75], v[76:77]
	v_add_co_u32_e32 v76, vcc, 0x6000, v124
	s_nop 1
	v_addc_co_u32_e32 v77, vcc, 0, v125, vcc
	global_store_dwordx2 v[76:77], v[74:75], off
; __device__ __forceinline__ u32x4 pack8f(f32x4 a, f32x4 b) { u32x4 w; w.x = cvt_pk_bf16(a[0], a[1]); w.y = cvt_pk_bf16(a[2], a[3]); w.z = cvt_pk_bf16(b[0], b[1]); w.w = cvt_pk_bf16(b[2], b[3]); return w; }
;     __device__ __forceinline__ void operator()(const f32x4 (&acc)[2][2][4][2], const Unit& u, int wr, int wc, int fr, int fq, const EpiCtx& X) const {
;     ...
;             for (int m = 0; m < 4; ++m) {
;                 const int rl = ai * HALF + m * 16; const unsigned off = lo + (unsigned)(rl * 64) * 2u;
;                 const f32x4 o0a = acc[ai][0][m][0], o0b = acc[ai][0][m][1], o1a = acc[ai][1][m][0], o1b = acc[ai][1][m][1];
;                 const f32x4 ra_ = dpp_swap1(odd ? o0a : o1a), rb_ = dpp_swap1(odd ? o0b : o1b);
;                 const f32x4 pa[2] = {odd ? ra_ : o0a, odd ? o1a : ra_}, pb[2] = {odd ? rb_ : o0b, odd ? o1b : rb_};
; #pragma unroll
;                 for (int q = 0; q < 2; ++q) {
;                     const u32x4 w0 = raw[2 * m + q];
;                     const f32x4 r0 = (f32x4){bf_lo(w0.x), bf_hi(w0.x), bf_lo(w0.y), bf_hi(w0.y)}, r1 = (f32x4){bf_lo(w0.z), bf_hi(w0.z), bf_lo(w0.w), bf_hi(w0.w)};
;                     f32x4 y0, y1;
;                     if (RESN) { const f32x2 t = tbl[rl + q]; const float mu = t.x, ra = t.y * ALPHA; y0 = (r0 - mu) * ra * g0 + b0 + pa[q]; y1 = (r1 - mu) * ra * g1 + b1 + pb[q]; }
;                     else { y0 = r0 * ALPHA + pa[q]; y1 = r1 * ALPHA + pb[q]; }
;                     { const u32x4 w = pack8f(y0, y1); *(u32x4*)(xb + off + q * 128) = w;
;                         y0 = (f32x4){bf_lo(w.x), bf_hi(w.x), bf_lo(w.y), bf_hi(w.y)}; y1 = (f32x4){bf_lo(w.z), bf_hi(w.z), bf_lo(w.w), bf_hi(w.w)}; }
;                     float sa = ((y0[0] + y0[1]) + (y0[2] + y0[3])) + ((y1[0] + y1[1]) + (y1[2] + y1[3]));
;                     float sb = ((y0[0] * y0[0] + y0[1] * y0[1]) + (y0[2] * y0[2] + y0[3] * y0[3])) + ((y1[0] * y1[0] + y1[1] * y1[1]) + (y1[2] * y1[2] + y1[3] * y1[3]));
;                     sa += dpp_x1(sa);
;                     sb += dpp_x1(sb);
;                     sa += __shfl_xor(sa, 16); sa += __shfl_xor(sa, 32); sb += __shfl_xor(sb, 16); sb += __shfl_xor(sb, 32);
;                     if (fq == 0 && !odd) ps[(size_t)(rl + q) * 64] = (f32x2){sa, sb};
.LBB0_596:
	s_or_b64 exec, exec, s[56:57]
	v_cndmask_b32_e64 v69, v69, v82, s[8:9]
	v_cndmask_b32_e64 v68, v68, v80, s[8:9]
	v_cndmask_b32_e64 v71, v71, v83, s[8:9]
	v_cndmask_b32_e64 v70, v70, v81, s[8:9]
	v_cndmask_b32_e64 v65, v65, v86, s[8:9]
	v_cndmask_b32_e64 v64, v64, v84, s[8:9]
	v_cndmask_b32_e64 v67, v67, v87, s[8:9]
	v_cndmask_b32_e64 v66, v66, v85, s[8:9]
	s_waitcnt vmcnt(18)
	v_lshlrev_b32_e32 v74, 16, v120
	v_and_b32_e32 v75, 0xffff0000, v120
	s_waitcnt lgkmcnt(1)
	v_lshlrev_b32_e32 v76, 16, v121
	s_waitcnt lgkmcnt(0)
	v_and_b32_e32 v77, 0xffff0000, v121
	v_lshlrev_b32_e32 v78, 16, v122
	v_and_b32_e32 v79, 0xffff0000, v122
	v_lshlrev_b32_e32 v80, 16, v123
	v_and_b32_e32 v81, 0xffff0000, v123
	v_pk_fma_f32 v[70:71], v[76:77], s[18:19], v[70:71] op_sel_hi:[1,0,1]
	v_pk_fma_f32 v[68:69], v[74:75], s[18:19], v[68:69] op_sel_hi:[1,0,1]
	v_pk_fma_f32 v[66:67], v[80:81], s[18:19], v[66:67] op_sel_hi:[1,0,1]
	v_pk_fma_f32 v[64:65], v[78:79], s[18:19], v[64:65] op_sel_hi:[1,0,1]
	v_cvt_pk_bf16_f32 v68, v68, v69
	v_cvt_pk_bf16_f32 v69, v70, v71
	s_nop 0
	v_cvt_pk_bf16_f32 v70, v64, v65
	v_cvt_pk_bf16_f32 v71, v66, v67
	v_lshlrev_b32_e32 v64, 16, v68
	v_and_b32_e32 v66, 0xffff0000, v68
	v_lshlrev_b32_e32 v74, 16, v69
	v_and_b32_e32 v76, 0xffff0000, v69
	v_lshlrev_b32_e32 v78, 16, v70
	v_and_b32_e32 v80, 0xffff0000, v70
	v_lshlrev_b32_e32 v82, 16, v71
	v_and_b32_e32 v84, 0xffff0000, v71
	v_mul_f32_e32 v65, v64, v64
	v_mul_f32_e32 v67, v66, v66
	v_mul_f32_e32 v75, v74, v74
	v_mul_f32_e32 v77, v76, v76
	v_mul_f32_e32 v79, v78, v78
	v_mul_f32_e32 v81, v80, v80
	v_mul_f32_e32 v83, v82, v82
	v_mul_f32_e32 v85, v84, v84
	v_pk_add_f32 v[64:65], v[64:65], v[66:67]
	v_pk_add_f32 v[66:67], v[74:75], v[76:77]
	v_pk_add_f32 v[74:75], v[82:83], v[84:85]
	v_pk_add_f32 v[64:65], v[64:65], v[66:67]
	v_pk_add_f32 v[66:67], v[78:79], v[80:81]
	global_store_dwordx4 v[72:73], v[68:71], off offset:128
	v_pk_add_f32 v[66:67], v[66:67], v[74:75]
	s_nop 0
	v_pk_add_f32 v[64:65], v[64:65], v[66:67]
	v_mov_b32_e32 v66, v165
	v_mov_b32_e32 v67, v165
	s_nop 0
	v_mov_b32_dpp v66, v64 quad_perm:[1,0,3,2] row_mask:0xf bank_mask:0xf
	v_mov_b32_dpp v67, v65 quad_perm:[1,0,3,2] row_mask:0xf bank_mask:0xf
	v_pk_add_f32 v[64:65], v[64:65], v[66:67]
	ds_bpermute_b32 v66, v130, v64
	ds_bpermute_b32 v67, v130, v65
	s_waitcnt lgkmcnt(0)
	v_pk_add_f32 v[64:65], v[64:65], v[66:67]
	ds_bpermute_b32 v66, v131, v64
	ds_bpermute_b32 v67, v131, v65
	s_and_saveexec_b64 s[56:57], s[10:11]
	s_waitcnt lgkmcnt(0)
	v_pk_add_f32 v[64:65], v[64:65], v[66:67]
	v_add_co_u32_e32 v66, vcc, 0x6000, v124
	s_nop 1
	v_addc_co_u32_e32 v67, vcc, 0, v125, vcc
	global_store_dwordx2 v[66:67], v[64:65], off offset:512
;     __device__ __forceinline__ void operator()(const f32x4 (&acc)[2][2][4][2], const Unit& u, int wr, int wc, int fr, int fq, const EpiCtx& X) const {
;     ...
;         for (int ai = 0; ai < 2; ++ai) {
;             u32x4 raw[8];
; #pragma unroll
;             for (int m = 0; m < 4; ++m) { const unsigned off = lo + (unsigned)((ai * HALF + m * 16) * 64) * 2u; raw[2 * m] = *(const u32x4*)(xb + off); raw[2 * m + 1] = *(const u32x4*)(xb + off + 128); }
; #pragma unroll
;             for (int m = 0; m < 4; ++m) {
;                 const int rl = ai * HALF + m * 16; const unsigned off = lo + (unsigned)(rl * 64) * 2u;
;                 const f32x4 o0a = acc[ai][0][m][0], o0b = acc[ai][0][m][1], o1a = acc[ai][1][m][0], o1b = acc[ai][1][m][1];
;                 const f32x4 ra_ = dpp_swap1(odd ? o0a : o1a), rb_ = dpp_swap1(odd ? o0b : o1b);
;                 const f32x4 pa[2] = {odd ? ra_ : o0a, odd ? o1a : ra_}, pb[2] = {odd ? rb_ : o0b, odd ? o1b : rb_};
; #pragma unroll
;                 for (int q = 0; q < 2; ++q) {
;                     const u32x4 w0 = raw[2 * m + q];
;                     const f32x4 r0 = (f32x4){bf_lo(w0.x), bf_hi(w0.x), bf_lo(w0.y), bf_hi(w0.y)}, r1 = (f32x4){bf_lo(w0.z), bf_hi(w0.z), bf_lo(w0.w), bf_hi(w0.w)};
;                     f32x4 y0, y1;
;                     if (RESN) { const f32x2 t = tbl[rl + q]; const float mu = t.x, ra = t.y * ALPHA; y0 = (r0 - mu) * ra * g0 + b0 + pa[q]; y1 = (r1 - mu) * ra * g1 + b1 + pb[q]; }
;                     else { y0 = r0 * ALPHA + pa[q]; y1 = r1 * ALPHA + pb[q]; }
;                     { const u32x4 w = pack8f(y0, y1); *(u32x4*)(xb + off + q * 128) = w;
;                         y0 = (f32x4){bf_lo(w.x), bf_hi(w.x), bf_lo(w.y), bf_hi(w.y)}; y1 = (f32x4){bf_lo(w.z), bf_hi(w.z), bf_lo(w.w), bf_hi(w.w)}; }
;                     float sa = ((y0[0] + y0[1]) + (y0[2] + y0[3])) + ((y1[0] + y1[1]) + (y1[2] + y1[3]));
;                     float sb = ((y0[0] * y0[0] + y0[1] * y0[1]) + (y0[2] * y0[2] + y0[3] * y0[3])) + ((y1[0] * y1[0] + y1[1] * y1[1]) + (y1[2] * y1[2] + y1[3] * y1[3]));
;                     sa += dpp_x1(sa);
;                     sb += dpp_x1(sb);
;                     sa += __shfl_xor(sa, 16); sa += __shfl_xor(sa, 32); sb += __shfl_xor(sb, 16); sb += __shfl_xor(sb, 32);
;                     if (fq == 0 && !odd) ps[(size_t)(rl + q) * 64] = (f32x2){sa, sb};
.LBB0_598:
	s_or_b64 exec, exec, s[56:57]
	v_add_u32_e32 v96, 0x4000, v164
	s_waitcnt vmcnt(16)
	v_mov_b32_e32 v104, v230
	v_mov_b32_e32 v105, v231
	v_mov_b32_e32 v106, v232
	v_mov_b32_e32 v107, v233
	v_add_u32_e32 v94, 0x4800, v164
	v_add_u32_e32 v92, 0x5000, v164
	v_add_u32_e32 v164, 0x5800, v164
	v_mov_b32_e32 v88, v234
	v_mov_b32_e32 v89, v235
	v_mov_b32_e32 v90, v236
	v_mov_b32_e32 v91, v237
	v_mov_b32_e32 v84, v238
	v_mov_b32_e32 v85, v239
	v_mov_b32_e32 v86, v240
	v_mov_b32_e32 v87, v241
	v_mov_b32_e32 v80, v242
	v_mov_b32_e32 v81, v243
	v_mov_b32_e32 v82, v244
	v_mov_b32_e32 v83, v245
	global_load_dwordx4 v[76:79], v92, s[54:55]
	global_load_dwordx4 v[72:75], v92, s[54:55] offset:128
	global_load_dwordx4 v[68:71], v164, s[54:55]
	s_waitcnt lgkmcnt(0)
	global_load_dwordx4 v[64:67], v164, s[54:55] offset:128
	v_cndmask_b32_e64 v103, v63, v55, s[8:9]
	v_cndmask_b32_e64 v110, v62, v54, s[8:9]
	v_cndmask_b32_e64 v111, v61, v53, s[8:9]
	v_cndmask_b32_e64 v112, v60, v52, s[8:9]
	v_mov_b32_e32 v93, 0
	v_mov_b32_e32 v97, 0
	v_mov_b32_e32 v95, 0
	v_mov_b32_e32 v98, 0
	v_cndmask_b32_e64 v113, v59, v51, s[8:9]
	v_cndmask_b32_e64 v114, v58, v50, s[8:9]
	v_cndmask_b32_e64 v115, v57, v49, s[8:9]
	v_cndmask_b32_e64 v116, v56, v48, s[8:9]
	v_mov_b32_e32 v99, 0
	v_mov_b32_e32 v101, 0
	v_mov_b32_e32 v100, 0
	v_mov_b32_e32 v102, 0
	v_mov_b32_dpp v93, v112 quad_perm:[1,0,3,2] row_mask:0xf bank_mask:0xf
	v_mov_b32_dpp v97, v111 quad_perm:[1,0,3,2] row_mask:0xf bank_mask:0xf
	v_mov_b32_dpp v95, v110 quad_perm:[1,0,3,2] row_mask:0xf bank_mask:0xf
	v_mov_b32_dpp v98, v103 quad_perm:[1,0,3,2] row_mask:0xf bank_mask:0xf
	v_mov_b32_dpp v99, v116 quad_perm:[1,0,3,2] row_mask:0xf bank_mask:0xf
	v_mov_b32_dpp v101, v115 quad_perm:[1,0,3,2] row_mask:0xf bank_mask:0xf
	v_mov_b32_dpp v100, v114 quad_perm:[1,0,3,2] row_mask:0xf bank_mask:0xf
	v_mov_b32_dpp v102, v113 quad_perm:[1,0,3,2] row_mask:0xf bank_mask:0xf
	v_cndmask_b32_e64 v61, v97, v61, s[8:9]
	v_cndmask_b32_e64 v60, v93, v60, s[8:9]
	v_cndmask_b32_e64 v63, v98, v63, s[8:9]
	v_cndmask_b32_e64 v62, v95, v62, s[8:9]
	v_cndmask_b32_e64 v57, v101, v57, s[8:9]
	v_cndmask_b32_e64 v56, v99, v56, s[8:9]
	v_cndmask_b32_e64 v59, v102, v59, s[8:9]
	v_cndmask_b32_e64 v58, v100, v58, s[8:9]
	v_mov_b32_e32 v108, v165
	v_mov_b32_e32 v109, v165
	v_lshlrev_b32_e32 v110, 16, v104
	v_and_b32_e32 v111, 0xffff0000, v104
	v_lshlrev_b32_e32 v104, 16, v105
	v_and_b32_e32 v105, 0xffff0000, v105
	v_lshlrev_b32_e32 v112, 16, v106
	v_and_b32_e32 v113, 0xffff0000, v106
	v_lshlrev_b32_e32 v106, 16, v107
	v_and_b32_e32 v107, 0xffff0000, v107
	v_pk_fma_f32 v[62:63], v[104:105], s[18:19], v[62:63] op_sel_hi:[1,0,1]
	v_pk_fma_f32 v[60:61], v[110:111], s[18:19], v[60:61] op_sel_hi:[1,0,1]
	v_pk_fma_f32 v[58:59], v[106:107], s[18:19], v[58:59] op_sel_hi:[1,0,1]
	v_pk_fma_f32 v[56:57], v[112:113], s[18:19], v[56:57] op_sel_hi:[1,0,1]
	v_cvt_pk_bf16_f32 v60, v60, v61
	v_cvt_pk_bf16_f32 v61, v62, v63
	s_nop 0
	v_cvt_pk_bf16_f32 v62, v56, v57
	v_cvt_pk_bf16_f32 v63, v58, v59
	v_lshlrev_b32_e32 v56, 16, v60
	v_and_b32_e32 v58, 0xffff0000, v60
	v_lshlrev_b32_e32 v104, 16, v61
	v_and_b32_e32 v106, 0xffff0000, v61
	v_lshlrev_b32_e32 v110, 16, v62
	v_and_b32_e32 v112, 0xffff0000, v62
	v_lshlrev_b32_e32 v114, 16, v63
	v_and_b32_e32 v116, 0xffff0000, v63
	v_mul_f32_e32 v57, v56, v56
	v_mul_f32_e32 v59, v58, v58
	v_mul_f32_e32 v105, v104, v104
	v_mul_f32_e32 v107, v106, v106
	v_mul_f32_e32 v111, v110, v110
	v_mul_f32_e32 v113, v112, v112
	v_mul_f32_e32 v115, v114, v114
	v_mul_f32_e32 v117, v116, v116
	v_pk_add_f32 v[56:57], v[56:57], v[58:59]
	v_pk_add_f32 v[58:59], v[104:105], v[106:107]
	v_pk_add_f32 v[104:105], v[110:111], v[112:113]
	v_pk_add_f32 v[106:107], v[114:115], v[116:117]
	v_pk_add_f32 v[56:57], v[56:57], v[58:59]
	v_pk_add_f32 v[58:59], v[104:105], v[106:107]
	global_store_dwordx4 v96, v[60:63], s[54:55]
	v_pk_add_f32 v[56:57], v[56:57], v[58:59]
	s_nop 1
	v_mov_b32_dpp v108, v56 quad_perm:[1,0,3,2] row_mask:0xf bank_mask:0xf
	v_mov_b32_dpp v109, v57 quad_perm:[1,0,3,2] row_mask:0xf bank_mask:0xf
	v_pk_add_f32 v[56:57], v[56:57], v[108:109]
	ds_bpermute_b32 v58, v130, v56
	ds_bpermute_b32 v59, v130, v57
	s_waitcnt lgkmcnt(0)
	v_pk_add_f32 v[56:57], v[56:57], v[58:59]
	ds_bpermute_b32 v58, v131, v56
	ds_bpermute_b32 v59, v131, v57
	s_and_saveexec_b64 s[56:57], s[10:11]
	s_cbranch_execz .LBB0_600
	s_waitcnt lgkmcnt(0)
	v_pk_add_f32 v[56:57], v[56:57], v[58:59]
	v_add_co_u32_e32 v58, vcc, 0x10000, v124
	s_nop 1
	v_addc_co_u32_e32 v59, vcc, 0, v125, vcc
	global_store_dwordx2 v[58:59], v[56:57], off

; #define LAS __attribute__((address_space(3)))
;     __device__ __forceinline__ void operator()(const f32x4 (&acc)[2][2][4][2], const Unit& u, int wr, int wc, int fr, int fq, const EpiCtx& X) const {
;     ...
;         char* yb = nullptr; char* xb = (char*)(XB + (size_t)u.pm * BM * DM + (size_t)(u.pn * 4 + wc) * (BM * 64));
;         unsigned lo = (unsigned)((wr * 64 + fe) * 64 + o32 + 8 * fq) * 2u; EPI_OPAQUE(lo);
;         const int col = u.pn * BM + wc * 64 + o32 + 8 * fq;
;         f32x4 g0, g1, b0, b1;
;         if (RESN) { ensure_tbl(PSp, sidp, u.pm, X);
;             g0 = *(const f32x4*)(gp + col); g1 = *(const f32x4*)(gp + col + 4); b0 = *(const f32x4*)(bp + col) * ALPHA; b1 = *(const f32x4*)(bp + col + 4) * ALPHA; }
;         const LAS f32x2* tbl = (const LAS f32x2*)(X.lds + TBL_OFF) + wr * 64 + fe;
;         f32x2* ps = PSn + ((size_t)u.pm * BM + wr * 64 + fe) * 64 + u.pn * 4 + wc;
; #pragma unroll
;         for (int ai = 0; ai < 2; ++ai) {
;             u32x4 raw[8];
; #pragma unroll
;             for (int m = 0; m < 4; ++m) { const unsigned off = lo + (unsigned)((ai * HALF + m * 16) * 64) * 2u; raw[2 * m] = *(const u32x4*)(xb + off); raw[2 * m + 1] = *(const u32x4*)(xb + off + 128); }
; #pragma unroll
;             for (int m = 0; m < 4; ++m) {
;                 const int rl = ai * HALF + m * 16; const unsigned off = lo + (unsigned)(rl * 64) * 2u;
;                 const f32x4 o0a = acc[ai][0][m][0], o0b = acc[ai][0][m][1], o1a = acc[ai][1][m][0], o1b = acc[ai][1][m][1];
;                 const f32x4 ra_ = dpp_swap1(odd ? o0a : o1a), rb_ = dpp_swap1(odd ? o0b : o1b);
;                 const f32x4 pa[2] = {odd ? ra_ : o0a, odd ? o1a : ra_}, pb[2] = {odd ? rb_ : o0b, odd ? o1b : rb_};
; #pragma unroll
;                 for (int q = 0; q < 2; ++q) {
;                     const u32x4 w0 = raw[2 * m + q];
;                     const f32x4 r0 = (f32x4){bf_lo(w0.x), bf_hi(w0.x), bf_lo(w0.y), bf_hi(w0.y)}, r1 = (f32x4){bf_lo(w0.z), bf_hi(w0.z), bf_lo(w0.w), bf_hi(w0.w)};
;                     f32x4 y0, y1;
;                     if (RESN) { const f32x2 t = tbl[rl + q]; const float mu = t.x, ra = t.y * ALPHA; y0 = (r0 - mu) * ra * g0 + b0 + pa[q]; y1 = (r1 - mu) * ra * g1 + b1 + pb[q]; }
;                     else { y0 = r0 * ALPHA + pa[q]; y1 = r1 * ALPHA + pb[q]; }
;                     { const u32x4 w = pack8f(y0, y1); *(u32x4*)(xb + off + q * 128) = w;
.LBB0_816:
	s_lshl_b64 s[4:5], s[70:71], 21
	s_add_u32 s20, s57, s4
	s_addc_u32 s21, s59, s5
	s_lshl_b32 s70, s68, 2
	s_or_b32 s4, s70, s41
	s_ashr_i32 s5, s4, 31
	v_lshl_add_u32 v72, s68, 8, v200
	v_ashrrev_i32_e32 v73, 31, v72
	s_lshl_b64 s[4:5], s[4:5], 15
	v_lshlrev_b64 v[72:73], 2, v[72:73]
	s_add_u32 s20, s20, s4
	v_lshl_add_u64 v[74:75], s[26:27], 0, v[72:73]
	s_addc_u32 s21, s21, s5
	global_load_dwordx4 v[194:197], v[74:75], off offset:16
	global_load_dwordx4 v[178:181], v[74:75], off
	global_load_dwordx4 v[214:217], v164, s[20:21]
	v_lshl_add_u64 v[72:73], s[24:25], 0, v[72:73]
	s_waitcnt lgkmcnt(0)
	global_load_dwordx4 v[76:79], v[72:73], off
	s_nop 0
	global_load_dwordx4 v[72:75], v[72:73], off offset:16
	v_cndmask_b32_e64 v136, v135, v127, s[10:11]
	v_cndmask_b32_e64 v137, v134, v126, s[10:11]
	v_cndmask_b32_e64 v138, v133, v125, s[10:11]
	v_cndmask_b32_e64 v139, v132, v124, s[10:11]
	v_mov_b32_e32 v189, 0
	v_mov_b32_e32 v193, 0
	v_mov_b32_e32 v191, 0
	v_mov_b32_e32 v209, 0
	v_cndmask_b32_e64 v140, v131, v123, s[10:11]
	v_cndmask_b32_e64 v141, v130, v122, s[10:11]
	v_cndmask_b32_e64 v142, v129, v121, s[10:11]
	v_cndmask_b32_e64 v143, v128, v120, s[10:11]
	v_mov_b32_e32 v210, 0
	v_mov_b32_e32 v212, 0
	v_mov_b32_e32 v211, 0
	v_mov_b32_e32 v213, 0
	v_mov_b32_dpp v189, v139 quad_perm:[1,0,3,2] row_mask:0xf bank_mask:0xf
	v_mov_b32_dpp v193, v138 quad_perm:[1,0,3,2] row_mask:0xf bank_mask:0xf
	v_mov_b32_dpp v191, v137 quad_perm:[1,0,3,2] row_mask:0xf bank_mask:0xf
	v_mov_b32_dpp v209, v136 quad_perm:[1,0,3,2] row_mask:0xf bank_mask:0xf
	v_mov_b32_dpp v210, v143 quad_perm:[1,0,3,2] row_mask:0xf bank_mask:0xf
	v_mov_b32_dpp v212, v142 quad_perm:[1,0,3,2] row_mask:0xf bank_mask:0xf
	v_mov_b32_dpp v211, v141 quad_perm:[1,0,3,2] row_mask:0xf bank_mask:0xf
	v_mov_b32_dpp v213, v140 quad_perm:[1,0,3,2] row_mask:0xf bank_mask:0xf
	v_add_u32_e32 v192, 0x800, v164
	v_add_u32_e32 v190, 0x1000, v164
	v_add_u32_e32 v188, 0x1800, v164
	ds_read_b64 v[218:219], v201
	v_cndmask_b32_e64 v221, v193, v133, s[10:11]
	v_cndmask_b32_e64 v220, v189, v132, s[10:11]
	v_cndmask_b32_e64 v223, v209, v135, s[10:11]
	v_cndmask_b32_e64 v222, v191, v134, s[10:11]
	v_cndmask_b32_e64 v225, v212, v129, s[10:11]
	v_cndmask_b32_e64 v224, v210, v128, s[10:11]
	v_cndmask_b32_e64 v227, v213, v131, s[10:11]
	v_cndmask_b32_e64 v226, v211, v130, s[10:11]
	global_load_dwordx4 v[152:155], v164, s[20:21] offset:128
	global_load_dwordx4 v[148:151], v192, s[20:21]
	global_load_dwordx4 v[144:147], v192, s[20:21] offset:128
	global_load_dwordx4 v[140:143], v190, s[20:21]
	global_load_dwordx4 v[136:139], v190, s[20:21] offset:128
	global_load_dwordx4 v[132:135], v188, s[20:21]
	global_load_dwordx4 v[128:131], v188, s[20:21] offset:128
	s_waitcnt lgkmcnt(0)
	v_mul_f32_e32 v208, 0x3fb504f3, v219
	v_lshl_add_u64 v[186:187], v[166:167], 0, s[72:73]
	s_ashr_i32 s71, s70, 31
	v_lshl_add_u64 v[186:187], s[70:71], 3, v[186:187]
	v_lshl_add_u64 v[186:187], v[186:187], 0, s[22:23]
	v_add_u32_e32 v246, 0x4000, v164
	v_add_u32_e32 v247, 0x4800, v164
	global_load_dwordx4 v[230:233], v246, s[20:21]
	global_load_dwordx4 v[234:237], v246, s[20:21] offset:128
	global_load_dwordx4 v[238:241], v247, s[20:21]
	global_load_dwordx4 v[242:245], v247, s[20:21] offset:128
	s_waitcnt vmcnt(14)
	v_pk_mul_f32 v[182:183], v[180:181], s[58:59] op_sel_hi:[1,0]
	v_pk_mul_f32 v[184:185], v[178:179], s[58:59] op_sel_hi:[1,0]
	v_pk_mul_f32 v[178:179], v[196:197], s[58:59] op_sel_hi:[1,0]
	v_pk_mul_f32 v[180:181], v[194:195], s[58:59] op_sel_hi:[1,0]
	s_waitcnt vmcnt(13)
	v_lshlrev_b32_e32 v194, 16, v214
	v_and_b32_e32 v195, 0xffff0000, v214
	v_lshlrev_b32_e32 v196, 16, v215
	v_and_b32_e32 v197, 0xffff0000, v215
	v_lshlrev_b32_e32 v207, 16, v216
	v_and_b32_e32 v214, 0xffff0000, v216
	v_lshlrev_b32_e32 v216, 16, v217
	v_and_b32_e32 v217, 0xffff0000, v217
	v_sub_f32_e32 v195, v195, v218
	v_sub_f32_e32 v194, v194, v218
	v_sub_f32_e32 v197, v197, v218
	v_sub_f32_e32 v196, v196, v218
	v_sub_f32_e32 v215, v214, v218
	v_sub_f32_e32 v214, v207, v218
	v_sub_f32_e32 v217, v217, v218
	v_sub_f32_e32 v216, v216, v218
	v_pk_mul_f32 v[196:197], v[196:197], v[208:209] op_sel_hi:[1,0]
	v_pk_mul_f32 v[194:195], v[194:195], v[208:209] op_sel_hi:[1,0]
	v_pk_mul_f32 v[216:217], v[216:217], v[208:209] op_sel_hi:[1,0]
	v_pk_mul_f32 v[214:215], v[214:215], v[208:209] op_sel_hi:[1,0]
	s_waitcnt vmcnt(12)
	v_pk_fma_f32 v[194:195], v[76:77], v[194:195], v[184:185]
	v_pk_fma_f32 v[196:197], v[78:79], v[196:197], v[182:183]
	s_waitcnt vmcnt(11)
	v_pk_fma_f32 v[214:215], v[72:73], v[214:215], v[180:181]
	v_pk_fma_f32 v[216:217], v[74:75], v[216:217], v[178:179]
	v_pk_add_f32 v[196:197], v[222:223], v[196:197]
	v_pk_add_f32 v[194:195], v[220:221], v[194:195]
	v_pk_add_f32 v[218:219], v[226:227], v[216:217]
	v_pk_add_f32 v[216:217], v[224:225], v[214:215]
	v_cvt_pk_bf16_f32 v214, v194, v195
	v_cvt_pk_bf16_f32 v215, v196, v197
	v_and_b32_e32 v208, 64, v206
	v_cvt_pk_bf16_f32 v216, v216, v217
	v_cvt_pk_bf16_f32 v217, v218, v219
	v_lshlrev_b32_e32 v194, 16, v214
	v_and_b32_e32 v196, 0xffff0000, v214
	v_lshlrev_b32_e32 v218, 16, v215
	v_and_b32_e32 v220, 0xffff0000, v215
	v_lshlrev_b32_e32 v222, 16, v216
	v_and_b32_e32 v224, 0xffff0000, v216
	v_lshlrev_b32_e32 v226, 16, v217
	v_and_b32_e32 v228, 0xffff0000, v217
	v_mul_f32_e32 v195, v194, v194
	v_mul_f32_e32 v197, v196, v196
	v_mul_f32_e32 v219, v218, v218
	v_mul_f32_e32 v221, v220, v220
	v_mul_f32_e32 v223, v222, v222
	v_mul_f32_e32 v225, v224, v224
	v_mul_f32_e32 v227, v226, v226
	v_mul_f32_e32 v229, v228, v228
	v_pk_add_f32 v[194:195], v[194:195], v[196:197]
	v_pk_add_f32 v[196:197], v[218:219], v[220:221]
	v_pk_add_f32 v[218:219], v[226:227], v[228:229]
	v_pk_add_f32 v[194:195], v[194:195], v[196:197]
	v_pk_add_f32 v[196:197], v[222:223], v[224:225]
	v_xor_b32_e32 v207, 16, v206
	v_add_u32_e32 v208, 64, v208
	v_pk_add_f32 v[196:197], v[196:197], v[218:219]
	v_cmp_lt_i32_e32 vcc, v207, v208
	v_pk_add_f32 v[194:195], v[194:195], v[196:197]
	v_mov_b32_e32 v196, 0
	v_mov_b32_e32 v197, 0
	v_cndmask_b32_e32 v207, v206, v207, vcc
	v_mov_b32_dpp v196, v194 quad_perm:[1,0,3,2] row_mask:0xf bank_mask:0xf
	v_mov_b32_dpp v197, v195 quad_perm:[1,0,3,2] row_mask:0xf bank_mask:0xf
	v_lshlrev_b32_e32 v207, 2, v207
	v_pk_add_f32 v[194:195], v[194:195], v[196:197]
	ds_bpermute_b32 v196, v207, v194
	ds_bpermute_b32 v197, v207, v195
	v_xor_b32_e32 v218, 32, v206
	v_cmp_lt_i32_e32 vcc, v218, v208
	global_store_dwordx4 v164, v[214:217], s[20:21]
	s_waitcnt lgkmcnt(0)
	v_pk_add_f32 v[194:195], v[194:195], v[196:197]
	v_cndmask_b32_e32 v208, v206, v218, vcc
	v_lshlrev_b32_e32 v208, 2, v208
	ds_bpermute_b32 v196, v208, v194
	ds_bpermute_b32 v197, v208, v195
	s_and_saveexec_b64 s[52:53], s[16:17]
	s_waitcnt lgkmcnt(0)
	v_pk_add_f32 v[194:195], v[194:195], v[196:197]
	global_store_dwordx2 v[186:187], v[194:195], off
; __device__ __forceinline__ u32x4 pack8f(f32x4 a, f32x4 b) { u32x4 w; w.x = cvt_pk_bf16(a[0], a[1]); w.y = cvt_pk_bf16(a[2], a[3]); w.z = cvt_pk_bf16(b[0], b[1]); w.w = cvt_pk_bf16(b[2], b[3]); return w; }
;     __device__ __forceinline__ void operator()(const f32x4 (&acc)[2][2][4][2], const Unit& u, int wr, int wc, int fr, int fq, const EpiCtx& X) const {
;     ...
;             for (int m = 0; m < 4; ++m) {
;                 const int rl = ai * HALF + m * 16; const unsigned off = lo + (unsigned)(rl * 64) * 2u;
;                 const f32x4 o0a = acc[ai][0][m][0], o0b = acc[ai][0][m][1], o1a = acc[ai][1][m][0], o1b = acc[ai][1][m][1];
;                 const f32x4 ra_ = dpp_swap1(odd ? o0a : o1a), rb_ = dpp_swap1(odd ? o0b : o1b);
;                 const f32x4 pa[2] = {odd ? ra_ : o0a, odd ? o1a : ra_}, pb[2] = {odd ? rb_ : o0b, odd ? o1b : rb_};
; #pragma unroll
;                 for (int q = 0; q < 2; ++q) {
;                     const u32x4 w0 = raw[2 * m + q];
;                     const f32x4 r0 = (f32x4){bf_lo(w0.x), bf_hi(w0.x), bf_lo(w0.y), bf_hi(w0.y)}, r1 = (f32x4){bf_lo(w0.z), bf_hi(w0.z), bf_lo(w0.w), bf_hi(w0.w)};
;                     f32x4 y0, y1;
;                     if (RESN) { const f32x2 t = tbl[rl + q]; const float mu = t.x, ra = t.y * ALPHA; y0 = (r0 - mu) * ra * g0 + b0 + pa[q]; y1 = (r1 - mu) * ra * g1 + b1 + pb[q]; }
;                     else { y0 = r0 * ALPHA + pa[q]; y1 = r1 * ALPHA + pb[q]; }
;                     { const u32x4 w = pack8f(y0, y1); *(u32x4*)(xb + off + q * 128) = w;
;                         y0 = (f32x4){bf_lo(w.x), bf_hi(w.x), bf_lo(w.y), bf_hi(w.y)}; y1 = (f32x4){bf_lo(w.z), bf_hi(w.z), bf_lo(w.w), bf_hi(w.w)}; }
;                     float sa = ((y0[0] + y0[1]) + (y0[2] + y0[3])) + ((y1[0] + y1[1]) + (y1[2] + y1[3]));
;                     float sb = ((y0[0] * y0[0] + y0[1] * y0[1]) + (y0[2] * y0[2] + y0[3] * y0[3])) + ((y1[0] * y1[0] + y1[1] * y1[1]) + (y1[2] * y1[2] + y1[3] * y1[3]));
;                     sa += dpp_x1(sa);
;                     sb += dpp_x1(sb);
;                     sa += __shfl_xor(sa, 16); sa += __shfl_xor(sa, 32); sb += __shfl_xor(sb, 16); sb += __shfl_xor(sb, 32);
;                     if (fq == 0 && !odd) ps[(size_t)(rl + q) * 64] = (f32x2){sa, sb};
.LBB0_818:
	s_or_b64 exec, exec, s[52:53]
	v_cndmask_b32_e64 v125, v125, v193, s[10:11]
	v_cndmask_b32_e64 v124, v124, v189, s[10:11]
	v_cndmask_b32_e64 v126, v126, v191, s[10:11]
	s_waitcnt vmcnt(12)
	v_lshlrev_b32_e32 v189, 16, v152
	v_and_b32_e32 v191, 0xffff0000, v152
	v_lshlrev_b32_e32 v193, 16, v153
	s_waitcnt lgkmcnt(1)
	v_and_b32_e32 v196, 0xffff0000, v153
	ds_read_b64 v[152:153], v201 offset:8
	v_cndmask_b32_e64 v127, v127, v209, s[10:11]
	v_cndmask_b32_e64 v120, v120, v210, s[10:11]
	v_cndmask_b32_e64 v122, v122, v211, s[10:11]
	v_lshlrev_b32_e32 v209, 16, v154
	v_and_b32_e32 v210, 0xffff0000, v154
	v_lshlrev_b32_e32 v211, 16, v155
	v_and_b32_e32 v155, 0xffff0000, v155
	s_waitcnt lgkmcnt(0)
	v_mul_f32_e32 v154, 0x3fb504f3, v153
	v_sub_f32_e32 v195, v191, v152
	v_sub_f32_e32 v194, v189, v152
	v_pk_mul_f32 v[194:195], v[194:195], v[154:155] op_sel_hi:[1,0]
	v_sub_f32_e32 v197, v196, v152
	v_pk_fma_f32 v[194:195], v[76:77], v[194:195], v[184:185]
	v_sub_f32_e32 v196, v193, v152
	v_pk_add_f32 v[124:125], v[124:125], v[194:195]
	v_sub_f32_e32 v195, v210, v152
	v_sub_f32_e32 v194, v209, v152
	v_sub_f32_e32 v153, v155, v152
	v_sub_f32_e32 v152, v211, v152
	v_pk_mul_f32 v[196:197], v[196:197], v[154:155] op_sel_hi:[1,0]
	v_pk_mul_f32 v[152:153], v[152:153], v[154:155] op_sel_hi:[1,0]
	v_pk_mul_f32 v[154:155], v[194:195], v[154:155] op_sel_hi:[1,0]
	v_cndmask_b32_e64 v121, v121, v212, s[10:11]
	v_cndmask_b32_e64 v123, v123, v213, s[10:11]
	v_pk_fma_f32 v[196:197], v[78:79], v[196:197], v[182:183]
	v_pk_fma_f32 v[154:155], v[72:73], v[154:155], v[180:181]
	v_pk_fma_f32 v[152:153], v[74:75], v[152:153], v[178:179]
	v_pk_add_f32 v[126:127], v[126:127], v[196:197]
	v_pk_add_f32 v[122:123], v[122:123], v[152:153]
	v_pk_add_f32 v[120:121], v[120:121], v[154:155]
	v_cvt_pk_bf16_f32 v124, v124, v125
	v_cvt_pk_bf16_f32 v125, v126, v127
	s_nop 0
	v_cvt_pk_bf16_f32 v126, v120, v121
	v_cvt_pk_bf16_f32 v127, v122, v123
	v_lshlrev_b32_e32 v120, 16, v124
	v_and_b32_e32 v122, 0xffff0000, v124
	v_lshlrev_b32_e32 v152, 16, v125
	v_and_b32_e32 v154, 0xffff0000, v125
	v_lshlrev_b32_e32 v194, 16, v126
	v_and_b32_e32 v196, 0xffff0000, v126
	v_lshlrev_b32_e32 v210, 16, v127
	v_and_b32_e32 v212, 0xffff0000, v127
	v_mul_f32_e32 v121, v120, v120
	v_mul_f32_e32 v123, v122, v122
	v_mul_f32_e32 v153, v152, v152
	v_mul_f32_e32 v155, v154, v154
	v_mul_f32_e32 v195, v194, v194
	v_mul_f32_e32 v197, v196, v196
	v_mul_f32_e32 v211, v210, v210
	v_mul_f32_e32 v213, v212, v212
	v_pk_add_f32 v[120:121], v[120:121], v[122:123]
	v_pk_add_f32 v[122:123], v[152:153], v[154:155]
	v_pk_add_f32 v[152:153], v[210:211], v[212:213]
	v_pk_add_f32 v[120:121], v[120:121], v[122:123]
	v_pk_add_f32 v[122:123], v[194:195], v[196:197]
	s_nop 0
	v_pk_add_f32 v[122:123], v[122:123], v[152:153]
	v_lshl_add_u64 v[152:153], s[20:21], 0, v[164:165]
	v_pk_add_f32 v[120:121], v[120:121], v[122:123]
	v_mov_b32_e32 v122, v165
	v_mov_b32_e32 v123, v165
	global_store_dwordx4 v[152:153], v[124:127], off offset:128
	v_mov_b32_dpp v122, v120 quad_perm:[1,0,3,2] row_mask:0xf bank_mask:0xf
	v_mov_b32_dpp v123, v121 quad_perm:[1,0,3,2] row_mask:0xf bank_mask:0xf
	v_pk_add_f32 v[120:121], v[120:121], v[122:123]
	ds_bpermute_b32 v122, v207, v120
	ds_bpermute_b32 v123, v207, v121
	s_waitcnt lgkmcnt(0)
	v_pk_add_f32 v[120:121], v[120:121], v[122:123]
	ds_bpermute_b32 v122, v208, v120
	ds_bpermute_b32 v123, v208, v121
	s_and_saveexec_b64 s[52:53], s[16:17]
	s_waitcnt lgkmcnt(0)
	v_pk_add_f32 v[120:121], v[120:121], v[122:123]
	global_store_dwordx2 v[186:187], v[120:121], off offset:512
.LBB0_820:
	s_or_b64 exec, exec, s[52:53]
	s_waitcnt lgkmcnt(1)
	v_cndmask_b32_e64 v122, v116, v108, s[10:11]
	v_mov_b32_e32 v120, 0
	v_cndmask_b32_e64 v121, v117, v109, s[10:11]
	s_waitcnt lgkmcnt(0)
	v_cndmask_b32_e64 v123, v118, v110, s[10:11]
	v_mov_b32_dpp v120, v122 quad_perm:[1,0,3,2] row_mask:0xf bank_mask:0xf
	v_mov_b32_e32 v122, 0
	v_cndmask_b32_e64 v124, v119, v111, s[10:11]
	v_cndmask_b32_e64 v126, v112, v104, s[10:11]
	v_mov_b32_dpp v122, v121 quad_perm:[1,0,3,2] row_mask:0xf bank_mask:0xf
	v_mov_b32_e32 v121, 0
	v_cndmask_b32_e64 v125, v113, v105, s[10:11]
	v_cndmask_b32_e64 v127, v114, v106, s[10:11]
	v_mov_b32_dpp v121, v123 quad_perm:[1,0,3,2] row_mask:0xf bank_mask:0xf
	v_mov_b32_e32 v123, 0
	v_cndmask_b32_e64 v152, v115, v107, s[10:11]
	s_waitcnt vmcnt(13)
	v_and_b32_e32 v153, 0xffff0000, v148
	v_mov_b32_dpp v123, v124 quad_perm:[1,0,3,2] row_mask:0xf bank_mask:0xf
	v_mov_b32_e32 v124, 0
	v_lshlrev_b32_e32 v154, 16, v149
	v_and_b32_e32 v155, 0xffff0000, v149
	v_mov_b32_dpp v124, v126 quad_perm:[1,0,3,2] row_mask:0xf bank_mask:0xf
	v_mov_b32_e32 v126, 0
	v_lshlrev_b32_e32 v189, 16, v150
	v_and_b32_e32 v191, 0xffff0000, v150
	v_mov_b32_dpp v126, v125 quad_perm:[1,0,3,2] row_mask:0xf bank_mask:0xf
	v_mov_b32_e32 v125, 0
	v_lshlrev_b32_e32 v193, 16, v151
	v_and_b32_e32 v151, 0xffff0000, v151
	v_mov_b32_dpp v125, v127 quad_perm:[1,0,3,2] row_mask:0xf bank_mask:0xf
	v_mov_b32_e32 v127, 0
	v_cndmask_b32_e64 v117, v122, v117, s[10:11]
	v_cndmask_b32_e64 v116, v120, v116, s[10:11]
	v_mov_b32_dpp v127, v152 quad_perm:[1,0,3,2] row_mask:0xf bank_mask:0xf
	v_lshlrev_b32_e32 v152, 16, v148
	ds_read_b64 v[148:149], v201 offset:128
	v_cndmask_b32_e64 v119, v123, v119, s[10:11]
	v_cndmask_b32_e64 v118, v121, v118, s[10:11]
	v_cndmask_b32_e64 v113, v126, v113, s[10:11]
	v_cndmask_b32_e64 v112, v124, v112, s[10:11]
	s_waitcnt lgkmcnt(0)
; __device__ __forceinline__ u32x4 pack8f(f32x4 a, f32x4 b) { u32x4 w; w.x = cvt_pk_bf16(a[0], a[1]); w.y = cvt_pk_bf16(a[2], a[3]); w.z = cvt_pk_bf16(b[0], b[1]); w.w = cvt_pk_bf16(b[2], b[3]); return w; }
;     __device__ __forceinline__ void operator()(const f32x4 (&acc)[2][2][4][2], const Unit& u, int wr, int wc, int fr, int fq, const EpiCtx& X) const {
;     ...
;             for (int m = 0; m < 4; ++m) {
;                 const int rl = ai * HALF + m * 16; const unsigned off = lo + (unsigned)(rl * 64) * 2u;
;                 const f32x4 o0a = acc[ai][0][m][0], o0b = acc[ai][0][m][1], o1a = acc[ai][1][m][0], o1b = acc[ai][1][m][1];
;                 const f32x4 ra_ = dpp_swap1(odd ? o0a : o1a), rb_ = dpp_swap1(odd ? o0b : o1b);
;                 const f32x4 pa[2] = {odd ? ra_ : o0a, odd ? o1a : ra_}, pb[2] = {odd ? rb_ : o0b, odd ? o1b : rb_};
; #pragma unroll
;                 for (int q = 0; q < 2; ++q) {
;                     const u32x4 w0 = raw[2 * m + q];
;                     const f32x4 r0 = (f32x4){bf_lo(w0.x), bf_hi(w0.x), bf_lo(w0.y), bf_hi(w0.y)}, r1 = (f32x4){bf_lo(w0.z), bf_hi(w0.z), bf_lo(w0.w), bf_hi(w0.w)};
;                     f32x4 y0, y1;
;                     if (RESN) { const f32x2 t = tbl[rl + q]; const float mu = t.x, ra = t.y * ALPHA; y0 = (r0 - mu) * ra * g0 + b0 + pa[q]; y1 = (r1 - mu) * ra * g1 + b1 + pb[q]; }
;                     else { y0 = r0 * ALPHA + pa[q]; y1 = r1 * ALPHA + pb[q]; }
;                     { const u32x4 w = pack8f(y0, y1); *(u32x4*)(xb + off + q * 128) = w;
;                         y0 = (f32x4){bf_lo(w.x), bf_hi(w.x), bf_lo(w.y), bf_hi(w.y)}; y1 = (f32x4){bf_lo(w.z), bf_hi(w.z), bf_lo(w.w), bf_hi(w.w)}; }
;                     float sa = ((y0[0] + y0[1]) + (y0[2] + y0[3])) + ((y1[0] + y1[1]) + (y1[2] + y1[3]));
;                     float sb = ((y0[0] * y0[0] + y0[1] * y0[1]) + (y0[2] * y0[2] + y0[3] * y0[3])) + ((y1[0] * y1[0] + y1[1] * y1[1]) + (y1[2] * y1[2] + y1[3] * y1[3]));
;                     sa += dpp_x1(sa);
;                     sb += dpp_x1(sb);
;                     sa += __shfl_xor(sa, 16); sa += __shfl_xor(sa, 32); sb += __shfl_xor(sb, 16); sb += __shfl_xor(sb, 32);
;                     if (fq == 0 && !odd) ps[(size_t)(rl + q) * 64] = (f32x2){sa, sb};
	v_mul_f32_e32 v150, 0x3fb504f3, v149
	v_sub_f32_e32 v153, v153, v148
	v_sub_f32_e32 v152, v152, v148
	v_pk_mul_f32 v[152:153], v[152:153], v[150:151] op_sel_hi:[1,0]
	v_sub_f32_e32 v155, v155, v148
	v_pk_fma_f32 v[152:153], v[76:77], v[152:153], v[184:185]
	v_sub_f32_e32 v154, v154, v148
	v_pk_add_f32 v[116:117], v[116:117], v[152:153]
	v_sub_f32_e32 v153, v191, v148
	v_sub_f32_e32 v152, v189, v148
	v_sub_f32_e32 v149, v151, v148
	v_sub_f32_e32 v148, v193, v148
	v_pk_mul_f32 v[154:155], v[154:155], v[150:151] op_sel_hi:[1,0]
	v_pk_mul_f32 v[148:149], v[148:149], v[150:151] op_sel_hi:[1,0]
	v_pk_mul_f32 v[150:151], v[152:153], v[150:151] op_sel_hi:[1,0]
	v_cndmask_b32_e64 v115, v127, v115, s[10:11]
	v_cndmask_b32_e64 v114, v125, v114, s[10:11]
	v_pk_fma_f32 v[154:155], v[78:79], v[154:155], v[182:183]
	v_pk_fma_f32 v[150:151], v[72:73], v[150:151], v[180:181]
	v_pk_fma_f32 v[148:149], v[74:75], v[148:149], v[178:179]
	v_pk_add_f32 v[118:119], v[118:119], v[154:155]
	v_pk_add_f32 v[114:115], v[114:115], v[148:149]
	v_pk_add_f32 v[112:113], v[112:113], v[150:151]
	v_cvt_pk_bf16_f32 v148, v116, v117
	v_cvt_pk_bf16_f32 v149, v118, v119
	v_mov_b32_e32 v193, v165
	v_cvt_pk_bf16_f32 v150, v112, v113
	v_cvt_pk_bf16_f32 v151, v114, v115
	v_lshlrev_b32_e32 v112, 16, v148
	v_and_b32_e32 v114, 0xffff0000, v148
	v_lshlrev_b32_e32 v116, 16, v149
	v_and_b32_e32 v118, 0xffff0000, v149
	v_lshlrev_b32_e32 v152, 16, v150
	v_and_b32_e32 v154, 0xffff0000, v150
	v_lshlrev_b32_e32 v194, 16, v151
	v_and_b32_e32 v196, 0xffff0000, v151
	v_mul_f32_e32 v113, v112, v112
	v_mul_f32_e32 v115, v114, v114
	v_mul_f32_e32 v117, v116, v116
	v_mul_f32_e32 v119, v118, v118
	v_mul_f32_e32 v153, v152, v152
	v_mul_f32_e32 v155, v154, v154
	v_mul_f32_e32 v195, v194, v194
	v_mul_f32_e32 v197, v196, v196
	v_pk_add_f32 v[112:113], v[112:113], v[114:115]
	v_pk_add_f32 v[114:115], v[116:117], v[118:119]
	v_pk_add_f32 v[116:117], v[194:195], v[196:197]
	v_pk_add_f32 v[112:113], v[112:113], v[114:115]
	v_pk_add_f32 v[114:115], v[152:153], v[154:155]
	s_nop 0
	v_pk_add_f32 v[114:115], v[114:115], v[116:117]
	s_nop 0
	v_pk_add_f32 v[112:113], v[112:113], v[114:115]
	v_mov_b32_e32 v114, v165
	v_mov_b32_e32 v115, v165
	s_nop 0
	v_mov_b32_dpp v114, v112 quad_perm:[1,0,3,2] row_mask:0xf bank_mask:0xf
	v_mov_b32_dpp v115, v113 quad_perm:[1,0,3,2] row_mask:0xf bank_mask:0xf
	v_pk_add_f32 v[112:113], v[112:113], v[114:115]
	ds_bpermute_b32 v114, v207, v112
	ds_bpermute_b32 v115, v207, v113
	s_waitcnt lgkmcnt(0)
	v_pk_add_f32 v[114:115], v[112:113], v[114:115]
	ds_bpermute_b32 v116, v208, v114
	ds_bpermute_b32 v117, v208, v115
	v_lshl_add_u64 v[112:113], s[20:21], 0, v[192:193]
	global_store_dwordx4 v[112:113], v[148:151], off
	s_and_saveexec_b64 s[68:69], s[16:17]
	s_waitcnt lgkmcnt(0)
	v_pk_add_f32 v[114:115], v[114:115], v[116:117]
	v_add_co_u32_e32 v116, vcc, 0x2000, v186
	s_nop 1
	v_addc_co_u32_e32 v117, vcc, 0, v187, vcc
	global_store_dwordx2 v[116:117], v[114:115], off
.LBB0_822:
	s_or_b64 exec, exec, s[68:69]
	ds_read_b64 v[114:115], v201 offset:136
	s_waitcnt lgkmcnt(1)
	s_waitcnt vmcnt(14)
	v_lshlrev_b32_e32 v117, 16, v144
	v_and_b32_e32 v118, 0xffff0000, v144
	v_cndmask_b32_e64 v109, v109, v122, s[10:11]
	v_cndmask_b32_e64 v108, v108, v120, s[10:11]
	s_waitcnt lgkmcnt(0)
	v_mul_f32_e32 v116, 0x3fb504f3, v115
	v_sub_f32_e32 v119, v118, v114
	v_sub_f32_e32 v118, v117, v114
	v_pk_mul_f32 v[118:119], v[118:119], v[116:117] op_sel_hi:[1,0]
	v_cndmask_b32_e64 v111, v111, v123, s[10:11]
	v_cndmask_b32_e64 v110, v110, v121, s[10:11]
	v_cndmask_b32_e64 v104, v104, v124, s[10:11]
	v_cndmask_b32_e64 v106, v106, v125, s[10:11]
	v_lshlrev_b32_e32 v120, 16, v145
	v_and_b32_e32 v121, 0xffff0000, v145
	v_lshlrev_b32_e32 v122, 16, v146
	v_and_b32_e32 v123, 0xffff0000, v146
	v_lshlrev_b32_e32 v124, 16, v147
	v_and_b32_e32 v125, 0xffff0000, v147
	v_pk_fma_f32 v[118:119], v[76:77], v[118:119], v[184:185]
	v_sub_f32_e32 v121, v121, v114
	v_sub_f32_e32 v120, v120, v114
	v_pk_add_f32 v[108:109], v[108:109], v[118:119]
	v_sub_f32_e32 v119, v123, v114
	v_sub_f32_e32 v118, v122, v114
	v_sub_f32_e32 v115, v125, v114
	v_sub_f32_e32 v114, v124, v114
	v_pk_mul_f32 v[120:121], v[120:121], v[116:117] op_sel_hi:[1,0]
	v_pk_mul_f32 v[114:115], v[114:115], v[116:117] op_sel_hi:[1,0]
	v_pk_mul_f32 v[116:117], v[118:119], v[116:117] op_sel_hi:[1,0]
	v_cndmask_b32_e64 v105, v105, v126, s[10:11]
	v_cndmask_b32_e64 v107, v107, v127, s[10:11]
	v_pk_fma_f32 v[120:121], v[78:79], v[120:121], v[182:183]
	v_pk_fma_f32 v[116:117], v[72:73], v[116:117], v[180:181]
	v_pk_fma_f32 v[114:115], v[74:75], v[114:115], v[178:179]
	v_pk_add_f32 v[110:111], v[110:111], v[120:121]
	v_pk_add_f32 v[106:107], v[106:107], v[114:115]
	v_pk_add_f32 v[104:105], v[104:105], v[116:117]
	v_cvt_pk_bf16_f32 v108, v108, v109
	v_cvt_pk_bf16_f32 v109, v110, v111
	s_nop 0
	v_cvt_pk_bf16_f32 v110, v104, v105
	v_cvt_pk_bf16_f32 v111, v106, v107
	v_lshlrev_b32_e32 v104, 16, v108
	v_and_b32_e32 v106, 0xffff0000, v108
	v_lshlrev_b32_e32 v114, 16, v109
	v_and_b32_e32 v116, 0xffff0000, v109
	v_lshlrev_b32_e32 v118, 16, v110
	v_and_b32_e32 v120, 0xffff0000, v110
	v_lshlrev_b32_e32 v122, 16, v111
	v_and_b32_e32 v124, 0xffff0000, v111
	v_mul_f32_e32 v105, v104, v104
	v_mul_f32_e32 v107, v106, v106
	v_mul_f32_e32 v115, v114, v114
	v_mul_f32_e32 v117, v116, v116
	v_mul_f32_e32 v119, v118, v118
	v_mul_f32_e32 v121, v120, v120
	v_mul_f32_e32 v123, v122, v122
	v_mul_f32_e32 v125, v124, v124
	v_pk_add_f32 v[104:105], v[104:105], v[106:107]
	v_pk_add_f32 v[106:107], v[114:115], v[116:117]
	v_pk_add_f32 v[114:115], v[122:123], v[124:125]
	v_pk_add_f32 v[104:105], v[104:105], v[106:107]
	v_pk_add_f32 v[106:107], v[118:119], v[120:121]
	global_store_dwordx4 v[112:113], v[108:111], off offset:128
	v_pk_add_f32 v[106:107], v[106:107], v[114:115]
	s_nop 0
	v_pk_add_f32 v[104:105], v[104:105], v[106:107]
	v_mov_b32_e32 v106, v165
	v_mov_b32_e32 v107, v165
	s_nop 0
	v_mov_b32_dpp v106, v104 quad_perm:[1,0,3,2] row_mask:0xf bank_mask:0xf
	v_mov_b32_dpp v107, v105 quad_perm:[1,0,3,2] row_mask:0xf bank_mask:0xf
	v_pk_add_f32 v[104:105], v[104:105], v[106:107]
	ds_bpermute_b32 v106, v207, v104
	ds_bpermute_b32 v107, v207, v105
	s_waitcnt lgkmcnt(0)
	v_pk_add_f32 v[104:105], v[104:105], v[106:107]
	ds_bpermute_b32 v106, v208, v104
	ds_bpermute_b32 v107, v208, v105
	s_and_saveexec_b64 s[68:69], s[16:17]
	s_waitcnt lgkmcnt(0)
	v_pk_add_f32 v[104:105], v[104:105], v[106:107]
	v_add_co_u32_e32 v106, vcc, 0x2000, v186
	s_nop 1
	v_addc_co_u32_e32 v107, vcc, 0, v187, vcc
	global_store_dwordx2 v[106:107], v[104:105], off offset:512
; __device__ __forceinline__ u32x4 pack8f(f32x4 a, f32x4 b) { u32x4 w; w.x = cvt_pk_bf16(a[0], a[1]); w.y = cvt_pk_bf16(a[2], a[3]); w.z = cvt_pk_bf16(b[0], b[1]); w.w = cvt_pk_bf16(b[2], b[3]); return w; }
;     __device__ __forceinline__ void operator()(const f32x4 (&acc)[2][2][4][2], const Unit& u, int wr, int wc, int fr, int fq, const EpiCtx& X) const {
;     ...
;             for (int m = 0; m < 4; ++m) {
;                 const int rl = ai * HALF + m * 16; const unsigned off = lo + (unsigned)(rl * 64) * 2u;
;                 const f32x4 o0a = acc[ai][0][m][0], o0b = acc[ai][0][m][1], o1a = acc[ai][1][m][0], o1b = acc[ai][1][m][1];
;                 const f32x4 ra_ = dpp_swap1(odd ? o0a : o1a), rb_ = dpp_swap1(odd ? o0b : o1b);
;                 const f32x4 pa[2] = {odd ? ra_ : o0a, odd ? o1a : ra_}, pb[2] = {odd ? rb_ : o0b, odd ? o1b : rb_};
; #pragma unroll
;                 for (int q = 0; q < 2; ++q) {
;                     const u32x4 w0 = raw[2 * m + q];
;                     const f32x4 r0 = (f32x4){bf_lo(w0.x), bf_hi(w0.x), bf_lo(w0.y), bf_hi(w0.y)}, r1 = (f32x4){bf_lo(w0.z), bf_hi(w0.z), bf_lo(w0.w), bf_hi(w0.w)};
;                     f32x4 y0, y1;
;                     if (RESN) { const f32x2 t = tbl[rl + q]; const float mu = t.x, ra = t.y * ALPHA; y0 = (r0 - mu) * ra * g0 + b0 + pa[q]; y1 = (r1 - mu) * ra * g1 + b1 + pb[q]; }
;                     else { y0 = r0 * ALPHA + pa[q]; y1 = r1 * ALPHA + pb[q]; }
;                     { const u32x4 w = pack8f(y0, y1); *(u32x4*)(xb + off + q * 128) = w;
;                         y0 = (f32x4){bf_lo(w.x), bf_hi(w.x), bf_lo(w.y), bf_hi(w.y)}; y1 = (f32x4){bf_lo(w.z), bf_hi(w.z), bf_lo(w.w), bf_hi(w.w)}; }
;                     float sa = ((y0[0] + y0[1]) + (y0[2] + y0[3])) + ((y1[0] + y1[1]) + (y1[2] + y1[3]));
;                     float sb = ((y0[0] * y0[0] + y0[1] * y0[1]) + (y0[2] * y0[2] + y0[3] * y0[3])) + ((y1[0] * y1[0] + y1[1] * y1[1]) + (y1[2] * y1[2] + y1[3] * y1[3]));
;                     sa += dpp_x1(sa);
;                     sb += dpp_x1(sb);
;                     sa += __shfl_xor(sa, 16); sa += __shfl_xor(sa, 32); sb += __shfl_xor(sb, 16); sb += __shfl_xor(sb, 32);
;                     if (fq == 0 && !odd) ps[(size_t)(rl + q) * 64] = (f32x2){sa, sb};
.LBB0_824:
	s_or_b64 exec, exec, s[68:69]
	s_waitcnt lgkmcnt(1)
	v_cndmask_b32_e64 v106, v100, v92, s[10:11]
	v_mov_b32_e32 v104, 0
	v_cndmask_b32_e64 v105, v101, v93, s[10:11]
	s_waitcnt lgkmcnt(0)
	v_cndmask_b32_e64 v107, v102, v94, s[10:11]
	v_mov_b32_dpp v104, v106 quad_perm:[1,0,3,2] row_mask:0xf bank_mask:0xf
	v_mov_b32_e32 v106, 0
	v_cndmask_b32_e64 v108, v103, v95, s[10:11]
	v_cndmask_b32_e64 v110, v96, v88, s[10:11]
	v_mov_b32_dpp v106, v105 quad_perm:[1,0,3,2] row_mask:0xf bank_mask:0xf
	v_mov_b32_e32 v105, 0
	v_cndmask_b32_e64 v109, v97, v89, s[10:11]
	v_cndmask_b32_e64 v111, v98, v90, s[10:11]
	v_mov_b32_dpp v105, v107 quad_perm:[1,0,3,2] row_mask:0xf bank_mask:0xf
	v_mov_b32_e32 v107, 0
	v_cndmask_b32_e64 v112, v99, v91, s[10:11]
	s_waitcnt vmcnt(15)
	v_lshlrev_b32_e32 v115, 16, v140
	v_mov_b32_dpp v107, v108 quad_perm:[1,0,3,2] row_mask:0xf bank_mask:0xf
	v_mov_b32_e32 v108, 0
	v_and_b32_e32 v116, 0xffff0000, v140
	v_cndmask_b32_e64 v101, v106, v101, s[10:11]
	v_mov_b32_dpp v108, v110 quad_perm:[1,0,3,2] row_mask:0xf bank_mask:0xf
	v_mov_b32_e32 v110, 0
	v_cndmask_b32_e64 v100, v104, v100, s[10:11]
	v_lshlrev_b32_e32 v118, 16, v141
	v_mov_b32_dpp v110, v109 quad_perm:[1,0,3,2] row_mask:0xf bank_mask:0xf
	v_mov_b32_e32 v109, 0
	v_and_b32_e32 v119, 0xffff0000, v141
	v_lshlrev_b32_e32 v120, 16, v142
	v_mov_b32_dpp v109, v111 quad_perm:[1,0,3,2] row_mask:0xf bank_mask:0xf
	v_mov_b32_e32 v111, 0
	v_and_b32_e32 v121, 0xffff0000, v142
	v_lshlrev_b32_e32 v122, 16, v143
	v_mov_b32_dpp v111, v112 quad_perm:[1,0,3,2] row_mask:0xf bank_mask:0xf
	ds_read_b64 v[112:113], v201 offset:256
	v_and_b32_e32 v123, 0xffff0000, v143
	v_cndmask_b32_e64 v103, v107, v103, s[10:11]
	v_cndmask_b32_e64 v102, v105, v102, s[10:11]
	v_cndmask_b32_e64 v97, v110, v97, s[10:11]
	s_waitcnt lgkmcnt(0)
	v_mul_f32_e32 v114, 0x3fb504f3, v113
	v_sub_f32_e32 v117, v116, v112
	v_sub_f32_e32 v116, v115, v112
	v_pk_mul_f32 v[116:117], v[116:117], v[114:115] op_sel_hi:[1,0]
	v_sub_f32_e32 v119, v119, v112
	v_pk_fma_f32 v[116:117], v[76:77], v[116:117], v[184:185]
	v_sub_f32_e32 v118, v118, v112
	v_pk_add_f32 v[100:101], v[100:101], v[116:117]
	v_sub_f32_e32 v117, v121, v112
	v_sub_f32_e32 v116, v120, v112
	v_sub_f32_e32 v113, v123, v112
	v_sub_f32_e32 v112, v122, v112
	v_pk_mul_f32 v[118:119], v[118:119], v[114:115] op_sel_hi:[1,0]
	v_pk_mul_f32 v[112:113], v[112:113], v[114:115] op_sel_hi:[1,0]
	v_pk_mul_f32 v[114:115], v[116:117], v[114:115] op_sel_hi:[1,0]
	v_cndmask_b32_e64 v96, v108, v96, s[10:11]
	v_cndmask_b32_e64 v99, v111, v99, s[10:11]
	v_cndmask_b32_e64 v98, v109, v98, s[10:11]
	v_pk_fma_f32 v[118:119], v[78:79], v[118:119], v[182:183]
	v_pk_fma_f32 v[114:115], v[72:73], v[114:115], v[180:181]
	v_pk_fma_f32 v[112:113], v[74:75], v[112:113], v[178:179]
	v_pk_add_f32 v[102:103], v[102:103], v[118:119]
	v_pk_add_f32 v[98:99], v[98:99], v[112:113]
	v_pk_add_f32 v[96:97], v[96:97], v[114:115]
	v_cvt_pk_bf16_f32 v112, v100, v101
	v_cvt_pk_bf16_f32 v113, v102, v103
	v_mov_b32_e32 v191, v165
	v_cvt_pk_bf16_f32 v114, v96, v97
	v_cvt_pk_bf16_f32 v115, v98, v99
	v_lshlrev_b32_e32 v96, 16, v112
	v_and_b32_e32 v98, 0xffff0000, v112
	v_lshlrev_b32_e32 v100, 16, v113
	v_and_b32_e32 v102, 0xffff0000, v113
	v_lshlrev_b32_e32 v116, 16, v114
	v_and_b32_e32 v118, 0xffff0000, v114
	v_lshlrev_b32_e32 v120, 16, v115
	v_and_b32_e32 v122, 0xffff0000, v115
	v_mul_f32_e32 v97, v96, v96
	v_mul_f32_e32 v99, v98, v98
	v_mul_f32_e32 v101, v100, v100
	v_mul_f32_e32 v103, v102, v102
	v_mul_f32_e32 v117, v116, v116
	v_mul_f32_e32 v119, v118, v118
	v_mul_f32_e32 v121, v120, v120
	v_mul_f32_e32 v123, v122, v122
	v_pk_add_f32 v[96:97], v[96:97], v[98:99]
	v_pk_add_f32 v[98:99], v[100:101], v[102:103]
	v_pk_add_f32 v[100:101], v[120:121], v[122:123]
	v_pk_add_f32 v[96:97], v[96:97], v[98:99]
	v_pk_add_f32 v[98:99], v[116:117], v[118:119]
	s_nop 0
	v_pk_add_f32 v[98:99], v[98:99], v[100:101]
	s_nop 0
	v_pk_add_f32 v[96:97], v[96:97], v[98:99]
	v_mov_b32_e32 v98, v165
	v_mov_b32_e32 v99, v165
	s_nop 0
	v_mov_b32_dpp v98, v96 quad_perm:[1,0,3,2] row_mask:0xf bank_mask:0xf
	v_mov_b32_dpp v99, v97 quad_perm:[1,0,3,2] row_mask:0xf bank_mask:0xf
	v_pk_add_f32 v[96:97], v[96:97], v[98:99]
	ds_bpermute_b32 v98, v207, v96
	ds_bpermute_b32 v99, v207, v97
	s_waitcnt lgkmcnt(0)
	v_pk_add_f32 v[98:99], v[96:97], v[98:99]
	ds_bpermute_b32 v100, v208, v98
	ds_bpermute_b32 v101, v208, v99
	v_lshl_add_u64 v[96:97], s[20:21], 0, v[190:191]
	global_store_dwordx4 v[96:97], v[112:115], off
	s_and_saveexec_b64 s[68:69], s[16:17]
	s_waitcnt lgkmcnt(0)
	v_pk_add_f32 v[98:99], v[98:99], v[100:101]
	v_add_co_u32_e32 v100, vcc, 0x4000, v186
	s_nop 1
	v_addc_co_u32_e32 v101, vcc, 0, v187, vcc
	global_store_dwordx2 v[100:101], v[98:99], off
; __device__ __forceinline__ u32x4 pack8f(f32x4 a, f32x4 b) { u32x4 w; w.x = cvt_pk_bf16(a[0], a[1]); w.y = cvt_pk_bf16(a[2], a[3]); w.z = cvt_pk_bf16(b[0], b[1]); w.w = cvt_pk_bf16(b[2], b[3]); return w; }
;     __device__ __forceinline__ void operator()(const f32x4 (&acc)[2][2][4][2], const Unit& u, int wr, int wc, int fr, int fq, const EpiCtx& X) const {
;     ...
;             for (int m = 0; m < 4; ++m) {
;                 const int rl = ai * HALF + m * 16; const unsigned off = lo + (unsigned)(rl * 64) * 2u;
;                 const f32x4 o0a = acc[ai][0][m][0], o0b = acc[ai][0][m][1], o1a = acc[ai][1][m][0], o1b = acc[ai][1][m][1];
;                 const f32x4 ra_ = dpp_swap1(odd ? o0a : o1a), rb_ = dpp_swap1(odd ? o0b : o1b);
;                 const f32x4 pa[2] = {odd ? ra_ : o0a, odd ? o1a : ra_}, pb[2] = {odd ? rb_ : o0b, odd ? o1b : rb_};
; #pragma unroll
;                 for (int q = 0; q < 2; ++q) {
;                     const u32x4 w0 = raw[2 * m + q];
;                     const f32x4 r0 = (f32x4){bf_lo(w0.x), bf_hi(w0.x), bf_lo(w0.y), bf_hi(w0.y)}, r1 = (f32x4){bf_lo(w0.z), bf_hi(w0.z), bf_lo(w0.w), bf_hi(w0.w)};
;                     f32x4 y0, y1;
;                     if (RESN) { const f32x2 t = tbl[rl + q]; const float mu = t.x, ra = t.y * ALPHA; y0 = (r0 - mu) * ra * g0 + b0 + pa[q]; y1 = (r1 - mu) * ra * g1 + b1 + pb[q]; }
;                     else { y0 = r0 * ALPHA + pa[q]; y1 = r1 * ALPHA + pb[q]; }
;                     { const u32x4 w = pack8f(y0, y1); *(u32x4*)(xb + off + q * 128) = w;
;                         y0 = (f32x4){bf_lo(w.x), bf_hi(w.x), bf_lo(w.y), bf_hi(w.y)}; y1 = (f32x4){bf_lo(w.z), bf_hi(w.z), bf_lo(w.w), bf_hi(w.w)}; }
;                     float sa = ((y0[0] + y0[1]) + (y0[2] + y0[3])) + ((y1[0] + y1[1]) + (y1[2] + y1[3]));
;                     float sb = ((y0[0] * y0[0] + y0[1] * y0[1]) + (y0[2] * y0[2] + y0[3] * y0[3])) + ((y1[0] * y1[0] + y1[1] * y1[1]) + (y1[2] * y1[2] + y1[3] * y1[3]));
;                     sa += dpp_x1(sa);
;                     sb += dpp_x1(sb);
;                     sa += __shfl_xor(sa, 16); sa += __shfl_xor(sa, 32); sb += __shfl_xor(sb, 16); sb += __shfl_xor(sb, 32);
;                     if (fq == 0 && !odd) ps[(size_t)(rl + q) * 64] = (f32x2){sa, sb};
.LBB0_826:
	s_or_b64 exec, exec, s[68:69]
	ds_read_b64 v[98:99], v201 offset:264
	s_waitcnt lgkmcnt(1)
	s_waitcnt vmcnt(16)
	v_lshlrev_b32_e32 v101, 16, v136
	v_and_b32_e32 v102, 0xffff0000, v136
	v_cndmask_b32_e64 v93, v93, v106, s[10:11]
	v_cndmask_b32_e64 v92, v92, v104, s[10:11]
	s_waitcnt lgkmcnt(0)
	v_mul_f32_e32 v100, 0x3fb504f3, v99
	v_sub_f32_e32 v103, v102, v98
	v_sub_f32_e32 v102, v101, v98
	v_pk_mul_f32 v[102:103], v[102:103], v[100:101] op_sel_hi:[1,0]
	v_cndmask_b32_e64 v95, v95, v107, s[10:11]
	v_cndmask_b32_e64 v94, v94, v105, s[10:11]
	v_cndmask_b32_e64 v88, v88, v108, s[10:11]
	v_cndmask_b32_e64 v90, v90, v109, s[10:11]
	v_lshlrev_b32_e32 v104, 16, v137
	v_and_b32_e32 v105, 0xffff0000, v137
	v_lshlrev_b32_e32 v106, 16, v138
	v_and_b32_e32 v107, 0xffff0000, v138
	v_lshlrev_b32_e32 v108, 16, v139
	v_and_b32_e32 v109, 0xffff0000, v139
	v_pk_fma_f32 v[102:103], v[76:77], v[102:103], v[184:185]
	v_sub_f32_e32 v105, v105, v98
	v_sub_f32_e32 v104, v104, v98
	v_pk_add_f32 v[92:93], v[92:93], v[102:103]
	v_sub_f32_e32 v103, v107, v98
	v_sub_f32_e32 v102, v106, v98
	v_sub_f32_e32 v99, v109, v98
	v_sub_f32_e32 v98, v108, v98
	v_pk_mul_f32 v[104:105], v[104:105], v[100:101] op_sel_hi:[1,0]
	v_pk_mul_f32 v[98:99], v[98:99], v[100:101] op_sel_hi:[1,0]
	v_pk_mul_f32 v[100:101], v[102:103], v[100:101] op_sel_hi:[1,0]
	v_cndmask_b32_e64 v89, v89, v110, s[10:11]
	v_cndmask_b32_e64 v91, v91, v111, s[10:11]
	v_pk_fma_f32 v[104:105], v[78:79], v[104:105], v[182:183]
	v_pk_fma_f32 v[100:101], v[72:73], v[100:101], v[180:181]
	v_pk_fma_f32 v[98:99], v[74:75], v[98:99], v[178:179]
	v_pk_add_f32 v[94:95], v[94:95], v[104:105]
	v_pk_add_f32 v[90:91], v[90:91], v[98:99]
	v_pk_add_f32 v[88:89], v[88:89], v[100:101]
	v_cvt_pk_bf16_f32 v92, v92, v93
	v_cvt_pk_bf16_f32 v93, v94, v95
	s_nop 0
	v_cvt_pk_bf16_f32 v94, v88, v89
	v_cvt_pk_bf16_f32 v95, v90, v91
	v_lshlrev_b32_e32 v88, 16, v92
	v_and_b32_e32 v90, 0xffff0000, v92
	v_lshlrev_b32_e32 v98, 16, v93
	v_and_b32_e32 v100, 0xffff0000, v93
	v_lshlrev_b32_e32 v102, 16, v94
	v_and_b32_e32 v104, 0xffff0000, v94
	v_lshlrev_b32_e32 v106, 16, v95
	v_and_b32_e32 v108, 0xffff0000, v95
	v_mul_f32_e32 v89, v88, v88
	v_mul_f32_e32 v91, v90, v90
	v_mul_f32_e32 v99, v98, v98
	v_mul_f32_e32 v101, v100, v100
	v_mul_f32_e32 v103, v102, v102
	v_mul_f32_e32 v105, v104, v104
	v_mul_f32_e32 v107, v106, v106
	v_mul_f32_e32 v109, v108, v108
	v_pk_add_f32 v[88:89], v[88:89], v[90:91]
	v_pk_add_f32 v[90:91], v[98:99], v[100:101]
	v_pk_add_f32 v[98:99], v[106:107], v[108:109]
	v_pk_add_f32 v[88:89], v[88:89], v[90:91]
	v_pk_add_f32 v[90:91], v[102:103], v[104:105]
	global_store_dwordx4 v[96:97], v[92:95], off offset:128
	v_pk_add_f32 v[90:91], v[90:91], v[98:99]
	s_nop 0
	v_pk_add_f32 v[88:89], v[88:89], v[90:91]
	v_mov_b32_e32 v90, v165
	v_mov_b32_e32 v91, v165
	s_nop 0
	v_mov_b32_dpp v90, v88 quad_perm:[1,0,3,2] row_mask:0xf bank_mask:0xf
	v_mov_b32_dpp v91, v89 quad_perm:[1,0,3,2] row_mask:0xf bank_mask:0xf
	v_pk_add_f32 v[88:89], v[88:89], v[90:91]
	ds_bpermute_b32 v90, v207, v88
	ds_bpermute_b32 v91, v207, v89
	s_waitcnt lgkmcnt(0)
	v_pk_add_f32 v[88:89], v[88:89], v[90:91]
	ds_bpermute_b32 v90, v208, v88
	ds_bpermute_b32 v91, v208, v89
	s_and_saveexec_b64 s[68:69], s[16:17]
	s_waitcnt lgkmcnt(0)
	v_pk_add_f32 v[88:89], v[88:89], v[90:91]
	v_add_co_u32_e32 v90, vcc, 0x4000, v186
	s_nop 1
	v_addc_co_u32_e32 v91, vcc, 0, v187, vcc
	global_store_dwordx2 v[90:91], v[88:89], off offset:512
.LBB0_828:
	s_or_b64 exec, exec, s[68:69]
	s_waitcnt lgkmcnt(1)
	v_cndmask_b32_e64 v90, v84, v68, s[10:11]
	v_mov_b32_e32 v88, 0
	v_cndmask_b32_e64 v89, v85, v69, s[10:11]
	s_waitcnt lgkmcnt(0)
	v_cndmask_b32_e64 v91, v86, v70, s[10:11]
	v_mov_b32_dpp v88, v90 quad_perm:[1,0,3,2] row_mask:0xf bank_mask:0xf
	v_mov_b32_e32 v90, 0
	v_cndmask_b32_e64 v92, v87, v71, s[10:11]
	v_cndmask_b32_e64 v94, v80, v64, s[10:11]
	v_mov_b32_dpp v90, v89 quad_perm:[1,0,3,2] row_mask:0xf bank_mask:0xf
	v_mov_b32_e32 v89, 0
	v_cndmask_b32_e64 v93, v81, v65, s[10:11]
	v_cndmask_b32_e64 v95, v82, v66, s[10:11]
	v_mov_b32_dpp v89, v91 quad_perm:[1,0,3,2] row_mask:0xf bank_mask:0xf
	v_mov_b32_e32 v91, 0
	v_cndmask_b32_e64 v96, v83, v67, s[10:11]
	s_waitcnt vmcnt(17)
	v_lshlrev_b32_e32 v99, 16, v132
	v_mov_b32_dpp v91, v92 quad_perm:[1,0,3,2] row_mask:0xf bank_mask:0xf
	v_mov_b32_e32 v92, 0
	v_and_b32_e32 v100, 0xffff0000, v132
	v_cndmask_b32_e64 v85, v90, v85, s[10:11]
	v_mov_b32_dpp v92, v94 quad_perm:[1,0,3,2] row_mask:0xf bank_mask:0xf
	v_mov_b32_e32 v94, 0
	v_cndmask_b32_e64 v84, v88, v84, s[10:11]
	v_lshlrev_b32_e32 v102, 16, v133
	v_mov_b32_dpp v94, v93 quad_perm:[1,0,3,2] row_mask:0xf bank_mask:0xf
	v_mov_b32_e32 v93, 0
	v_and_b32_e32 v103, 0xffff0000, v133
	v_lshlrev_b32_e32 v104, 16, v134
	v_mov_b32_dpp v93, v95 quad_perm:[1,0,3,2] row_mask:0xf bank_mask:0xf
	v_mov_b32_e32 v95, 0
	v_and_b32_e32 v105, 0xffff0000, v134
	v_lshlrev_b32_e32 v106, 16, v135
	v_mov_b32_dpp v95, v96 quad_perm:[1,0,3,2] row_mask:0xf bank_mask:0xf
	ds_read_b64 v[96:97], v201 offset:384
	v_and_b32_e32 v107, 0xffff0000, v135
	v_cndmask_b32_e64 v87, v91, v87, s[10:11]
	v_cndmask_b32_e64 v86, v89, v86, s[10:11]
	v_cndmask_b32_e64 v81, v94, v81, s[10:11]
	s_waitcnt lgkmcnt(0)
; __device__ __forceinline__ u32x4 pack8f(f32x4 a, f32x4 b) { u32x4 w; w.x = cvt_pk_bf16(a[0], a[1]); w.y = cvt_pk_bf16(a[2], a[3]); w.z = cvt_pk_bf16(b[0], b[1]); w.w = cvt_pk_bf16(b[2], b[3]); return w; }
;     __device__ __forceinline__ void operator()(const f32x4 (&acc)[2][2][4][2], const Unit& u, int wr, int wc, int fr, int fq, const EpiCtx& X) const {
;     ...
;             for (int m = 0; m < 4; ++m) {
;                 const int rl = ai * HALF + m * 16; const unsigned off = lo + (unsigned)(rl * 64) * 2u;
;                 const f32x4 o0a = acc[ai][0][m][0], o0b = acc[ai][0][m][1], o1a = acc[ai][1][m][0], o1b = acc[ai][1][m][1];
;                 const f32x4 ra_ = dpp_swap1(odd ? o0a : o1a), rb_ = dpp_swap1(odd ? o0b : o1b);
;                 const f32x4 pa[2] = {odd ? ra_ : o0a, odd ? o1a : ra_}, pb[2] = {odd ? rb_ : o0b, odd ? o1b : rb_};
; #pragma unroll
;                 for (int q = 0; q < 2; ++q) {
;                     const u32x4 w0 = raw[2 * m + q];
;                     const f32x4 r0 = (f32x4){bf_lo(w0.x), bf_hi(w0.x), bf_lo(w0.y), bf_hi(w0.y)}, r1 = (f32x4){bf_lo(w0.z), bf_hi(w0.z), bf_lo(w0.w), bf_hi(w0.w)};
;                     f32x4 y0, y1;
;                     if (RESN) { const f32x2 t = tbl[rl + q]; const float mu = t.x, ra = t.y * ALPHA; y0 = (r0 - mu) * ra * g0 + b0 + pa[q]; y1 = (r1 - mu) * ra * g1 + b1 + pb[q]; }
;                     else { y0 = r0 * ALPHA + pa[q]; y1 = r1 * ALPHA + pb[q]; }
;                     { const u32x4 w = pack8f(y0, y1); *(u32x4*)(xb + off + q * 128) = w;
;                         y0 = (f32x4){bf_lo(w.x), bf_hi(w.x), bf_lo(w.y), bf_hi(w.y)}; y1 = (f32x4){bf_lo(w.z), bf_hi(w.z), bf_lo(w.w), bf_hi(w.w)}; }
;                     float sa = ((y0[0] + y0[1]) + (y0[2] + y0[3])) + ((y1[0] + y1[1]) + (y1[2] + y1[3]));
;                     float sb = ((y0[0] * y0[0] + y0[1] * y0[1]) + (y0[2] * y0[2] + y0[3] * y0[3])) + ((y1[0] * y1[0] + y1[1] * y1[1]) + (y1[2] * y1[2] + y1[3] * y1[3]));
;                     sa += dpp_x1(sa);
;                     sb += dpp_x1(sb);
;                     sa += __shfl_xor(sa, 16); sa += __shfl_xor(sa, 32); sb += __shfl_xor(sb, 16); sb += __shfl_xor(sb, 32);
;                     if (fq == 0 && !odd) ps[(size_t)(rl + q) * 64] = (f32x2){sa, sb};
	v_mul_f32_e32 v98, 0x3fb504f3, v97
	v_sub_f32_e32 v101, v100, v96
	v_sub_f32_e32 v100, v99, v96
	v_pk_mul_f32 v[100:101], v[100:101], v[98:99] op_sel_hi:[1,0]
	v_sub_f32_e32 v103, v103, v96
	v_pk_fma_f32 v[100:101], v[76:77], v[100:101], v[184:185]
	v_sub_f32_e32 v102, v102, v96
	v_pk_add_f32 v[84:85], v[84:85], v[100:101]
	v_sub_f32_e32 v101, v105, v96
	v_sub_f32_e32 v100, v104, v96
	v_sub_f32_e32 v97, v107, v96
	v_sub_f32_e32 v96, v106, v96
	v_pk_mul_f32 v[102:103], v[102:103], v[98:99] op_sel_hi:[1,0]
	v_pk_mul_f32 v[96:97], v[96:97], v[98:99] op_sel_hi:[1,0]
	v_pk_mul_f32 v[98:99], v[100:101], v[98:99] op_sel_hi:[1,0]
	v_cndmask_b32_e64 v80, v92, v80, s[10:11]
	v_cndmask_b32_e64 v83, v95, v83, s[10:11]
	v_cndmask_b32_e64 v82, v93, v82, s[10:11]
	v_pk_fma_f32 v[102:103], v[78:79], v[102:103], v[182:183]
	v_pk_fma_f32 v[98:99], v[72:73], v[98:99], v[180:181]
	v_pk_fma_f32 v[96:97], v[74:75], v[96:97], v[178:179]
	v_pk_add_f32 v[86:87], v[86:87], v[102:103]
	v_pk_add_f32 v[82:83], v[82:83], v[96:97]
	v_pk_add_f32 v[80:81], v[80:81], v[98:99]
	v_cvt_pk_bf16_f32 v96, v84, v85
	v_cvt_pk_bf16_f32 v97, v86, v87
	v_mov_b32_e32 v189, v165
	v_cvt_pk_bf16_f32 v98, v80, v81
	v_cvt_pk_bf16_f32 v99, v82, v83
	v_lshlrev_b32_e32 v80, 16, v96
	v_and_b32_e32 v82, 0xffff0000, v96
	v_lshlrev_b32_e32 v84, 16, v97
	v_and_b32_e32 v86, 0xffff0000, v97
	v_lshlrev_b32_e32 v100, 16, v98
	v_and_b32_e32 v102, 0xffff0000, v98
	v_lshlrev_b32_e32 v104, 16, v99
	v_and_b32_e32 v106, 0xffff0000, v99
	v_mul_f32_e32 v81, v80, v80
	v_mul_f32_e32 v83, v82, v82
	v_mul_f32_e32 v85, v84, v84
	v_mul_f32_e32 v87, v86, v86
	v_mul_f32_e32 v101, v100, v100
	v_mul_f32_e32 v103, v102, v102
	v_mul_f32_e32 v105, v104, v104
	v_mul_f32_e32 v107, v106, v106
	v_pk_add_f32 v[80:81], v[80:81], v[82:83]
	v_pk_add_f32 v[82:83], v[84:85], v[86:87]
	v_pk_add_f32 v[84:85], v[104:105], v[106:107]
	v_pk_add_f32 v[80:81], v[80:81], v[82:83]
	v_pk_add_f32 v[82:83], v[100:101], v[102:103]
	s_nop 0
	v_pk_add_f32 v[82:83], v[82:83], v[84:85]
	s_nop 0
	v_pk_add_f32 v[80:81], v[80:81], v[82:83]
	v_mov_b32_e32 v82, v165
	v_mov_b32_e32 v83, v165
	s_nop 0
	v_mov_b32_dpp v82, v80 quad_perm:[1,0,3,2] row_mask:0xf bank_mask:0xf
	v_mov_b32_dpp v83, v81 quad_perm:[1,0,3,2] row_mask:0xf bank_mask:0xf
	v_pk_add_f32 v[80:81], v[80:81], v[82:83]
	ds_bpermute_b32 v82, v207, v80
	ds_bpermute_b32 v83, v207, v81
	s_waitcnt lgkmcnt(0)
	v_pk_add_f32 v[82:83], v[80:81], v[82:83]
	ds_bpermute_b32 v84, v208, v82
	ds_bpermute_b32 v85, v208, v83
	v_lshl_add_u64 v[80:81], s[20:21], 0, v[188:189]
	global_store_dwordx4 v[80:81], v[96:99], off
	s_and_saveexec_b64 s[68:69], s[16:17]
	s_waitcnt lgkmcnt(0)
	v_pk_add_f32 v[82:83], v[82:83], v[84:85]
	v_add_co_u32_e32 v84, vcc, 0x6000, v186
	s_nop 1
	v_addc_co_u32_e32 v85, vcc, 0, v187, vcc
	global_store_dwordx2 v[84:85], v[82:83], off
.LBB0_830:
	s_or_b64 exec, exec, s[68:69]
	ds_read_b64 v[82:83], v201 offset:392
	s_waitcnt lgkmcnt(1)
	s_waitcnt vmcnt(18)
	v_lshlrev_b32_e32 v85, 16, v128
	v_and_b32_e32 v86, 0xffff0000, v128
	v_cndmask_b32_e64 v69, v69, v90, s[10:11]
	v_cndmask_b32_e64 v68, v68, v88, s[10:11]
	s_waitcnt lgkmcnt(0)
	v_mul_f32_e32 v84, 0x3fb504f3, v83
	v_sub_f32_e32 v87, v86, v82
	v_sub_f32_e32 v86, v85, v82
	v_pk_mul_f32 v[86:87], v[86:87], v[84:85] op_sel_hi:[1,0]
	v_cndmask_b32_e64 v71, v71, v91, s[10:11]
	v_cndmask_b32_e64 v70, v70, v89, s[10:11]
	v_cndmask_b32_e64 v64, v64, v92, s[10:11]
	v_cndmask_b32_e64 v66, v66, v93, s[10:11]
	v_lshlrev_b32_e32 v88, 16, v129
	v_and_b32_e32 v89, 0xffff0000, v129
	v_lshlrev_b32_e32 v90, 16, v130
	v_and_b32_e32 v91, 0xffff0000, v130
	v_lshlrev_b32_e32 v92, 16, v131
	v_and_b32_e32 v93, 0xffff0000, v131
	v_pk_fma_f32 v[86:87], v[76:77], v[86:87], v[184:185]
	v_sub_f32_e32 v89, v89, v82
	v_sub_f32_e32 v88, v88, v82
	v_pk_add_f32 v[68:69], v[68:69], v[86:87]
	v_sub_f32_e32 v87, v91, v82
	v_sub_f32_e32 v86, v90, v82
	v_sub_f32_e32 v83, v93, v82
	v_sub_f32_e32 v82, v92, v82
	v_pk_mul_f32 v[88:89], v[88:89], v[84:85] op_sel_hi:[1,0]
	v_pk_mul_f32 v[82:83], v[82:83], v[84:85] op_sel_hi:[1,0]
	v_pk_mul_f32 v[84:85], v[86:87], v[84:85] op_sel_hi:[1,0]
	v_cndmask_b32_e64 v65, v65, v94, s[10:11]
	v_cndmask_b32_e64 v67, v67, v95, s[10:11]
	v_pk_fma_f32 v[88:89], v[78:79], v[88:89], v[182:183]
	v_pk_fma_f32 v[84:85], v[72:73], v[84:85], v[180:181]
	v_pk_fma_f32 v[82:83], v[74:75], v[82:83], v[178:179]
	v_pk_add_f32 v[70:71], v[70:71], v[88:89]
	v_pk_add_f32 v[66:67], v[66:67], v[82:83]
	v_pk_add_f32 v[64:65], v[64:65], v[84:85]
	v_cvt_pk_bf16_f32 v68, v68, v69
	v_cvt_pk_bf16_f32 v69, v70, v71
	s_nop 0
	v_cvt_pk_bf16_f32 v70, v64, v65
	v_cvt_pk_bf16_f32 v71, v66, v67
	v_lshlrev_b32_e32 v64, 16, v68
	v_and_b32_e32 v66, 0xffff0000, v68
	v_lshlrev_b32_e32 v82, 16, v69
	v_and_b32_e32 v84, 0xffff0000, v69
	v_lshlrev_b32_e32 v86, 16, v70
	v_and_b32_e32 v88, 0xffff0000, v70
	v_lshlrev_b32_e32 v90, 16, v71
	v_and_b32_e32 v92, 0xffff0000, v71
	v_mul_f32_e32 v65, v64, v64
	v_mul_f32_e32 v67, v66, v66
	v_mul_f32_e32 v83, v82, v82
	v_mul_f32_e32 v85, v84, v84
	v_mul_f32_e32 v87, v86, v86
	v_mul_f32_e32 v89, v88, v88
	v_mul_f32_e32 v91, v90, v90
	v_mul_f32_e32 v93, v92, v92
	v_pk_add_f32 v[64:65], v[64:65], v[66:67]
	v_pk_add_f32 v[66:67], v[82:83], v[84:85]
	v_pk_add_f32 v[82:83], v[90:91], v[92:93]
	v_pk_add_f32 v[64:65], v[64:65], v[66:67]
	v_pk_add_f32 v[66:67], v[86:87], v[88:89]
	global_store_dwordx4 v[80:81], v[68:71], off offset:128
	v_pk_add_f32 v[66:67], v[66:67], v[82:83]
	s_nop 0
	v_pk_add_f32 v[64:65], v[64:65], v[66:67]
	v_mov_b32_e32 v66, v165
	v_mov_b32_e32 v67, v165
	s_nop 0
	v_mov_b32_dpp v66, v64 quad_perm:[1,0,3,2] row_mask:0xf bank_mask:0xf
	v_mov_b32_dpp v67, v65 quad_perm:[1,0,3,2] row_mask:0xf bank_mask:0xf
	v_pk_add_f32 v[64:65], v[64:65], v[66:67]
	ds_bpermute_b32 v66, v207, v64
	ds_bpermute_b32 v67, v207, v65
	s_waitcnt lgkmcnt(0)
	v_pk_add_f32 v[64:65], v[64:65], v[66:67]
	ds_bpermute_b32 v66, v208, v64
	ds_bpermute_b32 v67, v208, v65
	s_and_saveexec_b64 s[68:69], s[16:17]
	s_waitcnt lgkmcnt(0)
	v_pk_add_f32 v[64:65], v[64:65], v[66:67]
	v_add_co_u32_e32 v66, vcc, 0x6000, v186
	s_nop 1
	v_addc_co_u32_e32 v67, vcc, 0, v187, vcc
	global_store_dwordx2 v[66:67], v[64:65], off offset:512
;     __device__ __forceinline__ void operator()(const f32x4 (&acc)[2][2][4][2], const Unit& u, int wr, int wc, int fr, int fq, const EpiCtx& X) const {
;     ...
;         for (int ai = 0; ai < 2; ++ai) {
;             u32x4 raw[8];
; #pragma unroll
;             for (int m = 0; m < 4; ++m) { const unsigned off = lo + (unsigned)((ai * HALF + m * 16) * 64) * 2u; raw[2 * m] = *(const u32x4*)(xb + off); raw[2 * m + 1] = *(const u32x4*)(xb + off + 128); }
; #pragma unroll
;             for (int m = 0; m < 4; ++m) {
;                 const int rl = ai * HALF + m * 16; const unsigned off = lo + (unsigned)(rl * 64) * 2u;
;                 const f32x4 o0a = acc[ai][0][m][0], o0b = acc[ai][0][m][1], o1a = acc[ai][1][m][0], o1b = acc[ai][1][m][1];
;                 const f32x4 ra_ = dpp_swap1(odd ? o0a : o1a), rb_ = dpp_swap1(odd ? o0b : o1b);
;                 const f32x4 pa[2] = {odd ? ra_ : o0a, odd ? o1a : ra_}, pb[2] = {odd ? rb_ : o0b, odd ? o1b : rb_};
; #pragma unroll
;                 for (int q = 0; q < 2; ++q) {
;                     const u32x4 w0 = raw[2 * m + q];
;                     const f32x4 r0 = (f32x4){bf_lo(w0.x), bf_hi(w0.x), bf_lo(w0.y), bf_hi(w0.y)}, r1 = (f32x4){bf_lo(w0.z), bf_hi(w0.z), bf_lo(w0.w), bf_hi(w0.w)};
;                     f32x4 y0, y1;
;                     if (RESN) { const f32x2 t = tbl[rl + q]; const float mu = t.x, ra = t.y * ALPHA; y0 = (r0 - mu) * ra * g0 + b0 + pa[q]; y1 = (r1 - mu) * ra * g1 + b1 + pb[q]; }
;                     else { y0 = r0 * ALPHA + pa[q]; y1 = r1 * ALPHA + pb[q]; }
;                     { const u32x4 w = pack8f(y0, y1); *(u32x4*)(xb + off + q * 128) = w;
;                         y0 = (f32x4){bf_lo(w.x), bf_hi(w.x), bf_lo(w.y), bf_hi(w.y)}; y1 = (f32x4){bf_lo(w.z), bf_hi(w.z), bf_lo(w.w), bf_hi(w.w)}; }
;                     float sa = ((y0[0] + y0[1]) + (y0[2] + y0[3])) + ((y1[0] + y1[1]) + (y1[2] + y1[3]));
;                     float sb = ((y0[0] * y0[0] + y0[1] * y0[1]) + (y0[2] * y0[2] + y0[3] * y0[3])) + ((y1[0] * y1[0] + y1[1] * y1[1]) + (y1[2] * y1[2] + y1[3] * y1[3]));
;                     sa += dpp_x1(sa);
;                     sb += dpp_x1(sb);
;                     sa += __shfl_xor(sa, 16); sa += __shfl_xor(sa, 32); sb += __shfl_xor(sb, 16); sb += __shfl_xor(sb, 32);
;                     if (fq == 0 && !odd) ps[(size_t)(rl + q) * 64] = (f32x2){sa, sb};
.LBB0_832:
	s_or_b64 exec, exec, s[68:69]
	v_add_u32_e32 v104, 0x4000, v164
	s_waitcnt vmcnt(16)
	v_mov_b32_e32 v112, v230
	v_mov_b32_e32 v113, v231
	v_mov_b32_e32 v114, v232
	v_mov_b32_e32 v115, v233
	v_add_u32_e32 v102, 0x4800, v164
	v_add_u32_e32 v100, 0x5000, v164
	v_add_u32_e32 v164, 0x5800, v164
	v_mov_b32_e32 v96, v234
	v_mov_b32_e32 v97, v235
	v_mov_b32_e32 v98, v236
	v_mov_b32_e32 v99, v237
	v_mov_b32_e32 v92, v238
	v_mov_b32_e32 v93, v239
	v_mov_b32_e32 v94, v240
	v_mov_b32_e32 v95, v241
	v_mov_b32_e32 v88, v242
	v_mov_b32_e32 v89, v243
	v_mov_b32_e32 v90, v244
	v_mov_b32_e32 v91, v245
	global_load_dwordx4 v[84:87], v100, s[20:21]
	global_load_dwordx4 v[80:83], v100, s[20:21] offset:128
	global_load_dwordx4 v[68:71], v164, s[20:21]
	s_waitcnt lgkmcnt(0)
	global_load_dwordx4 v[64:67], v164, s[20:21] offset:128
	v_cndmask_b32_e64 v116, v62, v54, s[10:11]
	v_cndmask_b32_e64 v117, v61, v53, s[10:11]
	v_mov_b32_e32 v105, 0
	v_mov_b32_e32 v103, 0
	v_cndmask_b32_e64 v111, v63, v55, s[10:11]
	v_mov_b32_dpp v105, v117 quad_perm:[1,0,3,2] row_mask:0xf bank_mask:0xf
	v_mov_b32_dpp v103, v116 quad_perm:[1,0,3,2] row_mask:0xf bank_mask:0xf
	ds_read_b64 v[116:117], v201 offset:1024
	v_cndmask_b32_e64 v118, v60, v52, s[10:11]
	v_mov_b32_e32 v101, 0
	v_mov_b32_e32 v106, 0
	v_cndmask_b32_e64 v119, v59, v51, s[10:11]
	v_cndmask_b32_e64 v120, v58, v50, s[10:11]
	v_cndmask_b32_e64 v121, v57, v49, s[10:11]
	v_cndmask_b32_e64 v122, v56, v48, s[10:11]
	v_mov_b32_e32 v107, 0
	v_mov_b32_e32 v109, 0
	v_mov_b32_e32 v108, 0
	v_mov_b32_e32 v110, 0
	v_mov_b32_dpp v101, v118 quad_perm:[1,0,3,2] row_mask:0xf bank_mask:0xf
	v_mov_b32_dpp v106, v111 quad_perm:[1,0,3,2] row_mask:0xf bank_mask:0xf
	v_mov_b32_dpp v107, v122 quad_perm:[1,0,3,2] row_mask:0xf bank_mask:0xf
	v_mov_b32_dpp v109, v121 quad_perm:[1,0,3,2] row_mask:0xf bank_mask:0xf
	v_mov_b32_dpp v108, v120 quad_perm:[1,0,3,2] row_mask:0xf bank_mask:0xf
	v_mov_b32_dpp v110, v119 quad_perm:[1,0,3,2] row_mask:0xf bank_mask:0xf
	s_waitcnt lgkmcnt(0)
	v_mul_f32_e32 v118, 0x3fb504f3, v117
	v_cndmask_b32_e64 v61, v105, v61, s[10:11]
	v_cndmask_b32_e64 v60, v101, v60, s[10:11]
	v_cndmask_b32_e64 v63, v106, v63, s[10:11]
	v_cndmask_b32_e64 v62, v103, v62, s[10:11]
	v_cndmask_b32_e64 v57, v109, v57, s[10:11]
	v_cndmask_b32_e64 v56, v107, v56, s[10:11]
	v_cndmask_b32_e64 v59, v110, v59, s[10:11]
	v_cndmask_b32_e64 v58, v108, v58, s[10:11]
	v_lshlrev_b32_e32 v111, 16, v112
	v_and_b32_e32 v112, 0xffff0000, v112
	v_lshlrev_b32_e32 v117, 16, v113
	v_and_b32_e32 v119, 0xffff0000, v113
	v_lshlrev_b32_e32 v120, 16, v114
	v_and_b32_e32 v121, 0xffff0000, v114
	v_lshlrev_b32_e32 v122, 16, v115
	v_and_b32_e32 v123, 0xffff0000, v115
	v_sub_f32_e32 v113, v112, v116
	v_sub_f32_e32 v112, v111, v116
	v_sub_f32_e32 v115, v119, v116
	v_sub_f32_e32 v114, v117, v116
	v_sub_f32_e32 v121, v121, v116
	v_sub_f32_e32 v120, v120, v116
	v_sub_f32_e32 v117, v123, v116
	v_sub_f32_e32 v116, v122, v116
	v_pk_mul_f32 v[114:115], v[114:115], v[118:119] op_sel_hi:[1,0]
	v_pk_mul_f32 v[112:113], v[112:113], v[118:119] op_sel_hi:[1,0]
	v_pk_mul_f32 v[116:117], v[116:117], v[118:119] op_sel_hi:[1,0]
	v_pk_mul_f32 v[118:119], v[120:121], v[118:119] op_sel_hi:[1,0]
	v_pk_fma_f32 v[112:113], v[76:77], v[112:113], v[184:185]
	v_pk_fma_f32 v[114:115], v[78:79], v[114:115], v[182:183]
	v_pk_fma_f32 v[118:119], v[72:73], v[118:119], v[180:181]
	v_pk_fma_f32 v[116:117], v[74:75], v[116:117], v[178:179]
	v_pk_add_f32 v[62:63], v[62:63], v[114:115]
	v_pk_add_f32 v[60:61], v[60:61], v[112:113]
	v_pk_add_f32 v[58:59], v[58:59], v[116:117]
	v_pk_add_f32 v[56:57], v[56:57], v[118:119]
	v_cvt_pk_bf16_f32 v60, v60, v61
	v_cvt_pk_bf16_f32 v61, v62, v63
	s_nop 0
	v_cvt_pk_bf16_f32 v62, v56, v57
	v_cvt_pk_bf16_f32 v63, v58, v59
	v_lshlrev_b32_e32 v56, 16, v60
	v_and_b32_e32 v58, 0xffff0000, v60
	v_lshlrev_b32_e32 v112, 16, v61
	v_and_b32_e32 v114, 0xffff0000, v61
	v_lshlrev_b32_e32 v116, 16, v62
	v_and_b32_e32 v118, 0xffff0000, v62
	v_lshlrev_b32_e32 v120, 16, v63
	v_and_b32_e32 v122, 0xffff0000, v63
	v_mul_f32_e32 v57, v56, v56
	v_mul_f32_e32 v59, v58, v58
	v_mul_f32_e32 v113, v112, v112
	v_mul_f32_e32 v115, v114, v114
	v_mul_f32_e32 v117, v116, v116
	v_mul_f32_e32 v119, v118, v118
	v_mul_f32_e32 v121, v120, v120
	v_mul_f32_e32 v123, v122, v122
	v_pk_add_f32 v[56:57], v[56:57], v[58:59]
	v_pk_add_f32 v[58:59], v[112:113], v[114:115]
	v_pk_add_f32 v[112:113], v[120:121], v[122:123]
	v_pk_add_f32 v[56:57], v[56:57], v[58:59]
	v_pk_add_f32 v[58:59], v[116:117], v[118:119]
	global_store_dwordx4 v104, v[60:63], s[20:21]
	v_pk_add_f32 v[58:59], v[58:59], v[112:113]
	s_nop 0
	v_pk_add_f32 v[56:57], v[56:57], v[58:59]
	v_mov_b32_e32 v58, v165
	v_mov_b32_e32 v59, v165
	s_nop 0
	v_mov_b32_dpp v58, v56 quad_perm:[1,0,3,2] row_mask:0xf bank_mask:0xf
	v_mov_b32_dpp v59, v57 quad_perm:[1,0,3,2] row_mask:0xf bank_mask:0xf
	v_pk_add_f32 v[56:57], v[56:57], v[58:59]
	ds_bpermute_b32 v58, v207, v56
	ds_bpermute_b32 v59, v207, v57
	s_waitcnt lgkmcnt(0)
	v_pk_add_f32 v[56:57], v[56:57], v[58:59]
	ds_bpermute_b32 v58, v208, v56
	ds_bpermute_b32 v59, v208, v57
	s_and_saveexec_b64 s[68:69], s[16:17]
	s_cbranch_execz .LBB0_834
	s_waitcnt lgkmcnt(0)
	v_pk_add_f32 v[56:57], v[56:57], v[58:59]
	v_add_co_u32_e32 v58, vcc, 0x10000, v186
	s_nop 1
	v_addc_co_u32_e32 v59, vcc, 0, v187, vcc
	global_store_dwordx2 v[58:59], v[56:57], off

; #define LAS __attribute__((address_space(3)))
;     __device__ __forceinline__ void operator()(const f32x4 (&acc)[2][2][4][2], const Unit& u, int wr, int wc, int fr, int fq, const EpiCtx& X) const {
;     ...
;         char* yb = nullptr; char* xb = (char*)(XB + (size_t)u.pm * BM * DM + (size_t)(u.pn * 4 + wc) * (BM * 64));
;         unsigned lo = (unsigned)((wr * 64 + fe) * 64 + o32 + 8 * fq) * 2u; EPI_OPAQUE(lo);
;         const int col = u.pn * BM + wc * 64 + o32 + 8 * fq;
;         f32x4 g0, g1, b0, b1;
;         if (RESN) { ensure_tbl(PSp, sidp, u.pm, X);
;             g0 = *(const f32x4*)(gp + col); g1 = *(const f32x4*)(gp + col + 4); b0 = *(const f32x4*)(bp + col) * ALPHA; b1 = *(const f32x4*)(bp + col + 4) * ALPHA; }
;         const LAS f32x2* tbl = (const LAS f32x2*)(X.lds + TBL_OFF) + wr * 64 + fe;
;         f32x2* ps = PSn + ((size_t)u.pm * BM + wr * 64 + fe) * 64 + u.pn * 4 + wc;
; #pragma unroll
;         for (int ai = 0; ai < 2; ++ai) {
;             u32x4 raw[8];
; #pragma unroll
;             for (int m = 0; m < 4; ++m) { const unsigned off = lo + (unsigned)((ai * HALF + m * 16) * 64) * 2u; raw[2 * m] = *(const u32x4*)(xb + off); raw[2 * m + 1] = *(const u32x4*)(xb + off + 128); }
; #pragma unroll
;             for (int m = 0; m < 4; ++m) {
;                 const int rl = ai * HALF + m * 16; const unsigned off = lo + (unsigned)(rl * 64) * 2u;
;                 const f32x4 o0a = acc[ai][0][m][0], o0b = acc[ai][0][m][1], o1a = acc[ai][1][m][0], o1b = acc[ai][1][m][1];
;                 const f32x4 ra_ = dpp_swap1(odd ? o0a : o1a), rb_ = dpp_swap1(odd ? o0b : o1b);
;                 const f32x4 pa[2] = {odd ? ra_ : o0a, odd ? o1a : ra_}, pb[2] = {odd ? rb_ : o0b, odd ? o1b : rb_};
; #pragma unroll
;                 for (int q = 0; q < 2; ++q) {
;                     const u32x4 w0 = raw[2 * m + q];
;                     const f32x4 r0 = (f32x4){bf_lo(w0.x), bf_hi(w0.x), bf_lo(w0.y), bf_hi(w0.y)}, r1 = (f32x4){bf_lo(w0.z), bf_hi(w0.z), bf_lo(w0.w), bf_hi(w0.w)};
;                     f32x4 y0, y1;
;                     if (RESN) { const f32x2 t = tbl[rl + q]; const float mu = t.x, ra = t.y * ALPHA; y0 = (r0 - mu) * ra * g0 + b0 + pa[q]; y1 = (r1 - mu) * ra * g1 + b1 + pb[q]; }
;                     else { y0 = r0 * ALPHA + pa[q]; y1 = r1 * ALPHA + pb[q]; }
;                     { const u32x4 w = pack8f(y0, y1); *(u32x4*)(xb + off + q * 128) = w;
.LBB0_1463:
	s_lshl_b64 s[4:5], s[66:67], 21
	s_add_u32 s20, s51, s4
	s_addc_u32 s21, s53, s5
	s_lshl_b32 s66, s64, 2
	s_or_b32 s4, s66, s41
	s_ashr_i32 s5, s4, 31
	v_lshl_add_u32 v72, s64, 8, v200
	v_ashrrev_i32_e32 v73, 31, v72
	s_lshl_b64 s[4:5], s[4:5], 15
	v_lshlrev_b64 v[72:73], 2, v[72:73]
	s_add_u32 s20, s20, s4
	v_lshl_add_u64 v[74:75], s[26:27], 0, v[72:73]
	s_addc_u32 s21, s21, s5
	global_load_dwordx4 v[194:197], v[74:75], off offset:16
	global_load_dwordx4 v[178:181], v[74:75], off
	global_load_dwordx4 v[214:217], v164, s[20:21]
	v_lshl_add_u64 v[72:73], s[24:25], 0, v[72:73]
	s_waitcnt lgkmcnt(0)
	global_load_dwordx4 v[76:79], v[72:73], off
	s_nop 0
	global_load_dwordx4 v[72:75], v[72:73], off offset:16
	v_cndmask_b32_e64 v136, v135, v127, s[10:11]
	v_cndmask_b32_e64 v137, v134, v126, s[10:11]
	v_cndmask_b32_e64 v138, v133, v125, s[10:11]
	v_cndmask_b32_e64 v139, v132, v124, s[10:11]
	v_mov_b32_e32 v189, 0
	v_mov_b32_e32 v193, 0
	v_mov_b32_e32 v191, 0
	v_mov_b32_e32 v209, 0
	v_cndmask_b32_e64 v140, v131, v123, s[10:11]
	v_cndmask_b32_e64 v141, v130, v122, s[10:11]
	v_cndmask_b32_e64 v142, v129, v121, s[10:11]
	v_cndmask_b32_e64 v143, v128, v120, s[10:11]
	v_mov_b32_e32 v210, 0
	v_mov_b32_e32 v212, 0
	v_mov_b32_e32 v211, 0
	v_mov_b32_e32 v213, 0
	v_mov_b32_dpp v189, v139 quad_perm:[1,0,3,2] row_mask:0xf bank_mask:0xf
	v_mov_b32_dpp v193, v138 quad_perm:[1,0,3,2] row_mask:0xf bank_mask:0xf
	v_mov_b32_dpp v191, v137 quad_perm:[1,0,3,2] row_mask:0xf bank_mask:0xf
	v_mov_b32_dpp v209, v136 quad_perm:[1,0,3,2] row_mask:0xf bank_mask:0xf
	v_mov_b32_dpp v210, v143 quad_perm:[1,0,3,2] row_mask:0xf bank_mask:0xf
	v_mov_b32_dpp v212, v142 quad_perm:[1,0,3,2] row_mask:0xf bank_mask:0xf
	v_mov_b32_dpp v211, v141 quad_perm:[1,0,3,2] row_mask:0xf bank_mask:0xf
	v_mov_b32_dpp v213, v140 quad_perm:[1,0,3,2] row_mask:0xf bank_mask:0xf
	v_add_u32_e32 v192, 0x800, v164
	v_add_u32_e32 v190, 0x1000, v164
	v_add_u32_e32 v188, 0x1800, v164
	ds_read_b64 v[218:219], v201
	v_cndmask_b32_e64 v221, v193, v133, s[10:11]
	v_cndmask_b32_e64 v220, v189, v132, s[10:11]
	v_cndmask_b32_e64 v223, v209, v135, s[10:11]
	v_cndmask_b32_e64 v222, v191, v134, s[10:11]
	v_cndmask_b32_e64 v225, v212, v129, s[10:11]
	v_cndmask_b32_e64 v224, v210, v128, s[10:11]
	v_cndmask_b32_e64 v227, v213, v131, s[10:11]
	v_cndmask_b32_e64 v226, v211, v130, s[10:11]
	global_load_dwordx4 v[152:155], v164, s[20:21] offset:128
	global_load_dwordx4 v[148:151], v192, s[20:21]
	global_load_dwordx4 v[144:147], v192, s[20:21] offset:128
	global_load_dwordx4 v[140:143], v190, s[20:21]
	global_load_dwordx4 v[136:139], v190, s[20:21] offset:128
	global_load_dwordx4 v[132:135], v188, s[20:21]
	global_load_dwordx4 v[128:131], v188, s[20:21] offset:128
	s_waitcnt lgkmcnt(0)
	v_mul_f32_e32 v208, 0x3fb504f3, v219
	v_lshl_add_u64 v[186:187], v[166:167], 0, s[68:69]
	s_ashr_i32 s67, s66, 31
	v_lshl_add_u64 v[186:187], s[66:67], 3, v[186:187]
	v_lshl_add_u64 v[186:187], v[186:187], 0, s[22:23]
	v_add_u32_e32 v246, 0x4000, v164
	v_add_u32_e32 v247, 0x4800, v164
	global_load_dwordx4 v[230:233], v246, s[20:21]
	global_load_dwordx4 v[234:237], v246, s[20:21] offset:128
	global_load_dwordx4 v[238:241], v247, s[20:21]
	global_load_dwordx4 v[242:245], v247, s[20:21] offset:128
	s_waitcnt vmcnt(14)
	v_pk_mul_f32 v[182:183], v[180:181], s[52:53] op_sel_hi:[1,0]
	v_pk_mul_f32 v[184:185], v[178:179], s[52:53] op_sel_hi:[1,0]
	v_pk_mul_f32 v[178:179], v[196:197], s[52:53] op_sel_hi:[1,0]
	v_pk_mul_f32 v[180:181], v[194:195], s[52:53] op_sel_hi:[1,0]
	s_waitcnt vmcnt(13)
	v_lshlrev_b32_e32 v194, 16, v214
	v_and_b32_e32 v195, 0xffff0000, v214
	v_lshlrev_b32_e32 v196, 16, v215
	v_and_b32_e32 v197, 0xffff0000, v215
	v_lshlrev_b32_e32 v207, 16, v216
	v_and_b32_e32 v214, 0xffff0000, v216
	v_lshlrev_b32_e32 v216, 16, v217
	v_and_b32_e32 v217, 0xffff0000, v217
	v_sub_f32_e32 v195, v195, v218
	v_sub_f32_e32 v194, v194, v218
	v_sub_f32_e32 v197, v197, v218
	v_sub_f32_e32 v196, v196, v218
	v_sub_f32_e32 v215, v214, v218
	v_sub_f32_e32 v214, v207, v218
	v_sub_f32_e32 v217, v217, v218
	v_sub_f32_e32 v216, v216, v218
	v_pk_mul_f32 v[196:197], v[196:197], v[208:209] op_sel_hi:[1,0]
	v_pk_mul_f32 v[194:195], v[194:195], v[208:209] op_sel_hi:[1,0]
	v_pk_mul_f32 v[216:217], v[216:217], v[208:209] op_sel_hi:[1,0]
	v_pk_mul_f32 v[214:215], v[214:215], v[208:209] op_sel_hi:[1,0]
	s_waitcnt vmcnt(12)
	v_pk_fma_f32 v[194:195], v[76:77], v[194:195], v[184:185]
	v_pk_fma_f32 v[196:197], v[78:79], v[196:197], v[182:183]
	s_waitcnt vmcnt(11)
	v_pk_fma_f32 v[214:215], v[72:73], v[214:215], v[180:181]
	v_pk_fma_f32 v[216:217], v[74:75], v[216:217], v[178:179]
	v_pk_add_f32 v[196:197], v[222:223], v[196:197]
	v_pk_add_f32 v[194:195], v[220:221], v[194:195]
	v_pk_add_f32 v[218:219], v[226:227], v[216:217]
	v_pk_add_f32 v[216:217], v[224:225], v[214:215]
	v_cvt_pk_bf16_f32 v214, v194, v195
	v_cvt_pk_bf16_f32 v215, v196, v197
	v_and_b32_e32 v208, 64, v206
	v_cvt_pk_bf16_f32 v216, v216, v217
	v_cvt_pk_bf16_f32 v217, v218, v219
	v_lshlrev_b32_e32 v194, 16, v214
	v_and_b32_e32 v196, 0xffff0000, v214
	v_lshlrev_b32_e32 v218, 16, v215
	v_and_b32_e32 v220, 0xffff0000, v215
	v_lshlrev_b32_e32 v222, 16, v216
	v_and_b32_e32 v224, 0xffff0000, v216
	v_lshlrev_b32_e32 v226, 16, v217
	v_and_b32_e32 v228, 0xffff0000, v217
	v_mul_f32_e32 v195, v194, v194
	v_mul_f32_e32 v197, v196, v196
	v_mul_f32_e32 v219, v218, v218
	v_mul_f32_e32 v221, v220, v220
	v_mul_f32_e32 v223, v222, v222
	v_mul_f32_e32 v225, v224, v224
	v_mul_f32_e32 v227, v226, v226
	v_mul_f32_e32 v229, v228, v228
	v_pk_add_f32 v[194:195], v[194:195], v[196:197]
	v_pk_add_f32 v[196:197], v[218:219], v[220:221]
	v_pk_add_f32 v[218:219], v[226:227], v[228:229]
	v_pk_add_f32 v[194:195], v[194:195], v[196:197]
	v_pk_add_f32 v[196:197], v[222:223], v[224:225]
	v_xor_b32_e32 v207, 16, v206
	v_add_u32_e32 v208, 64, v208
	v_pk_add_f32 v[196:197], v[196:197], v[218:219]
	v_cmp_lt_i32_e32 vcc, v207, v208
	v_pk_add_f32 v[194:195], v[194:195], v[196:197]
	v_mov_b32_e32 v196, 0
	v_mov_b32_e32 v197, 0
	v_cndmask_b32_e32 v207, v206, v207, vcc
	v_mov_b32_dpp v196, v194 quad_perm:[1,0,3,2] row_mask:0xf bank_mask:0xf
	v_mov_b32_dpp v197, v195 quad_perm:[1,0,3,2] row_mask:0xf bank_mask:0xf
	v_lshlrev_b32_e32 v207, 2, v207
	v_pk_add_f32 v[194:195], v[194:195], v[196:197]
	ds_bpermute_b32 v196, v207, v194
	ds_bpermute_b32 v197, v207, v195
	v_xor_b32_e32 v218, 32, v206
	v_cmp_lt_i32_e32 vcc, v218, v208
	global_store_dwordx4 v164, v[214:217], s[20:21]
	s_waitcnt lgkmcnt(0)
	v_pk_add_f32 v[194:195], v[194:195], v[196:197]
	v_cndmask_b32_e32 v208, v206, v218, vcc
	v_lshlrev_b32_e32 v208, 2, v208
	ds_bpermute_b32 v196, v208, v194
	ds_bpermute_b32 v197, v208, v195
	s_and_saveexec_b64 s[64:65], s[16:17]
	s_waitcnt lgkmcnt(0)
	v_pk_add_f32 v[194:195], v[194:195], v[196:197]
	global_store_dwordx2 v[186:187], v[194:195], off
; __device__ __forceinline__ u32x4 pack8f(f32x4 a, f32x4 b) { u32x4 w; w.x = cvt_pk_bf16(a[0], a[1]); w.y = cvt_pk_bf16(a[2], a[3]); w.z = cvt_pk_bf16(b[0], b[1]); w.w = cvt_pk_bf16(b[2], b[3]); return w; }
;     __device__ __forceinline__ void operator()(const f32x4 (&acc)[2][2][4][2], const Unit& u, int wr, int wc, int fr, int fq, const EpiCtx& X) const {
;     ...
;             for (int m = 0; m < 4; ++m) {
;                 const int rl = ai * HALF + m * 16; const unsigned off = lo + (unsigned)(rl * 64) * 2u;
;                 const f32x4 o0a = acc[ai][0][m][0], o0b = acc[ai][0][m][1], o1a = acc[ai][1][m][0], o1b = acc[ai][1][m][1];
;                 const f32x4 ra_ = dpp_swap1(odd ? o0a : o1a), rb_ = dpp_swap1(odd ? o0b : o1b);
;                 const f32x4 pa[2] = {odd ? ra_ : o0a, odd ? o1a : ra_}, pb[2] = {odd ? rb_ : o0b, odd ? o1b : rb_};
; #pragma unroll
;                 for (int q = 0; q < 2; ++q) {
;                     const u32x4 w0 = raw[2 * m + q];
;                     const f32x4 r0 = (f32x4){bf_lo(w0.x), bf_hi(w0.x), bf_lo(w0.y), bf_hi(w0.y)}, r1 = (f32x4){bf_lo(w0.z), bf_hi(w0.z), bf_lo(w0.w), bf_hi(w0.w)};
;                     f32x4 y0, y1;
;                     if (RESN) { const f32x2 t = tbl[rl + q]; const float mu = t.x, ra = t.y * ALPHA; y0 = (r0 - mu) * ra * g0 + b0 + pa[q]; y1 = (r1 - mu) * ra * g1 + b1 + pb[q]; }
;                     else { y0 = r0 * ALPHA + pa[q]; y1 = r1 * ALPHA + pb[q]; }
;                     { const u32x4 w = pack8f(y0, y1); *(u32x4*)(xb + off + q * 128) = w;
;                         y0 = (f32x4){bf_lo(w.x), bf_hi(w.x), bf_lo(w.y), bf_hi(w.y)}; y1 = (f32x4){bf_lo(w.z), bf_hi(w.z), bf_lo(w.w), bf_hi(w.w)}; }
;                     float sa = ((y0[0] + y0[1]) + (y0[2] + y0[3])) + ((y1[0] + y1[1]) + (y1[2] + y1[3]));
;                     float sb = ((y0[0] * y0[0] + y0[1] * y0[1]) + (y0[2] * y0[2] + y0[3] * y0[3])) + ((y1[0] * y1[0] + y1[1] * y1[1]) + (y1[2] * y1[2] + y1[3] * y1[3]));
;                     sa += dpp_x1(sa);
;                     sb += dpp_x1(sb);
;                     sa += __shfl_xor(sa, 16); sa += __shfl_xor(sa, 32); sb += __shfl_xor(sb, 16); sb += __shfl_xor(sb, 32);
;                     if (fq == 0 && !odd) ps[(size_t)(rl + q) * 64] = (f32x2){sa, sb};
.LBB0_1465:
	s_or_b64 exec, exec, s[64:65]
	v_cndmask_b32_e64 v125, v125, v193, s[10:11]
	v_cndmask_b32_e64 v124, v124, v189, s[10:11]
	v_cndmask_b32_e64 v126, v126, v191, s[10:11]
	s_waitcnt vmcnt(12)
	v_lshlrev_b32_e32 v189, 16, v152
	v_and_b32_e32 v191, 0xffff0000, v152
	v_lshlrev_b32_e32 v193, 16, v153
	s_waitcnt lgkmcnt(1)
	v_and_b32_e32 v196, 0xffff0000, v153
	ds_read_b64 v[152:153], v201 offset:8
	v_cndmask_b32_e64 v127, v127, v209, s[10:11]
	v_cndmask_b32_e64 v120, v120, v210, s[10:11]
	v_cndmask_b32_e64 v122, v122, v211, s[10:11]
	v_lshlrev_b32_e32 v209, 16, v154
	v_and_b32_e32 v210, 0xffff0000, v154
	v_lshlrev_b32_e32 v211, 16, v155
	v_and_b32_e32 v155, 0xffff0000, v155
	s_waitcnt lgkmcnt(0)
	v_mul_f32_e32 v154, 0x3fb504f3, v153
	v_sub_f32_e32 v195, v191, v152
	v_sub_f32_e32 v194, v189, v152
	v_pk_mul_f32 v[194:195], v[194:195], v[154:155] op_sel_hi:[1,0]
	v_sub_f32_e32 v197, v196, v152
	v_pk_fma_f32 v[194:195], v[76:77], v[194:195], v[184:185]
	v_sub_f32_e32 v196, v193, v152
	v_pk_add_f32 v[124:125], v[124:125], v[194:195]
	v_sub_f32_e32 v195, v210, v152
	v_sub_f32_e32 v194, v209, v152
	v_sub_f32_e32 v153, v155, v152
	v_sub_f32_e32 v152, v211, v152
	v_pk_mul_f32 v[196:197], v[196:197], v[154:155] op_sel_hi:[1,0]
	v_pk_mul_f32 v[152:153], v[152:153], v[154:155] op_sel_hi:[1,0]
	v_pk_mul_f32 v[154:155], v[194:195], v[154:155] op_sel_hi:[1,0]
	v_cndmask_b32_e64 v121, v121, v212, s[10:11]
	v_cndmask_b32_e64 v123, v123, v213, s[10:11]
	v_pk_fma_f32 v[196:197], v[78:79], v[196:197], v[182:183]
	v_pk_fma_f32 v[154:155], v[72:73], v[154:155], v[180:181]
	v_pk_fma_f32 v[152:153], v[74:75], v[152:153], v[178:179]
	v_pk_add_f32 v[126:127], v[126:127], v[196:197]
	v_pk_add_f32 v[122:123], v[122:123], v[152:153]
	v_pk_add_f32 v[120:121], v[120:121], v[154:155]
	v_cvt_pk_bf16_f32 v124, v124, v125
	v_cvt_pk_bf16_f32 v125, v126, v127
	s_nop 0
	v_cvt_pk_bf16_f32 v126, v120, v121
	v_cvt_pk_bf16_f32 v127, v122, v123
	v_lshlrev_b32_e32 v120, 16, v124
	v_and_b32_e32 v122, 0xffff0000, v124
	v_lshlrev_b32_e32 v152, 16, v125
	v_and_b32_e32 v154, 0xffff0000, v125
	v_lshlrev_b32_e32 v194, 16, v126
	v_and_b32_e32 v196, 0xffff0000, v126
	v_lshlrev_b32_e32 v210, 16, v127
	v_and_b32_e32 v212, 0xffff0000, v127
	v_mul_f32_e32 v121, v120, v120
	v_mul_f32_e32 v123, v122, v122
	v_mul_f32_e32 v153, v152, v152
	v_mul_f32_e32 v155, v154, v154
	v_mul_f32_e32 v195, v194, v194
	v_mul_f32_e32 v197, v196, v196
	v_mul_f32_e32 v211, v210, v210
	v_mul_f32_e32 v213, v212, v212
	v_pk_add_f32 v[120:121], v[120:121], v[122:123]
	v_pk_add_f32 v[122:123], v[152:153], v[154:155]
	v_pk_add_f32 v[152:153], v[210:211], v[212:213]
	v_pk_add_f32 v[120:121], v[120:121], v[122:123]
	v_pk_add_f32 v[122:123], v[194:195], v[196:197]
	s_nop 0
	v_pk_add_f32 v[122:123], v[122:123], v[152:153]
	v_lshl_add_u64 v[152:153], s[20:21], 0, v[164:165]
	v_pk_add_f32 v[120:121], v[120:121], v[122:123]
	v_mov_b32_e32 v122, v165
	v_mov_b32_e32 v123, v165
	global_store_dwordx4 v[152:153], v[124:127], off offset:128
	v_mov_b32_dpp v122, v120 quad_perm:[1,0,3,2] row_mask:0xf bank_mask:0xf
	v_mov_b32_dpp v123, v121 quad_perm:[1,0,3,2] row_mask:0xf bank_mask:0xf
	v_pk_add_f32 v[120:121], v[120:121], v[122:123]
	ds_bpermute_b32 v122, v207, v120
	ds_bpermute_b32 v123, v207, v121
	s_waitcnt lgkmcnt(0)
	v_pk_add_f32 v[120:121], v[120:121], v[122:123]
	ds_bpermute_b32 v122, v208, v120
	ds_bpermute_b32 v123, v208, v121
	s_and_saveexec_b64 s[64:65], s[16:17]
	s_waitcnt lgkmcnt(0)
	v_pk_add_f32 v[120:121], v[120:121], v[122:123]
	global_store_dwordx2 v[186:187], v[120:121], off offset:512
.LBB0_1467:
	s_or_b64 exec, exec, s[64:65]
	s_waitcnt lgkmcnt(1)
	v_cndmask_b32_e64 v122, v116, v108, s[10:11]
	v_mov_b32_e32 v120, 0
	v_cndmask_b32_e64 v121, v117, v109, s[10:11]
	s_waitcnt lgkmcnt(0)
	v_cndmask_b32_e64 v123, v118, v110, s[10:11]
	v_mov_b32_dpp v120, v122 quad_perm:[1,0,3,2] row_mask:0xf bank_mask:0xf
	v_mov_b32_e32 v122, 0
	v_cndmask_b32_e64 v124, v119, v111, s[10:11]
	v_cndmask_b32_e64 v126, v112, v104, s[10:11]
	v_mov_b32_dpp v122, v121 quad_perm:[1,0,3,2] row_mask:0xf bank_mask:0xf
	v_mov_b32_e32 v121, 0
	v_cndmask_b32_e64 v125, v113, v105, s[10:11]
	v_cndmask_b32_e64 v127, v114, v106, s[10:11]
	v_mov_b32_dpp v121, v123 quad_perm:[1,0,3,2] row_mask:0xf bank_mask:0xf
	v_mov_b32_e32 v123, 0
	v_cndmask_b32_e64 v152, v115, v107, s[10:11]
	s_waitcnt vmcnt(13)
	v_and_b32_e32 v153, 0xffff0000, v148
	v_mov_b32_dpp v123, v124 quad_perm:[1,0,3,2] row_mask:0xf bank_mask:0xf
	v_mov_b32_e32 v124, 0
	v_lshlrev_b32_e32 v154, 16, v149
	v_and_b32_e32 v155, 0xffff0000, v149
	v_mov_b32_dpp v124, v126 quad_perm:[1,0,3,2] row_mask:0xf bank_mask:0xf
	v_mov_b32_e32 v126, 0
	v_lshlrev_b32_e32 v189, 16, v150
	v_and_b32_e32 v191, 0xffff0000, v150
	v_mov_b32_dpp v126, v125 quad_perm:[1,0,3,2] row_mask:0xf bank_mask:0xf
	v_mov_b32_e32 v125, 0
	v_lshlrev_b32_e32 v193, 16, v151
	v_and_b32_e32 v151, 0xffff0000, v151
	v_mov_b32_dpp v125, v127 quad_perm:[1,0,3,2] row_mask:0xf bank_mask:0xf
	v_mov_b32_e32 v127, 0
	v_cndmask_b32_e64 v117, v122, v117, s[10:11]
	v_cndmask_b32_e64 v116, v120, v116, s[10:11]
	v_mov_b32_dpp v127, v152 quad_perm:[1,0,3,2] row_mask:0xf bank_mask:0xf
	v_lshlrev_b32_e32 v152, 16, v148
	ds_read_b64 v[148:149], v201 offset:128
	v_cndmask_b32_e64 v119, v123, v119, s[10:11]
	v_cndmask_b32_e64 v118, v121, v118, s[10:11]
	v_cndmask_b32_e64 v113, v126, v113, s[10:11]
	v_cndmask_b32_e64 v112, v124, v112, s[10:11]
	s_waitcnt lgkmcnt(0)
; __device__ __forceinline__ u32x4 pack8f(f32x4 a, f32x4 b) { u32x4 w; w.x = cvt_pk_bf16(a[0], a[1]); w.y = cvt_pk_bf16(a[2], a[3]); w.z = cvt_pk_bf16(b[0], b[1]); w.w = cvt_pk_bf16(b[2], b[3]); return w; }
;     __device__ __forceinline__ void operator()(const f32x4 (&acc)[2][2][4][2], const Unit& u, int wr, int wc, int fr, int fq, const EpiCtx& X) const {
;     ...
;             for (int m = 0; m < 4; ++m) {
;                 const int rl = ai * HALF + m * 16; const unsigned off = lo + (unsigned)(rl * 64) * 2u;
;                 const f32x4 o0a = acc[ai][0][m][0], o0b = acc[ai][0][m][1], o1a = acc[ai][1][m][0], o1b = acc[ai][1][m][1];
;                 const f32x4 ra_ = dpp_swap1(odd ? o0a : o1a), rb_ = dpp_swap1(odd ? o0b : o1b);
;                 const f32x4 pa[2] = {odd ? ra_ : o0a, odd ? o1a : ra_}, pb[2] = {odd ? rb_ : o0b, odd ? o1b : rb_};
; #pragma unroll
;                 for (int q = 0; q < 2; ++q) {
;                     const u32x4 w0 = raw[2 * m + q];
;                     const f32x4 r0 = (f32x4){bf_lo(w0.x), bf_hi(w0.x), bf_lo(w0.y), bf_hi(w0.y)}, r1 = (f32x4){bf_lo(w0.z), bf_hi(w0.z), bf_lo(w0.w), bf_hi(w0.w)};
;                     f32x4 y0, y1;
;                     if (RESN) { const f32x2 t = tbl[rl + q]; const float mu = t.x, ra = t.y * ALPHA; y0 = (r0 - mu) * ra * g0 + b0 + pa[q]; y1 = (r1 - mu) * ra * g1 + b1 + pb[q]; }
;                     else { y0 = r0 * ALPHA + pa[q]; y1 = r1 * ALPHA + pb[q]; }
;                     { const u32x4 w = pack8f(y0, y1); *(u32x4*)(xb + off + q * 128) = w;
;                         y0 = (f32x4){bf_lo(w.x), bf_hi(w.x), bf_lo(w.y), bf_hi(w.y)}; y1 = (f32x4){bf_lo(w.z), bf_hi(w.z), bf_lo(w.w), bf_hi(w.w)}; }
;                     float sa = ((y0[0] + y0[1]) + (y0[2] + y0[3])) + ((y1[0] + y1[1]) + (y1[2] + y1[3]));
;                     float sb = ((y0[0] * y0[0] + y0[1] * y0[1]) + (y0[2] * y0[2] + y0[3] * y0[3])) + ((y1[0] * y1[0] + y1[1] * y1[1]) + (y1[2] * y1[2] + y1[3] * y1[3]));
;                     sa += dpp_x1(sa);
;                     sb += dpp_x1(sb);
;                     sa += __shfl_xor(sa, 16); sa += __shfl_xor(sa, 32); sb += __shfl_xor(sb, 16); sb += __shfl_xor(sb, 32);
;                     if (fq == 0 && !odd) ps[(size_t)(rl + q) * 64] = (f32x2){sa, sb};
	v_mul_f32_e32 v150, 0x3fb504f3, v149
	v_sub_f32_e32 v153, v153, v148
	v_sub_f32_e32 v152, v152, v148
	v_pk_mul_f32 v[152:153], v[152:153], v[150:151] op_sel_hi:[1,0]
	v_sub_f32_e32 v155, v155, v148
	v_pk_fma_f32 v[152:153], v[76:77], v[152:153], v[184:185]
	v_sub_f32_e32 v154, v154, v148
	v_pk_add_f32 v[116:117], v[116:117], v[152:153]
	v_sub_f32_e32 v153, v191, v148
	v_sub_f32_e32 v152, v189, v148
	v_sub_f32_e32 v149, v151, v148
	v_sub_f32_e32 v148, v193, v148
	v_pk_mul_f32 v[154:155], v[154:155], v[150:151] op_sel_hi:[1,0]
	v_pk_mul_f32 v[148:149], v[148:149], v[150:151] op_sel_hi:[1,0]
	v_pk_mul_f32 v[150:151], v[152:153], v[150:151] op_sel_hi:[1,0]
	v_cndmask_b32_e64 v115, v127, v115, s[10:11]
	v_cndmask_b32_e64 v114, v125, v114, s[10:11]
	v_pk_fma_f32 v[154:155], v[78:79], v[154:155], v[182:183]
	v_pk_fma_f32 v[150:151], v[72:73], v[150:151], v[180:181]
	v_pk_fma_f32 v[148:149], v[74:75], v[148:149], v[178:179]
	v_pk_add_f32 v[118:119], v[118:119], v[154:155]
	v_pk_add_f32 v[114:115], v[114:115], v[148:149]
	v_pk_add_f32 v[112:113], v[112:113], v[150:151]
	v_cvt_pk_bf16_f32 v148, v116, v117
	v_cvt_pk_bf16_f32 v149, v118, v119
	v_mov_b32_e32 v193, v165
	v_cvt_pk_bf16_f32 v150, v112, v113
	v_cvt_pk_bf16_f32 v151, v114, v115
	v_lshlrev_b32_e32 v112, 16, v148
	v_and_b32_e32 v114, 0xffff0000, v148
	v_lshlrev_b32_e32 v116, 16, v149
	v_and_b32_e32 v118, 0xffff0000, v149
	v_lshlrev_b32_e32 v152, 16, v150
	v_and_b32_e32 v154, 0xffff0000, v150
	v_lshlrev_b32_e32 v194, 16, v151
	v_and_b32_e32 v196, 0xffff0000, v151
	v_mul_f32_e32 v113, v112, v112
	v_mul_f32_e32 v115, v114, v114
	v_mul_f32_e32 v117, v116, v116
	v_mul_f32_e32 v119, v118, v118
	v_mul_f32_e32 v153, v152, v152
	v_mul_f32_e32 v155, v154, v154
	v_mul_f32_e32 v195, v194, v194
	v_mul_f32_e32 v197, v196, v196
	v_pk_add_f32 v[112:113], v[112:113], v[114:115]
	v_pk_add_f32 v[114:115], v[116:117], v[118:119]
	v_pk_add_f32 v[116:117], v[194:195], v[196:197]
	v_pk_add_f32 v[112:113], v[112:113], v[114:115]
	v_pk_add_f32 v[114:115], v[152:153], v[154:155]
	s_nop 0
	v_pk_add_f32 v[114:115], v[114:115], v[116:117]
	s_nop 0
	v_pk_add_f32 v[112:113], v[112:113], v[114:115]
	v_mov_b32_e32 v114, v165
	v_mov_b32_e32 v115, v165
	s_nop 0
	v_mov_b32_dpp v114, v112 quad_perm:[1,0,3,2] row_mask:0xf bank_mask:0xf
	v_mov_b32_dpp v115, v113 quad_perm:[1,0,3,2] row_mask:0xf bank_mask:0xf
	v_pk_add_f32 v[112:113], v[112:113], v[114:115]
	ds_bpermute_b32 v114, v207, v112
	ds_bpermute_b32 v115, v207, v113
	s_waitcnt lgkmcnt(0)
	v_pk_add_f32 v[114:115], v[112:113], v[114:115]
	ds_bpermute_b32 v116, v208, v114
	ds_bpermute_b32 v117, v208, v115
	v_lshl_add_u64 v[112:113], s[20:21], 0, v[192:193]
	global_store_dwordx4 v[112:113], v[148:151], off
	s_and_saveexec_b64 s[64:65], s[16:17]
	s_waitcnt lgkmcnt(0)
	v_pk_add_f32 v[114:115], v[114:115], v[116:117]
	v_add_co_u32_e32 v116, vcc, 0x2000, v186
	s_nop 1
	v_addc_co_u32_e32 v117, vcc, 0, v187, vcc
	global_store_dwordx2 v[116:117], v[114:115], off
.LBB0_1469:
	s_or_b64 exec, exec, s[64:65]
	ds_read_b64 v[114:115], v201 offset:136
	s_waitcnt lgkmcnt(1)
	s_waitcnt vmcnt(14)
	v_lshlrev_b32_e32 v117, 16, v144
	v_and_b32_e32 v118, 0xffff0000, v144
	v_cndmask_b32_e64 v109, v109, v122, s[10:11]
	v_cndmask_b32_e64 v108, v108, v120, s[10:11]
	s_waitcnt lgkmcnt(0)
	v_mul_f32_e32 v116, 0x3fb504f3, v115
	v_sub_f32_e32 v119, v118, v114
	v_sub_f32_e32 v118, v117, v114
	v_pk_mul_f32 v[118:119], v[118:119], v[116:117] op_sel_hi:[1,0]
	v_cndmask_b32_e64 v111, v111, v123, s[10:11]
	v_cndmask_b32_e64 v110, v110, v121, s[10:11]
	v_cndmask_b32_e64 v104, v104, v124, s[10:11]
	v_cndmask_b32_e64 v106, v106, v125, s[10:11]
	v_lshlrev_b32_e32 v120, 16, v145
	v_and_b32_e32 v121, 0xffff0000, v145
	v_lshlrev_b32_e32 v122, 16, v146
	v_and_b32_e32 v123, 0xffff0000, v146
	v_lshlrev_b32_e32 v124, 16, v147
	v_and_b32_e32 v125, 0xffff0000, v147
	v_pk_fma_f32 v[118:119], v[76:77], v[118:119], v[184:185]
	v_sub_f32_e32 v121, v121, v114
	v_sub_f32_e32 v120, v120, v114
	v_pk_add_f32 v[108:109], v[108:109], v[118:119]
	v_sub_f32_e32 v119, v123, v114
	v_sub_f32_e32 v118, v122, v114
	v_sub_f32_e32 v115, v125, v114
	v_sub_f32_e32 v114, v124, v114
	v_pk_mul_f32 v[120:121], v[120:121], v[116:117] op_sel_hi:[1,0]
	v_pk_mul_f32 v[114:115], v[114:115], v[116:117] op_sel_hi:[1,0]
	v_pk_mul_f32 v[116:117], v[118:119], v[116:117] op_sel_hi:[1,0]
	v_cndmask_b32_e64 v105, v105, v126, s[10:11]
	v_cndmask_b32_e64 v107, v107, v127, s[10:11]
	v_pk_fma_f32 v[120:121], v[78:79], v[120:121], v[182:183]
	v_pk_fma_f32 v[116:117], v[72:73], v[116:117], v[180:181]
	v_pk_fma_f32 v[114:115], v[74:75], v[114:115], v[178:179]
	v_pk_add_f32 v[110:111], v[110:111], v[120:121]
	v_pk_add_f32 v[106:107], v[106:107], v[114:115]
	v_pk_add_f32 v[104:105], v[104:105], v[116:117]
	v_cvt_pk_bf16_f32 v108, v108, v109
	v_cvt_pk_bf16_f32 v109, v110, v111
	s_nop 0
	v_cvt_pk_bf16_f32 v110, v104, v105
	v_cvt_pk_bf16_f32 v111, v106, v107
	v_lshlrev_b32_e32 v104, 16, v108
	v_and_b32_e32 v106, 0xffff0000, v108
	v_lshlrev_b32_e32 v114, 16, v109
	v_and_b32_e32 v116, 0xffff0000, v109
	v_lshlrev_b32_e32 v118, 16, v110
	v_and_b32_e32 v120, 0xffff0000, v110
	v_lshlrev_b32_e32 v122, 16, v111
	v_and_b32_e32 v124, 0xffff0000, v111
	v_mul_f32_e32 v105, v104, v104
	v_mul_f32_e32 v107, v106, v106
	v_mul_f32_e32 v115, v114, v114
	v_mul_f32_e32 v117, v116, v116
	v_mul_f32_e32 v119, v118, v118
	v_mul_f32_e32 v121, v120, v120
	v_mul_f32_e32 v123, v122, v122
	v_mul_f32_e32 v125, v124, v124
	v_pk_add_f32 v[104:105], v[104:105], v[106:107]
	v_pk_add_f32 v[106:107], v[114:115], v[116:117]
	v_pk_add_f32 v[114:115], v[122:123], v[124:125]
	v_pk_add_f32 v[104:105], v[104:105], v[106:107]
	v_pk_add_f32 v[106:107], v[118:119], v[120:121]
	global_store_dwordx4 v[112:113], v[108:111], off offset:128
	v_pk_add_f32 v[106:107], v[106:107], v[114:115]
	s_nop 0
	v_pk_add_f32 v[104:105], v[104:105], v[106:107]
	v_mov_b32_e32 v106, v165
	v_mov_b32_e32 v107, v165
	s_nop 0
	v_mov_b32_dpp v106, v104 quad_perm:[1,0,3,2] row_mask:0xf bank_mask:0xf
	v_mov_b32_dpp v107, v105 quad_perm:[1,0,3,2] row_mask:0xf bank_mask:0xf
	v_pk_add_f32 v[104:105], v[104:105], v[106:107]
	ds_bpermute_b32 v106, v207, v104
	ds_bpermute_b32 v107, v207, v105
	s_waitcnt lgkmcnt(0)
	v_pk_add_f32 v[104:105], v[104:105], v[106:107]
	ds_bpermute_b32 v106, v208, v104
	ds_bpermute_b32 v107, v208, v105
	s_and_saveexec_b64 s[64:65], s[16:17]
	s_waitcnt lgkmcnt(0)
	v_pk_add_f32 v[104:105], v[104:105], v[106:107]
	v_add_co_u32_e32 v106, vcc, 0x2000, v186
	s_nop 1
	v_addc_co_u32_e32 v107, vcc, 0, v187, vcc
	global_store_dwordx2 v[106:107], v[104:105], off offset:512
; __device__ __forceinline__ u32x4 pack8f(f32x4 a, f32x4 b) { u32x4 w; w.x = cvt_pk_bf16(a[0], a[1]); w.y = cvt_pk_bf16(a[2], a[3]); w.z = cvt_pk_bf16(b[0], b[1]); w.w = cvt_pk_bf16(b[2], b[3]); return w; }
;     __device__ __forceinline__ void operator()(const f32x4 (&acc)[2][2][4][2], const Unit& u, int wr, int wc, int fr, int fq, const EpiCtx& X) const {
;     ...
;             for (int m = 0; m < 4; ++m) {
;                 const int rl = ai * HALF + m * 16; const unsigned off = lo + (unsigned)(rl * 64) * 2u;
;                 const f32x4 o0a = acc[ai][0][m][0], o0b = acc[ai][0][m][1], o1a = acc[ai][1][m][0], o1b = acc[ai][1][m][1];
;                 const f32x4 ra_ = dpp_swap1(odd ? o0a : o1a), rb_ = dpp_swap1(odd ? o0b : o1b);
;                 const f32x4 pa[2] = {odd ? ra_ : o0a, odd ? o1a : ra_}, pb[2] = {odd ? rb_ : o0b, odd ? o1b : rb_};
; #pragma unroll
;                 for (int q = 0; q < 2; ++q) {
;                     const u32x4 w0 = raw[2 * m + q];
;                     const f32x4 r0 = (f32x4){bf_lo(w0.x), bf_hi(w0.x), bf_lo(w0.y), bf_hi(w0.y)}, r1 = (f32x4){bf_lo(w0.z), bf_hi(w0.z), bf_lo(w0.w), bf_hi(w0.w)};
;                     f32x4 y0, y1;
;                     if (RESN) { const f32x2 t = tbl[rl + q]; const float mu = t.x, ra = t.y * ALPHA; y0 = (r0 - mu) * ra * g0 + b0 + pa[q]; y1 = (r1 - mu) * ra * g1 + b1 + pb[q]; }
;                     else { y0 = r0 * ALPHA + pa[q]; y1 = r1 * ALPHA + pb[q]; }
;                     { const u32x4 w = pack8f(y0, y1); *(u32x4*)(xb + off + q * 128) = w;
;                         y0 = (f32x4){bf_lo(w.x), bf_hi(w.x), bf_lo(w.y), bf_hi(w.y)}; y1 = (f32x4){bf_lo(w.z), bf_hi(w.z), bf_lo(w.w), bf_hi(w.w)}; }
;                     float sa = ((y0[0] + y0[1]) + (y0[2] + y0[3])) + ((y1[0] + y1[1]) + (y1[2] + y1[3]));
;                     float sb = ((y0[0] * y0[0] + y0[1] * y0[1]) + (y0[2] * y0[2] + y0[3] * y0[3])) + ((y1[0] * y1[0] + y1[1] * y1[1]) + (y1[2] * y1[2] + y1[3] * y1[3]));
;                     sa += dpp_x1(sa);
;                     sb += dpp_x1(sb);
;                     sa += __shfl_xor(sa, 16); sa += __shfl_xor(sa, 32); sb += __shfl_xor(sb, 16); sb += __shfl_xor(sb, 32);
;                     if (fq == 0 && !odd) ps[(size_t)(rl + q) * 64] = (f32x2){sa, sb};
.LBB0_1471:
	s_or_b64 exec, exec, s[64:65]
	s_waitcnt lgkmcnt(1)
	v_cndmask_b32_e64 v106, v100, v92, s[10:11]
	v_mov_b32_e32 v104, 0
	v_cndmask_b32_e64 v105, v101, v93, s[10:11]
	s_waitcnt lgkmcnt(0)
	v_cndmask_b32_e64 v107, v102, v94, s[10:11]
	v_mov_b32_dpp v104, v106 quad_perm:[1,0,3,2] row_mask:0xf bank_mask:0xf
	v_mov_b32_e32 v106, 0
	v_cndmask_b32_e64 v108, v103, v95, s[10:11]
	v_cndmask_b32_e64 v110, v96, v88, s[10:11]
	v_mov_b32_dpp v106, v105 quad_perm:[1,0,3,2] row_mask:0xf bank_mask:0xf
	v_mov_b32_e32 v105, 0
	v_cndmask_b32_e64 v109, v97, v89, s[10:11]
	v_cndmask_b32_e64 v111, v98, v90, s[10:11]
	v_mov_b32_dpp v105, v107 quad_perm:[1,0,3,2] row_mask:0xf bank_mask:0xf
	v_mov_b32_e32 v107, 0
	v_cndmask_b32_e64 v112, v99, v91, s[10:11]
	s_waitcnt vmcnt(15)
	v_lshlrev_b32_e32 v115, 16, v140
	v_mov_b32_dpp v107, v108 quad_perm:[1,0,3,2] row_mask:0xf bank_mask:0xf
	v_mov_b32_e32 v108, 0
	v_and_b32_e32 v116, 0xffff0000, v140
	v_cndmask_b32_e64 v101, v106, v101, s[10:11]
	v_mov_b32_dpp v108, v110 quad_perm:[1,0,3,2] row_mask:0xf bank_mask:0xf
	v_mov_b32_e32 v110, 0
	v_cndmask_b32_e64 v100, v104, v100, s[10:11]
	v_lshlrev_b32_e32 v118, 16, v141
	v_mov_b32_dpp v110, v109 quad_perm:[1,0,3,2] row_mask:0xf bank_mask:0xf
	v_mov_b32_e32 v109, 0
	v_and_b32_e32 v119, 0xffff0000, v141
	v_lshlrev_b32_e32 v120, 16, v142
	v_mov_b32_dpp v109, v111 quad_perm:[1,0,3,2] row_mask:0xf bank_mask:0xf
	v_mov_b32_e32 v111, 0
	v_and_b32_e32 v121, 0xffff0000, v142
	v_lshlrev_b32_e32 v122, 16, v143
	v_mov_b32_dpp v111, v112 quad_perm:[1,0,3,2] row_mask:0xf bank_mask:0xf
	ds_read_b64 v[112:113], v201 offset:256
	v_and_b32_e32 v123, 0xffff0000, v143
	v_cndmask_b32_e64 v103, v107, v103, s[10:11]
	v_cndmask_b32_e64 v102, v105, v102, s[10:11]
	v_cndmask_b32_e64 v97, v110, v97, s[10:11]
	s_waitcnt lgkmcnt(0)
	v_mul_f32_e32 v114, 0x3fb504f3, v113
	v_sub_f32_e32 v117, v116, v112
	v_sub_f32_e32 v116, v115, v112
	v_pk_mul_f32 v[116:117], v[116:117], v[114:115] op_sel_hi:[1,0]
	v_sub_f32_e32 v119, v119, v112
	v_pk_fma_f32 v[116:117], v[76:77], v[116:117], v[184:185]
	v_sub_f32_e32 v118, v118, v112
	v_pk_add_f32 v[100:101], v[100:101], v[116:117]
	v_sub_f32_e32 v117, v121, v112
	v_sub_f32_e32 v116, v120, v112
	v_sub_f32_e32 v113, v123, v112
	v_sub_f32_e32 v112, v122, v112
	v_pk_mul_f32 v[118:119], v[118:119], v[114:115] op_sel_hi:[1,0]
	v_pk_mul_f32 v[112:113], v[112:113], v[114:115] op_sel_hi:[1,0]
	v_pk_mul_f32 v[114:115], v[116:117], v[114:115] op_sel_hi:[1,0]
	v_cndmask_b32_e64 v96, v108, v96, s[10:11]
	v_cndmask_b32_e64 v99, v111, v99, s[10:11]
	v_cndmask_b32_e64 v98, v109, v98, s[10:11]
	v_pk_fma_f32 v[118:119], v[78:79], v[118:119], v[182:183]
	v_pk_fma_f32 v[114:115], v[72:73], v[114:115], v[180:181]
	v_pk_fma_f32 v[112:113], v[74:75], v[112:113], v[178:179]
	v_pk_add_f32 v[102:103], v[102:103], v[118:119]
	v_pk_add_f32 v[98:99], v[98:99], v[112:113]
	v_pk_add_f32 v[96:97], v[96:97], v[114:115]
	v_cvt_pk_bf16_f32 v112, v100, v101
	v_cvt_pk_bf16_f32 v113, v102, v103
	v_mov_b32_e32 v191, v165
	v_cvt_pk_bf16_f32 v114, v96, v97
	v_cvt_pk_bf16_f32 v115, v98, v99
	v_lshlrev_b32_e32 v96, 16, v112
	v_and_b32_e32 v98, 0xffff0000, v112
	v_lshlrev_b32_e32 v100, 16, v113
	v_and_b32_e32 v102, 0xffff0000, v113
	v_lshlrev_b32_e32 v116, 16, v114
	v_and_b32_e32 v118, 0xffff0000, v114
	v_lshlrev_b32_e32 v120, 16, v115
	v_and_b32_e32 v122, 0xffff0000, v115
	v_mul_f32_e32 v97, v96, v96
	v_mul_f32_e32 v99, v98, v98
	v_mul_f32_e32 v101, v100, v100
	v_mul_f32_e32 v103, v102, v102
	v_mul_f32_e32 v117, v116, v116
	v_mul_f32_e32 v119, v118, v118
	v_mul_f32_e32 v121, v120, v120
	v_mul_f32_e32 v123, v122, v122
	v_pk_add_f32 v[96:97], v[96:97], v[98:99]
	v_pk_add_f32 v[98:99], v[100:101], v[102:103]
	v_pk_add_f32 v[100:101], v[120:121], v[122:123]
	v_pk_add_f32 v[96:97], v[96:97], v[98:99]
	v_pk_add_f32 v[98:99], v[116:117], v[118:119]
	s_nop 0
	v_pk_add_f32 v[98:99], v[98:99], v[100:101]
	s_nop 0
	v_pk_add_f32 v[96:97], v[96:97], v[98:99]
	v_mov_b32_e32 v98, v165
	v_mov_b32_e32 v99, v165
	s_nop 0
	v_mov_b32_dpp v98, v96 quad_perm:[1,0,3,2] row_mask:0xf bank_mask:0xf
	v_mov_b32_dpp v99, v97 quad_perm:[1,0,3,2] row_mask:0xf bank_mask:0xf
	v_pk_add_f32 v[96:97], v[96:97], v[98:99]
	ds_bpermute_b32 v98, v207, v96
	ds_bpermute_b32 v99, v207, v97
	s_waitcnt lgkmcnt(0)
	v_pk_add_f32 v[98:99], v[96:97], v[98:99]
	ds_bpermute_b32 v100, v208, v98
	ds_bpermute_b32 v101, v208, v99
	v_lshl_add_u64 v[96:97], s[20:21], 0, v[190:191]
	global_store_dwordx4 v[96:97], v[112:115], off
	s_and_saveexec_b64 s[64:65], s[16:17]
	s_waitcnt lgkmcnt(0)
	v_pk_add_f32 v[98:99], v[98:99], v[100:101]
	v_add_co_u32_e32 v100, vcc, 0x4000, v186
	s_nop 1
	v_addc_co_u32_e32 v101, vcc, 0, v187, vcc
	global_store_dwordx2 v[100:101], v[98:99], off
; __device__ __forceinline__ u32x4 pack8f(f32x4 a, f32x4 b) { u32x4 w; w.x = cvt_pk_bf16(a[0], a[1]); w.y = cvt_pk_bf16(a[2], a[3]); w.z = cvt_pk_bf16(b[0], b[1]); w.w = cvt_pk_bf16(b[2], b[3]); return w; }
;     __device__ __forceinline__ void operator()(const f32x4 (&acc)[2][2][4][2], const Unit& u, int wr, int wc, int fr, int fq, const EpiCtx& X) const {
;     ...
;             for (int m = 0; m < 4; ++m) {
;                 const int rl = ai * HALF + m * 16; const unsigned off = lo + (unsigned)(rl * 64) * 2u;
;                 const f32x4 o0a = acc[ai][0][m][0], o0b = acc[ai][0][m][1], o1a = acc[ai][1][m][0], o1b = acc[ai][1][m][1];
;                 const f32x4 ra_ = dpp_swap1(odd ? o0a : o1a), rb_ = dpp_swap1(odd ? o0b : o1b);
;                 const f32x4 pa[2] = {odd ? ra_ : o0a, odd ? o1a : ra_}, pb[2] = {odd ? rb_ : o0b, odd ? o1b : rb_};
; #pragma unroll
;                 for (int q = 0; q < 2; ++q) {
;                     const u32x4 w0 = raw[2 * m + q];
;                     const f32x4 r0 = (f32x4){bf_lo(w0.x), bf_hi(w0.x), bf_lo(w0.y), bf_hi(w0.y)}, r1 = (f32x4){bf_lo(w0.z), bf_hi(w0.z), bf_lo(w0.w), bf_hi(w0.w)};
;                     f32x4 y0, y1;
;                     if (RESN) { const f32x2 t = tbl[rl + q]; const float mu = t.x, ra = t.y * ALPHA; y0 = (r0 - mu) * ra * g0 + b0 + pa[q]; y1 = (r1 - mu) * ra * g1 + b1 + pb[q]; }
;                     else { y0 = r0 * ALPHA + pa[q]; y1 = r1 * ALPHA + pb[q]; }
;                     { const u32x4 w = pack8f(y0, y1); *(u32x4*)(xb + off + q * 128) = w;
;                         y0 = (f32x4){bf_lo(w.x), bf_hi(w.x), bf_lo(w.y), bf_hi(w.y)}; y1 = (f32x4){bf_lo(w.z), bf_hi(w.z), bf_lo(w.w), bf_hi(w.w)}; }
;                     float sa = ((y0[0] + y0[1]) + (y0[2] + y0[3])) + ((y1[0] + y1[1]) + (y1[2] + y1[3]));
;                     float sb = ((y0[0] * y0[0] + y0[1] * y0[1]) + (y0[2] * y0[2] + y0[3] * y0[3])) + ((y1[0] * y1[0] + y1[1] * y1[1]) + (y1[2] * y1[2] + y1[3] * y1[3]));
;                     sa += dpp_x1(sa);
;                     sb += dpp_x1(sb);
;                     sa += __shfl_xor(sa, 16); sa += __shfl_xor(sa, 32); sb += __shfl_xor(sb, 16); sb += __shfl_xor(sb, 32);
;                     if (fq == 0 && !odd) ps[(size_t)(rl + q) * 64] = (f32x2){sa, sb};
.LBB0_1473:
	s_or_b64 exec, exec, s[64:65]
	ds_read_b64 v[98:99], v201 offset:264
	s_waitcnt lgkmcnt(1)
	s_waitcnt vmcnt(16)
	v_lshlrev_b32_e32 v101, 16, v136
	v_and_b32_e32 v102, 0xffff0000, v136
	v_cndmask_b32_e64 v93, v93, v106, s[10:11]
	v_cndmask_b32_e64 v92, v92, v104, s[10:11]
	s_waitcnt lgkmcnt(0)
	v_mul_f32_e32 v100, 0x3fb504f3, v99
	v_sub_f32_e32 v103, v102, v98
	v_sub_f32_e32 v102, v101, v98
	v_pk_mul_f32 v[102:103], v[102:103], v[100:101] op_sel_hi:[1,0]
	v_cndmask_b32_e64 v95, v95, v107, s[10:11]
	v_cndmask_b32_e64 v94, v94, v105, s[10:11]
	v_cndmask_b32_e64 v88, v88, v108, s[10:11]
	v_cndmask_b32_e64 v90, v90, v109, s[10:11]
	v_lshlrev_b32_e32 v104, 16, v137
	v_and_b32_e32 v105, 0xffff0000, v137
	v_lshlrev_b32_e32 v106, 16, v138
	v_and_b32_e32 v107, 0xffff0000, v138
	v_lshlrev_b32_e32 v108, 16, v139
	v_and_b32_e32 v109, 0xffff0000, v139
	v_pk_fma_f32 v[102:103], v[76:77], v[102:103], v[184:185]
	v_sub_f32_e32 v105, v105, v98
	v_sub_f32_e32 v104, v104, v98
	v_pk_add_f32 v[92:93], v[92:93], v[102:103]
	v_sub_f32_e32 v103, v107, v98
	v_sub_f32_e32 v102, v106, v98
	v_sub_f32_e32 v99, v109, v98
	v_sub_f32_e32 v98, v108, v98
	v_pk_mul_f32 v[104:105], v[104:105], v[100:101] op_sel_hi:[1,0]
	v_pk_mul_f32 v[98:99], v[98:99], v[100:101] op_sel_hi:[1,0]
	v_pk_mul_f32 v[100:101], v[102:103], v[100:101] op_sel_hi:[1,0]
	v_cndmask_b32_e64 v89, v89, v110, s[10:11]
	v_cndmask_b32_e64 v91, v91, v111, s[10:11]
	v_pk_fma_f32 v[104:105], v[78:79], v[104:105], v[182:183]
	v_pk_fma_f32 v[100:101], v[72:73], v[100:101], v[180:181]
	v_pk_fma_f32 v[98:99], v[74:75], v[98:99], v[178:179]
	v_pk_add_f32 v[94:95], v[94:95], v[104:105]
	v_pk_add_f32 v[90:91], v[90:91], v[98:99]
	v_pk_add_f32 v[88:89], v[88:89], v[100:101]
	v_cvt_pk_bf16_f32 v92, v92, v93
	v_cvt_pk_bf16_f32 v93, v94, v95
	s_nop 0
	v_cvt_pk_bf16_f32 v94, v88, v89
	v_cvt_pk_bf16_f32 v95, v90, v91
	v_lshlrev_b32_e32 v88, 16, v92
	v_and_b32_e32 v90, 0xffff0000, v92
	v_lshlrev_b32_e32 v98, 16, v93
	v_and_b32_e32 v100, 0xffff0000, v93
	v_lshlrev_b32_e32 v102, 16, v94
	v_and_b32_e32 v104, 0xffff0000, v94
	v_lshlrev_b32_e32 v106, 16, v95
	v_and_b32_e32 v108, 0xffff0000, v95
	v_mul_f32_e32 v89, v88, v88
	v_mul_f32_e32 v91, v90, v90
	v_mul_f32_e32 v99, v98, v98
	v_mul_f32_e32 v101, v100, v100
	v_mul_f32_e32 v103, v102, v102
	v_mul_f32_e32 v105, v104, v104
	v_mul_f32_e32 v107, v106, v106
	v_mul_f32_e32 v109, v108, v108
	v_pk_add_f32 v[88:89], v[88:89], v[90:91]
	v_pk_add_f32 v[90:91], v[98:99], v[100:101]
	v_pk_add_f32 v[98:99], v[106:107], v[108:109]
	v_pk_add_f32 v[88:89], v[88:89], v[90:91]
	v_pk_add_f32 v[90:91], v[102:103], v[104:105]
	global_store_dwordx4 v[96:97], v[92:95], off offset:128
	v_pk_add_f32 v[90:91], v[90:91], v[98:99]
	s_nop 0
	v_pk_add_f32 v[88:89], v[88:89], v[90:91]
	v_mov_b32_e32 v90, v165
	v_mov_b32_e32 v91, v165
	s_nop 0
	v_mov_b32_dpp v90, v88 quad_perm:[1,0,3,2] row_mask:0xf bank_mask:0xf
	v_mov_b32_dpp v91, v89 quad_perm:[1,0,3,2] row_mask:0xf bank_mask:0xf
	v_pk_add_f32 v[88:89], v[88:89], v[90:91]
	ds_bpermute_b32 v90, v207, v88
	ds_bpermute_b32 v91, v207, v89
	s_waitcnt lgkmcnt(0)
	v_pk_add_f32 v[88:89], v[88:89], v[90:91]
	ds_bpermute_b32 v90, v208, v88
	ds_bpermute_b32 v91, v208, v89
	s_and_saveexec_b64 s[64:65], s[16:17]
	s_waitcnt lgkmcnt(0)
	v_pk_add_f32 v[88:89], v[88:89], v[90:91]
	v_add_co_u32_e32 v90, vcc, 0x4000, v186
	s_nop 1
	v_addc_co_u32_e32 v91, vcc, 0, v187, vcc
	global_store_dwordx2 v[90:91], v[88:89], off offset:512
.LBB0_1475:
	s_or_b64 exec, exec, s[64:65]
	s_waitcnt lgkmcnt(1)
	v_cndmask_b32_e64 v90, v84, v68, s[10:11]
	v_mov_b32_e32 v88, 0
	v_cndmask_b32_e64 v89, v85, v69, s[10:11]
	s_waitcnt lgkmcnt(0)
	v_cndmask_b32_e64 v91, v86, v70, s[10:11]
	v_mov_b32_dpp v88, v90 quad_perm:[1,0,3,2] row_mask:0xf bank_mask:0xf
	v_mov_b32_e32 v90, 0
	v_cndmask_b32_e64 v92, v87, v71, s[10:11]
	v_cndmask_b32_e64 v94, v80, v64, s[10:11]
	v_mov_b32_dpp v90, v89 quad_perm:[1,0,3,2] row_mask:0xf bank_mask:0xf
	v_mov_b32_e32 v89, 0
	v_cndmask_b32_e64 v93, v81, v65, s[10:11]
	v_cndmask_b32_e64 v95, v82, v66, s[10:11]
	v_mov_b32_dpp v89, v91 quad_perm:[1,0,3,2] row_mask:0xf bank_mask:0xf
	v_mov_b32_e32 v91, 0
	v_cndmask_b32_e64 v96, v83, v67, s[10:11]
	s_waitcnt vmcnt(17)
	v_lshlrev_b32_e32 v99, 16, v132
	v_mov_b32_dpp v91, v92 quad_perm:[1,0,3,2] row_mask:0xf bank_mask:0xf
	v_mov_b32_e32 v92, 0
	v_and_b32_e32 v100, 0xffff0000, v132
	v_cndmask_b32_e64 v85, v90, v85, s[10:11]
	v_mov_b32_dpp v92, v94 quad_perm:[1,0,3,2] row_mask:0xf bank_mask:0xf
	v_mov_b32_e32 v94, 0
	v_cndmask_b32_e64 v84, v88, v84, s[10:11]
	v_lshlrev_b32_e32 v102, 16, v133
	v_mov_b32_dpp v94, v93 quad_perm:[1,0,3,2] row_mask:0xf bank_mask:0xf
	v_mov_b32_e32 v93, 0
	v_and_b32_e32 v103, 0xffff0000, v133
	v_lshlrev_b32_e32 v104, 16, v134
	v_mov_b32_dpp v93, v95 quad_perm:[1,0,3,2] row_mask:0xf bank_mask:0xf
	v_mov_b32_e32 v95, 0
	v_and_b32_e32 v105, 0xffff0000, v134
	v_lshlrev_b32_e32 v106, 16, v135
	v_mov_b32_dpp v95, v96 quad_perm:[1,0,3,2] row_mask:0xf bank_mask:0xf
	ds_read_b64 v[96:97], v201 offset:384
	v_and_b32_e32 v107, 0xffff0000, v135
	v_cndmask_b32_e64 v87, v91, v87, s[10:11]
	v_cndmask_b32_e64 v86, v89, v86, s[10:11]
	v_cndmask_b32_e64 v81, v94, v81, s[10:11]
	s_waitcnt lgkmcnt(0)
; __device__ __forceinline__ u32x4 pack8f(f32x4 a, f32x4 b) { u32x4 w; w.x = cvt_pk_bf16(a[0], a[1]); w.y = cvt_pk_bf16(a[2], a[3]); w.z = cvt_pk_bf16(b[0], b[1]); w.w = cvt_pk_bf16(b[2], b[3]); return w; }
;     __device__ __forceinline__ void operator()(const f32x4 (&acc)[2][2][4][2], const Unit& u, int wr, int wc, int fr, int fq, const EpiCtx& X) const {
;     ...
;             for (int m = 0; m < 4; ++m) {
;                 const int rl = ai * HALF + m * 16; const unsigned off = lo + (unsigned)(rl * 64) * 2u;
;                 const f32x4 o0a = acc[ai][0][m][0], o0b = acc[ai][0][m][1], o1a = acc[ai][1][m][0], o1b = acc[ai][1][m][1];
;                 const f32x4 ra_ = dpp_swap1(odd ? o0a : o1a), rb_ = dpp_swap1(odd ? o0b : o1b);
;                 const f32x4 pa[2] = {odd ? ra_ : o0a, odd ? o1a : ra_}, pb[2] = {odd ? rb_ : o0b, odd ? o1b : rb_};
; #pragma unroll
;                 for (int q = 0; q < 2; ++q) {
;                     const u32x4 w0 = raw[2 * m + q];
;                     const f32x4 r0 = (f32x4){bf_lo(w0.x), bf_hi(w0.x), bf_lo(w0.y), bf_hi(w0.y)}, r1 = (f32x4){bf_lo(w0.z), bf_hi(w0.z), bf_lo(w0.w), bf_hi(w0.w)};
;                     f32x4 y0, y1;
;                     if (RESN) { const f32x2 t = tbl[rl + q]; const float mu = t.x, ra = t.y * ALPHA; y0 = (r0 - mu) * ra * g0 + b0 + pa[q]; y1 = (r1 - mu) * ra * g1 + b1 + pb[q]; }
;                     else { y0 = r0 * ALPHA + pa[q]; y1 = r1 * ALPHA + pb[q]; }
;                     { const u32x4 w = pack8f(y0, y1); *(u32x4*)(xb + off + q * 128) = w;
;                         y0 = (f32x4){bf_lo(w.x), bf_hi(w.x), bf_lo(w.y), bf_hi(w.y)}; y1 = (f32x4){bf_lo(w.z), bf_hi(w.z), bf_lo(w.w), bf_hi(w.w)}; }
;                     float sa = ((y0[0] + y0[1]) + (y0[2] + y0[3])) + ((y1[0] + y1[1]) + (y1[2] + y1[3]));
;                     float sb = ((y0[0] * y0[0] + y0[1] * y0[1]) + (y0[2] * y0[2] + y0[3] * y0[3])) + ((y1[0] * y1[0] + y1[1] * y1[1]) + (y1[2] * y1[2] + y1[3] * y1[3]));
;                     sa += dpp_x1(sa);
;                     sb += dpp_x1(sb);
;                     sa += __shfl_xor(sa, 16); sa += __shfl_xor(sa, 32); sb += __shfl_xor(sb, 16); sb += __shfl_xor(sb, 32);
;                     if (fq == 0 && !odd) ps[(size_t)(rl + q) * 64] = (f32x2){sa, sb};
	v_mul_f32_e32 v98, 0x3fb504f3, v97
	v_sub_f32_e32 v101, v100, v96
	v_sub_f32_e32 v100, v99, v96
	v_pk_mul_f32 v[100:101], v[100:101], v[98:99] op_sel_hi:[1,0]
	v_sub_f32_e32 v103, v103, v96
	v_pk_fma_f32 v[100:101], v[76:77], v[100:101], v[184:185]
	v_sub_f32_e32 v102, v102, v96
	v_pk_add_f32 v[84:85], v[84:85], v[100:101]
	v_sub_f32_e32 v101, v105, v96
	v_sub_f32_e32 v100, v104, v96
	v_sub_f32_e32 v97, v107, v96
	v_sub_f32_e32 v96, v106, v96
	v_pk_mul_f32 v[102:103], v[102:103], v[98:99] op_sel_hi:[1,0]
	v_pk_mul_f32 v[96:97], v[96:97], v[98:99] op_sel_hi:[1,0]
	v_pk_mul_f32 v[98:99], v[100:101], v[98:99] op_sel_hi:[1,0]
	v_cndmask_b32_e64 v80, v92, v80, s[10:11]
	v_cndmask_b32_e64 v83, v95, v83, s[10:11]
	v_cndmask_b32_e64 v82, v93, v82, s[10:11]
	v_pk_fma_f32 v[102:103], v[78:79], v[102:103], v[182:183]
	v_pk_fma_f32 v[98:99], v[72:73], v[98:99], v[180:181]
	v_pk_fma_f32 v[96:97], v[74:75], v[96:97], v[178:179]
	v_pk_add_f32 v[86:87], v[86:87], v[102:103]
	v_pk_add_f32 v[82:83], v[82:83], v[96:97]
	v_pk_add_f32 v[80:81], v[80:81], v[98:99]
	v_cvt_pk_bf16_f32 v96, v84, v85
	v_cvt_pk_bf16_f32 v97, v86, v87
	v_mov_b32_e32 v189, v165
	v_cvt_pk_bf16_f32 v98, v80, v81
	v_cvt_pk_bf16_f32 v99, v82, v83
	v_lshlrev_b32_e32 v80, 16, v96
	v_and_b32_e32 v82, 0xffff0000, v96
	v_lshlrev_b32_e32 v84, 16, v97
	v_and_b32_e32 v86, 0xffff0000, v97
	v_lshlrev_b32_e32 v100, 16, v98
	v_and_b32_e32 v102, 0xffff0000, v98
	v_lshlrev_b32_e32 v104, 16, v99
	v_and_b32_e32 v106, 0xffff0000, v99
	v_mul_f32_e32 v81, v80, v80
	v_mul_f32_e32 v83, v82, v82
	v_mul_f32_e32 v85, v84, v84
	v_mul_f32_e32 v87, v86, v86
	v_mul_f32_e32 v101, v100, v100
	v_mul_f32_e32 v103, v102, v102
	v_mul_f32_e32 v105, v104, v104
	v_mul_f32_e32 v107, v106, v106
	v_pk_add_f32 v[80:81], v[80:81], v[82:83]
	v_pk_add_f32 v[82:83], v[84:85], v[86:87]
	v_pk_add_f32 v[84:85], v[104:105], v[106:107]
	v_pk_add_f32 v[80:81], v[80:81], v[82:83]
	v_pk_add_f32 v[82:83], v[100:101], v[102:103]
	s_nop 0
	v_pk_add_f32 v[82:83], v[82:83], v[84:85]
	s_nop 0
	v_pk_add_f32 v[80:81], v[80:81], v[82:83]
	v_mov_b32_e32 v82, v165
	v_mov_b32_e32 v83, v165
	s_nop 0
	v_mov_b32_dpp v82, v80 quad_perm:[1,0,3,2] row_mask:0xf bank_mask:0xf
	v_mov_b32_dpp v83, v81 quad_perm:[1,0,3,2] row_mask:0xf bank_mask:0xf
	v_pk_add_f32 v[80:81], v[80:81], v[82:83]
	ds_bpermute_b32 v82, v207, v80
	ds_bpermute_b32 v83, v207, v81
	s_waitcnt lgkmcnt(0)
	v_pk_add_f32 v[82:83], v[80:81], v[82:83]
	ds_bpermute_b32 v84, v208, v82
	ds_bpermute_b32 v85, v208, v83
	v_lshl_add_u64 v[80:81], s[20:21], 0, v[188:189]
	global_store_dwordx4 v[80:81], v[96:99], off
	s_and_saveexec_b64 s[64:65], s[16:17]
	s_waitcnt lgkmcnt(0)
	v_pk_add_f32 v[82:83], v[82:83], v[84:85]
	v_add_co_u32_e32 v84, vcc, 0x6000, v186
	s_nop 1
	v_addc_co_u32_e32 v85, vcc, 0, v187, vcc
	global_store_dwordx2 v[84:85], v[82:83], off
.LBB0_1477:
	s_or_b64 exec, exec, s[64:65]
	ds_read_b64 v[82:83], v201 offset:392
	s_waitcnt lgkmcnt(1)
	s_waitcnt vmcnt(18)
	v_lshlrev_b32_e32 v85, 16, v128
	v_and_b32_e32 v86, 0xffff0000, v128
	v_cndmask_b32_e64 v69, v69, v90, s[10:11]
	v_cndmask_b32_e64 v68, v68, v88, s[10:11]
	s_waitcnt lgkmcnt(0)
	v_mul_f32_e32 v84, 0x3fb504f3, v83
	v_sub_f32_e32 v87, v86, v82
	v_sub_f32_e32 v86, v85, v82
	v_pk_mul_f32 v[86:87], v[86:87], v[84:85] op_sel_hi:[1,0]
	v_cndmask_b32_e64 v71, v71, v91, s[10:11]
	v_cndmask_b32_e64 v70, v70, v89, s[10:11]
	v_cndmask_b32_e64 v64, v64, v92, s[10:11]
	v_cndmask_b32_e64 v66, v66, v93, s[10:11]
	v_lshlrev_b32_e32 v88, 16, v129
	v_and_b32_e32 v89, 0xffff0000, v129
	v_lshlrev_b32_e32 v90, 16, v130
	v_and_b32_e32 v91, 0xffff0000, v130
	v_lshlrev_b32_e32 v92, 16, v131
	v_and_b32_e32 v93, 0xffff0000, v131
	v_pk_fma_f32 v[86:87], v[76:77], v[86:87], v[184:185]
	v_sub_f32_e32 v89, v89, v82
	v_sub_f32_e32 v88, v88, v82
	v_pk_add_f32 v[68:69], v[68:69], v[86:87]
	v_sub_f32_e32 v87, v91, v82
	v_sub_f32_e32 v86, v90, v82
	v_sub_f32_e32 v83, v93, v82
	v_sub_f32_e32 v82, v92, v82
	v_pk_mul_f32 v[88:89], v[88:89], v[84:85] op_sel_hi:[1,0]
	v_pk_mul_f32 v[82:83], v[82:83], v[84:85] op_sel_hi:[1,0]
	v_pk_mul_f32 v[84:85], v[86:87], v[84:85] op_sel_hi:[1,0]
	v_cndmask_b32_e64 v65, v65, v94, s[10:11]
	v_cndmask_b32_e64 v67, v67, v95, s[10:11]
	v_pk_fma_f32 v[88:89], v[78:79], v[88:89], v[182:183]
	v_pk_fma_f32 v[84:85], v[72:73], v[84:85], v[180:181]
	v_pk_fma_f32 v[82:83], v[74:75], v[82:83], v[178:179]
	v_pk_add_f32 v[70:71], v[70:71], v[88:89]
	v_pk_add_f32 v[66:67], v[66:67], v[82:83]
	v_pk_add_f32 v[64:65], v[64:65], v[84:85]
	v_cvt_pk_bf16_f32 v68, v68, v69
	v_cvt_pk_bf16_f32 v69, v70, v71
	s_nop 0
	v_cvt_pk_bf16_f32 v70, v64, v65
	v_cvt_pk_bf16_f32 v71, v66, v67
	v_lshlrev_b32_e32 v64, 16, v68
	v_and_b32_e32 v66, 0xffff0000, v68
	v_lshlrev_b32_e32 v82, 16, v69
	v_and_b32_e32 v84, 0xffff0000, v69
	v_lshlrev_b32_e32 v86, 16, v70
	v_and_b32_e32 v88, 0xffff0000, v70
	v_lshlrev_b32_e32 v90, 16, v71
	v_and_b32_e32 v92, 0xffff0000, v71
	v_mul_f32_e32 v65, v64, v64
	v_mul_f32_e32 v67, v66, v66
	v_mul_f32_e32 v83, v82, v82
	v_mul_f32_e32 v85, v84, v84
	v_mul_f32_e32 v87, v86, v86
	v_mul_f32_e32 v89, v88, v88
	v_mul_f32_e32 v91, v90, v90
	v_mul_f32_e32 v93, v92, v92
	v_pk_add_f32 v[64:65], v[64:65], v[66:67]
	v_pk_add_f32 v[66:67], v[82:83], v[84:85]
	v_pk_add_f32 v[82:83], v[90:91], v[92:93]
	v_pk_add_f32 v[64:65], v[64:65], v[66:67]
	v_pk_add_f32 v[66:67], v[86:87], v[88:89]
	global_store_dwordx4 v[80:81], v[68:71], off offset:128
	v_pk_add_f32 v[66:67], v[66:67], v[82:83]
	s_nop 0
	v_pk_add_f32 v[64:65], v[64:65], v[66:67]
	v_mov_b32_e32 v66, v165
	v_mov_b32_e32 v67, v165
	s_nop 0
	v_mov_b32_dpp v66, v64 quad_perm:[1,0,3,2] row_mask:0xf bank_mask:0xf
	v_mov_b32_dpp v67, v65 quad_perm:[1,0,3,2] row_mask:0xf bank_mask:0xf
	v_pk_add_f32 v[64:65], v[64:65], v[66:67]
	ds_bpermute_b32 v66, v207, v64
	ds_bpermute_b32 v67, v207, v65
	s_waitcnt lgkmcnt(0)
	v_pk_add_f32 v[64:65], v[64:65], v[66:67]
	ds_bpermute_b32 v66, v208, v64
	ds_bpermute_b32 v67, v208, v65
	s_and_saveexec_b64 s[64:65], s[16:17]
	s_waitcnt lgkmcnt(0)
	v_pk_add_f32 v[64:65], v[64:65], v[66:67]
	v_add_co_u32_e32 v66, vcc, 0x6000, v186
	s_nop 1
	v_addc_co_u32_e32 v67, vcc, 0, v187, vcc
	global_store_dwordx2 v[66:67], v[64:65], off offset:512
;     __device__ __forceinline__ void operator()(const f32x4 (&acc)[2][2][4][2], const Unit& u, int wr, int wc, int fr, int fq, const EpiCtx& X) const {
;     ...
;         for (int ai = 0; ai < 2; ++ai) {
;             u32x4 raw[8];
; #pragma unroll
;             for (int m = 0; m < 4; ++m) { const unsigned off = lo + (unsigned)((ai * HALF + m * 16) * 64) * 2u; raw[2 * m] = *(const u32x4*)(xb + off); raw[2 * m + 1] = *(const u32x4*)(xb + off + 128); }
; #pragma unroll
;             for (int m = 0; m < 4; ++m) {
;                 const int rl = ai * HALF + m * 16; const unsigned off = lo + (unsigned)(rl * 64) * 2u;
;                 const f32x4 o0a = acc[ai][0][m][0], o0b = acc[ai][0][m][1], o1a = acc[ai][1][m][0], o1b = acc[ai][1][m][1];
;                 const f32x4 ra_ = dpp_swap1(odd ? o0a : o1a), rb_ = dpp_swap1(odd ? o0b : o1b);
;                 const f32x4 pa[2] = {odd ? ra_ : o0a, odd ? o1a : ra_}, pb[2] = {odd ? rb_ : o0b, odd ? o1b : rb_};
; #pragma unroll
;                 for (int q = 0; q < 2; ++q) {
;                     const u32x4 w0 = raw[2 * m + q];
;                     const f32x4 r0 = (f32x4){bf_lo(w0.x), bf_hi(w0.x), bf_lo(w0.y), bf_hi(w0.y)}, r1 = (f32x4){bf_lo(w0.z), bf_hi(w0.z), bf_lo(w0.w), bf_hi(w0.w)};
;                     f32x4 y0, y1;
;                     if (RESN) { const f32x2 t = tbl[rl + q]; const float mu = t.x, ra = t.y * ALPHA; y0 = (r0 - mu) * ra * g0 + b0 + pa[q]; y1 = (r1 - mu) * ra * g1 + b1 + pb[q]; }
;                     else { y0 = r0 * ALPHA + pa[q]; y1 = r1 * ALPHA + pb[q]; }
;                     { const u32x4 w = pack8f(y0, y1); *(u32x4*)(xb + off + q * 128) = w;
;                         y0 = (f32x4){bf_lo(w.x), bf_hi(w.x), bf_lo(w.y), bf_hi(w.y)}; y1 = (f32x4){bf_lo(w.z), bf_hi(w.z), bf_lo(w.w), bf_hi(w.w)}; }
;                     float sa = ((y0[0] + y0[1]) + (y0[2] + y0[3])) + ((y1[0] + y1[1]) + (y1[2] + y1[3]));
;                     float sb = ((y0[0] * y0[0] + y0[1] * y0[1]) + (y0[2] * y0[2] + y0[3] * y0[3])) + ((y1[0] * y1[0] + y1[1] * y1[1]) + (y1[2] * y1[2] + y1[3] * y1[3]));
;                     sa += dpp_x1(sa);
;                     sb += dpp_x1(sb);
;                     sa += __shfl_xor(sa, 16); sa += __shfl_xor(sa, 32); sb += __shfl_xor(sb, 16); sb += __shfl_xor(sb, 32);
;                     if (fq == 0 && !odd) ps[(size_t)(rl + q) * 64] = (f32x2){sa, sb};
.LBB0_1479:
	s_or_b64 exec, exec, s[64:65]
	v_add_u32_e32 v104, 0x4000, v164
	s_waitcnt vmcnt(16)
	v_mov_b32_e32 v112, v230
	v_mov_b32_e32 v113, v231
	v_mov_b32_e32 v114, v232
	v_mov_b32_e32 v115, v233
	v_add_u32_e32 v102, 0x4800, v164
	v_add_u32_e32 v100, 0x5000, v164
	v_add_u32_e32 v164, 0x5800, v164
	v_mov_b32_e32 v96, v234
	v_mov_b32_e32 v97, v235
	v_mov_b32_e32 v98, v236
	v_mov_b32_e32 v99, v237
	v_mov_b32_e32 v92, v238
	v_mov_b32_e32 v93, v239
	v_mov_b32_e32 v94, v240
	v_mov_b32_e32 v95, v241
	v_mov_b32_e32 v88, v242
	v_mov_b32_e32 v89, v243
	v_mov_b32_e32 v90, v244
	v_mov_b32_e32 v91, v245
	global_load_dwordx4 v[84:87], v100, s[20:21]
	global_load_dwordx4 v[80:83], v100, s[20:21] offset:128
	global_load_dwordx4 v[68:71], v164, s[20:21]
	s_waitcnt lgkmcnt(0)
	global_load_dwordx4 v[64:67], v164, s[20:21] offset:128
	v_cndmask_b32_e64 v116, v62, v54, s[10:11]
	v_cndmask_b32_e64 v117, v61, v53, s[10:11]
	v_mov_b32_e32 v105, 0
	v_mov_b32_e32 v103, 0
	v_cndmask_b32_e64 v111, v63, v55, s[10:11]
	v_mov_b32_dpp v105, v117 quad_perm:[1,0,3,2] row_mask:0xf bank_mask:0xf
	v_mov_b32_dpp v103, v116 quad_perm:[1,0,3,2] row_mask:0xf bank_mask:0xf
	ds_read_b64 v[116:117], v201 offset:1024
	v_cndmask_b32_e64 v118, v60, v52, s[10:11]
	v_mov_b32_e32 v101, 0
	v_mov_b32_e32 v106, 0
	v_cndmask_b32_e64 v119, v59, v51, s[10:11]
	v_cndmask_b32_e64 v120, v58, v50, s[10:11]
	v_cndmask_b32_e64 v121, v57, v49, s[10:11]
	v_cndmask_b32_e64 v122, v56, v48, s[10:11]
	v_mov_b32_e32 v107, 0
	v_mov_b32_e32 v109, 0
	v_mov_b32_e32 v108, 0
	v_mov_b32_e32 v110, 0
	v_mov_b32_dpp v101, v118 quad_perm:[1,0,3,2] row_mask:0xf bank_mask:0xf
	v_mov_b32_dpp v106, v111 quad_perm:[1,0,3,2] row_mask:0xf bank_mask:0xf
	v_mov_b32_dpp v107, v122 quad_perm:[1,0,3,2] row_mask:0xf bank_mask:0xf
	v_mov_b32_dpp v109, v121 quad_perm:[1,0,3,2] row_mask:0xf bank_mask:0xf
	v_mov_b32_dpp v108, v120 quad_perm:[1,0,3,2] row_mask:0xf bank_mask:0xf
	v_mov_b32_dpp v110, v119 quad_perm:[1,0,3,2] row_mask:0xf bank_mask:0xf
	s_waitcnt lgkmcnt(0)
	v_mul_f32_e32 v118, 0x3fb504f3, v117
	v_cndmask_b32_e64 v61, v105, v61, s[10:11]
	v_cndmask_b32_e64 v60, v101, v60, s[10:11]
	v_cndmask_b32_e64 v63, v106, v63, s[10:11]
	v_cndmask_b32_e64 v62, v103, v62, s[10:11]
	v_cndmask_b32_e64 v57, v109, v57, s[10:11]
	v_cndmask_b32_e64 v56, v107, v56, s[10:11]
	v_cndmask_b32_e64 v59, v110, v59, s[10:11]
	v_cndmask_b32_e64 v58, v108, v58, s[10:11]
	v_lshlrev_b32_e32 v111, 16, v112
	v_and_b32_e32 v112, 0xffff0000, v112
	v_lshlrev_b32_e32 v117, 16, v113
	v_and_b32_e32 v119, 0xffff0000, v113
	v_lshlrev_b32_e32 v120, 16, v114
	v_and_b32_e32 v121, 0xffff0000, v114
	v_lshlrev_b32_e32 v122, 16, v115
	v_and_b32_e32 v123, 0xffff0000, v115
	v_sub_f32_e32 v113, v112, v116
	v_sub_f32_e32 v112, v111, v116
	v_sub_f32_e32 v115, v119, v116
	v_sub_f32_e32 v114, v117, v116
	v_sub_f32_e32 v121, v121, v116
	v_sub_f32_e32 v120, v120, v116
	v_sub_f32_e32 v117, v123, v116
	v_sub_f32_e32 v116, v122, v116
	v_pk_mul_f32 v[114:115], v[114:115], v[118:119] op_sel_hi:[1,0]
	v_pk_mul_f32 v[112:113], v[112:113], v[118:119] op_sel_hi:[1,0]
	v_pk_mul_f32 v[116:117], v[116:117], v[118:119] op_sel_hi:[1,0]
	v_pk_mul_f32 v[118:119], v[120:121], v[118:119] op_sel_hi:[1,0]
	v_pk_fma_f32 v[112:113], v[76:77], v[112:113], v[184:185]
	v_pk_fma_f32 v[114:115], v[78:79], v[114:115], v[182:183]
	v_pk_fma_f32 v[118:119], v[72:73], v[118:119], v[180:181]
	v_pk_fma_f32 v[116:117], v[74:75], v[116:117], v[178:179]
	v_pk_add_f32 v[62:63], v[62:63], v[114:115]
	v_pk_add_f32 v[60:61], v[60:61], v[112:113]
	v_pk_add_f32 v[58:59], v[58:59], v[116:117]
	v_pk_add_f32 v[56:57], v[56:57], v[118:119]
	v_cvt_pk_bf16_f32 v60, v60, v61
	v_cvt_pk_bf16_f32 v61, v62, v63
	s_nop 0
	v_cvt_pk_bf16_f32 v62, v56, v57
	v_cvt_pk_bf16_f32 v63, v58, v59
	v_lshlrev_b32_e32 v56, 16, v60
	v_and_b32_e32 v58, 0xffff0000, v60
	v_lshlrev_b32_e32 v112, 16, v61
	v_and_b32_e32 v114, 0xffff0000, v61
	v_lshlrev_b32_e32 v116, 16, v62
	v_and_b32_e32 v118, 0xffff0000, v62
	v_lshlrev_b32_e32 v120, 16, v63
	v_and_b32_e32 v122, 0xffff0000, v63
	v_mul_f32_e32 v57, v56, v56
	v_mul_f32_e32 v59, v58, v58
	v_mul_f32_e32 v113, v112, v112
	v_mul_f32_e32 v115, v114, v114
	v_mul_f32_e32 v117, v116, v116
	v_mul_f32_e32 v119, v118, v118
	v_mul_f32_e32 v121, v120, v120
	v_mul_f32_e32 v123, v122, v122
	v_pk_add_f32 v[56:57], v[56:57], v[58:59]
	v_pk_add_f32 v[58:59], v[112:113], v[114:115]
	v_pk_add_f32 v[112:113], v[120:121], v[122:123]
	v_pk_add_f32 v[56:57], v[56:57], v[58:59]
	v_pk_add_f32 v[58:59], v[116:117], v[118:119]
	global_store_dwordx4 v104, v[60:63], s[20:21]
	v_pk_add_f32 v[58:59], v[58:59], v[112:113]
	s_nop 0
	v_pk_add_f32 v[56:57], v[56:57], v[58:59]
	v_mov_b32_e32 v58, v165
	v_mov_b32_e32 v59, v165
	s_nop 0
	v_mov_b32_dpp v58, v56 quad_perm:[1,0,3,2] row_mask:0xf bank_mask:0xf
	v_mov_b32_dpp v59, v57 quad_perm:[1,0,3,2] row_mask:0xf bank_mask:0xf
	v_pk_add_f32 v[56:57], v[56:57], v[58:59]
	ds_bpermute_b32 v58, v207, v56
	ds_bpermute_b32 v59, v207, v57
	s_waitcnt lgkmcnt(0)
	v_pk_add_f32 v[56:57], v[56:57], v[58:59]
	ds_bpermute_b32 v58, v208, v56
	ds_bpermute_b32 v59, v208, v57
	s_and_saveexec_b64 s[64:65], s[16:17]
	s_cbranch_execz .LBB0_1481
	s_waitcnt lgkmcnt(0)
	v_pk_add_f32 v[56:57], v[56:57], v[58:59]
	v_add_co_u32_e32 v58, vcc, 0x10000, v186
	s_nop 1
	v_addc_co_u32_e32 v59, vcc, 0, v187, vcc
	global_store_dwordx2 v[58:59], v[56:57], off

; #define LAS __attribute__((address_space(3)))
;     __device__ __forceinline__ void operator()(const f32x4 (&acc)[2][2][4][2], const Unit& u, int wr, int wc, int fr, int fq, const EpiCtx& X) const {
;     ...
;         char* yb = nullptr; char* xb = (char*)(XB + (size_t)u.pm * BM * DM + (size_t)(u.pn * 4 + wc) * (BM * 64));
;         unsigned lo = (unsigned)((wr * 64 + fe) * 64 + o32 + 8 * fq) * 2u; EPI_OPAQUE(lo);
;         const int col = u.pn * BM + wc * 64 + o32 + 8 * fq;
;         f32x4 g0, g1, b0, b1;
;         if (RESN) { ensure_tbl(PSp, sidp, u.pm, X);
;             g0 = *(const f32x4*)(gp + col); g1 = *(const f32x4*)(gp + col + 4); b0 = *(const f32x4*)(bp + col) * ALPHA; b1 = *(const f32x4*)(bp + col + 4) * ALPHA; }
;         const LAS f32x2* tbl = (const LAS f32x2*)(X.lds + TBL_OFF) + wr * 64 + fe;
;         f32x2* ps = PSn + ((size_t)u.pm * BM + wr * 64 + fe) * 64 + u.pn * 4 + wc;
; #pragma unroll
;         for (int ai = 0; ai < 2; ++ai) {
;             u32x4 raw[8];
; #pragma unroll
;             for (int m = 0; m < 4; ++m) { const unsigned off = lo + (unsigned)((ai * HALF + m * 16) * 64) * 2u; raw[2 * m] = *(const u32x4*)(xb + off); raw[2 * m + 1] = *(const u32x4*)(xb + off + 128); }
; #pragma unroll
;             for (int m = 0; m < 4; ++m) {
;                 const int rl = ai * HALF + m * 16; const unsigned off = lo + (unsigned)(rl * 64) * 2u;
;                 const f32x4 o0a = acc[ai][0][m][0], o0b = acc[ai][0][m][1], o1a = acc[ai][1][m][0], o1b = acc[ai][1][m][1];
;                 const f32x4 ra_ = dpp_swap1(odd ? o0a : o1a), rb_ = dpp_swap1(odd ? o0b : o1b);
;                 const f32x4 pa[2] = {odd ? ra_ : o0a, odd ? o1a : ra_}, pb[2] = {odd ? rb_ : o0b, odd ? o1b : rb_};
; #pragma unroll
;                 for (int q = 0; q < 2; ++q) {
;                     const u32x4 w0 = raw[2 * m + q];
;                     const f32x4 r0 = (f32x4){bf_lo(w0.x), bf_hi(w0.x), bf_lo(w0.y), bf_hi(w0.y)}, r1 = (f32x4){bf_lo(w0.z), bf_hi(w0.z), bf_lo(w0.w), bf_hi(w0.w)};
;                     f32x4 y0, y1;
;                     if (RESN) { const f32x2 t = tbl[rl + q]; const float mu = t.x, ra = t.y * ALPHA; y0 = (r0 - mu) * ra * g0 + b0 + pa[q]; y1 = (r1 - mu) * ra * g1 + b1 + pb[q]; }
;                     else { y0 = r0 * ALPHA + pa[q]; y1 = r1 * ALPHA + pb[q]; }
;                     { const u32x4 w = pack8f(y0, y1); *(u32x4*)(xb + off + q * 128) = w;
.LBB0_1697:
	s_lshl_b64 s[16:17], s[58:59], 21
	s_add_u32 s35, s31, s16
	s_addc_u32 s38, s68, s17
	s_lshl_b32 s58, s56, 2
	s_or_b32 s16, s58, s41
	s_ashr_i32 s17, s16, 31
	v_lshl_add_u32 v72, s56, 8, v200
	v_ashrrev_i32_e32 v73, 31, v72
	s_lshl_b64 s[16:17], s[16:17], 15
	v_lshlrev_b64 v[72:73], 2, v[72:73]
	s_add_u32 s16, s35, s16
	v_lshl_add_u64 v[74:75], s[26:27], 0, v[72:73]
	s_addc_u32 s17, s38, s17
	global_load_dwordx4 v[194:197], v[74:75], off offset:16
	global_load_dwordx4 v[178:181], v[74:75], off
	global_load_dwordx4 v[214:217], v164, s[16:17]
	v_lshl_add_u64 v[72:73], s[24:25], 0, v[72:73]
	s_waitcnt lgkmcnt(0)
	global_load_dwordx4 v[76:79], v[72:73], off
	s_nop 0
	global_load_dwordx4 v[72:75], v[72:73], off offset:16
	v_cndmask_b32_e64 v136, v135, v127, s[6:7]
	v_cndmask_b32_e64 v137, v134, v126, s[6:7]
	v_cndmask_b32_e64 v138, v133, v125, s[6:7]
	v_cndmask_b32_e64 v139, v132, v124, s[6:7]
	v_mov_b32_e32 v189, 0
	v_mov_b32_e32 v193, 0
	v_mov_b32_e32 v191, 0
	v_mov_b32_e32 v209, 0
	v_cndmask_b32_e64 v140, v131, v123, s[6:7]
	v_cndmask_b32_e64 v141, v130, v122, s[6:7]
	v_cndmask_b32_e64 v142, v129, v121, s[6:7]
	v_cndmask_b32_e64 v143, v128, v120, s[6:7]
	v_mov_b32_e32 v210, 0
	v_mov_b32_e32 v212, 0
	v_mov_b32_e32 v211, 0
	v_mov_b32_e32 v213, 0
	v_mov_b32_dpp v189, v139 quad_perm:[1,0,3,2] row_mask:0xf bank_mask:0xf
	v_mov_b32_dpp v193, v138 quad_perm:[1,0,3,2] row_mask:0xf bank_mask:0xf
	v_mov_b32_dpp v191, v137 quad_perm:[1,0,3,2] row_mask:0xf bank_mask:0xf
	v_mov_b32_dpp v209, v136 quad_perm:[1,0,3,2] row_mask:0xf bank_mask:0xf
	v_mov_b32_dpp v210, v143 quad_perm:[1,0,3,2] row_mask:0xf bank_mask:0xf
	v_mov_b32_dpp v212, v142 quad_perm:[1,0,3,2] row_mask:0xf bank_mask:0xf
	v_mov_b32_dpp v211, v141 quad_perm:[1,0,3,2] row_mask:0xf bank_mask:0xf
	v_mov_b32_dpp v213, v140 quad_perm:[1,0,3,2] row_mask:0xf bank_mask:0xf
	v_add_u32_e32 v192, 0x800, v164
	v_add_u32_e32 v190, 0x1000, v164
	v_add_u32_e32 v188, 0x1800, v164
	ds_read_b64 v[218:219], v201
	v_cndmask_b32_e64 v221, v193, v133, s[6:7]
	v_cndmask_b32_e64 v220, v189, v132, s[6:7]
	v_cndmask_b32_e64 v223, v209, v135, s[6:7]
	v_cndmask_b32_e64 v222, v191, v134, s[6:7]
	v_cndmask_b32_e64 v225, v212, v129, s[6:7]
	v_cndmask_b32_e64 v224, v210, v128, s[6:7]
	v_cndmask_b32_e64 v227, v213, v131, s[6:7]
	v_cndmask_b32_e64 v226, v211, v130, s[6:7]
	global_load_dwordx4 v[152:155], v164, s[16:17] offset:128
	global_load_dwordx4 v[148:151], v192, s[16:17]
	global_load_dwordx4 v[144:147], v192, s[16:17] offset:128
	global_load_dwordx4 v[140:143], v190, s[16:17]
	global_load_dwordx4 v[136:139], v190, s[16:17] offset:128
	global_load_dwordx4 v[132:135], v188, s[16:17]
	global_load_dwordx4 v[128:131], v188, s[16:17] offset:128
	s_waitcnt lgkmcnt(0)
	v_mul_f32_e32 v208, 0x3fb504f3, v219
	v_lshl_add_u64 v[186:187], v[166:167], 0, s[60:61]
	s_ashr_i32 s59, s58, 31
	v_lshl_add_u64 v[186:187], s[58:59], 3, v[186:187]
	v_lshl_add_u64 v[186:187], v[186:187], 0, s[20:21]
	v_add_u32_e32 v246, 0x4000, v164
	v_add_u32_e32 v247, 0x4800, v164
	global_load_dwordx4 v[230:233], v246, s[16:17]
	global_load_dwordx4 v[234:237], v246, s[16:17] offset:128
	global_load_dwordx4 v[238:241], v247, s[16:17]
	global_load_dwordx4 v[242:245], v247, s[16:17] offset:128
	s_waitcnt vmcnt(14)
	v_pk_mul_f32 v[182:183], v[180:181], s[46:47] op_sel_hi:[1,0]
	v_pk_mul_f32 v[184:185], v[178:179], s[46:47] op_sel_hi:[1,0]
	v_pk_mul_f32 v[178:179], v[196:197], s[46:47] op_sel_hi:[1,0]
	v_pk_mul_f32 v[180:181], v[194:195], s[46:47] op_sel_hi:[1,0]
	s_waitcnt vmcnt(13)
	v_lshlrev_b32_e32 v194, 16, v214
	v_and_b32_e32 v195, 0xffff0000, v214
	v_lshlrev_b32_e32 v196, 16, v215
	v_and_b32_e32 v197, 0xffff0000, v215
	v_lshlrev_b32_e32 v207, 16, v216
	v_and_b32_e32 v214, 0xffff0000, v216
	v_lshlrev_b32_e32 v216, 16, v217
	v_and_b32_e32 v217, 0xffff0000, v217
	v_sub_f32_e32 v195, v195, v218
	v_sub_f32_e32 v194, v194, v218
	v_sub_f32_e32 v197, v197, v218
	v_sub_f32_e32 v196, v196, v218
	v_sub_f32_e32 v215, v214, v218
	v_sub_f32_e32 v214, v207, v218
	v_sub_f32_e32 v217, v217, v218
	v_sub_f32_e32 v216, v216, v218
	v_pk_mul_f32 v[196:197], v[196:197], v[208:209] op_sel_hi:[1,0]
	v_pk_mul_f32 v[194:195], v[194:195], v[208:209] op_sel_hi:[1,0]
	v_pk_mul_f32 v[216:217], v[216:217], v[208:209] op_sel_hi:[1,0]
	v_pk_mul_f32 v[214:215], v[214:215], v[208:209] op_sel_hi:[1,0]
	s_waitcnt vmcnt(12)
	v_pk_fma_f32 v[194:195], v[76:77], v[194:195], v[184:185]
	v_pk_fma_f32 v[196:197], v[78:79], v[196:197], v[182:183]
	s_waitcnt vmcnt(11)
	v_pk_fma_f32 v[214:215], v[72:73], v[214:215], v[180:181]
	v_pk_fma_f32 v[216:217], v[74:75], v[216:217], v[178:179]
	v_pk_add_f32 v[196:197], v[222:223], v[196:197]
	v_pk_add_f32 v[194:195], v[220:221], v[194:195]
	v_pk_add_f32 v[218:219], v[226:227], v[216:217]
	v_pk_add_f32 v[216:217], v[224:225], v[214:215]
	v_cvt_pk_bf16_f32 v214, v194, v195
	v_cvt_pk_bf16_f32 v215, v196, v197
	v_and_b32_e32 v208, 64, v206
	v_cvt_pk_bf16_f32 v216, v216, v217
	v_cvt_pk_bf16_f32 v217, v218, v219
	v_lshlrev_b32_e32 v194, 16, v214
	v_and_b32_e32 v196, 0xffff0000, v214
	v_lshlrev_b32_e32 v218, 16, v215
	v_and_b32_e32 v220, 0xffff0000, v215
	v_lshlrev_b32_e32 v222, 16, v216
	v_and_b32_e32 v224, 0xffff0000, v216
	v_lshlrev_b32_e32 v226, 16, v217
	v_and_b32_e32 v228, 0xffff0000, v217
	v_mul_f32_e32 v195, v194, v194
	v_mul_f32_e32 v197, v196, v196
	v_mul_f32_e32 v219, v218, v218
	v_mul_f32_e32 v221, v220, v220
	v_mul_f32_e32 v223, v222, v222
	v_mul_f32_e32 v225, v224, v224
	v_mul_f32_e32 v227, v226, v226
	v_mul_f32_e32 v229, v228, v228
	v_pk_add_f32 v[194:195], v[194:195], v[196:197]
	v_pk_add_f32 v[196:197], v[218:219], v[220:221]
	v_pk_add_f32 v[218:219], v[226:227], v[228:229]
	v_pk_add_f32 v[194:195], v[194:195], v[196:197]
	v_pk_add_f32 v[196:197], v[222:223], v[224:225]
	v_xor_b32_e32 v207, 16, v206
	v_add_u32_e32 v208, 64, v208
	v_pk_add_f32 v[196:197], v[196:197], v[218:219]
	v_cmp_lt_i32_e32 vcc, v207, v208
	v_pk_add_f32 v[194:195], v[194:195], v[196:197]
	v_mov_b32_e32 v196, 0
	v_mov_b32_e32 v197, 0
	v_cndmask_b32_e32 v207, v206, v207, vcc
	v_mov_b32_dpp v196, v194 quad_perm:[1,0,3,2] row_mask:0xf bank_mask:0xf
	v_mov_b32_dpp v197, v195 quad_perm:[1,0,3,2] row_mask:0xf bank_mask:0xf
	v_lshlrev_b32_e32 v207, 2, v207
	v_pk_add_f32 v[194:195], v[194:195], v[196:197]
	ds_bpermute_b32 v196, v207, v194
	ds_bpermute_b32 v197, v207, v195
	v_xor_b32_e32 v218, 32, v206
	v_cmp_lt_i32_e32 vcc, v218, v208
	global_store_dwordx4 v164, v[214:217], s[16:17]
	s_waitcnt lgkmcnt(0)
	v_pk_add_f32 v[194:195], v[194:195], v[196:197]
	v_cndmask_b32_e32 v208, v206, v218, vcc
	v_lshlrev_b32_e32 v208, 2, v208
	ds_bpermute_b32 v196, v208, v194
	ds_bpermute_b32 v197, v208, v195
	s_and_saveexec_b64 s[56:57], s[12:13]
	s_waitcnt lgkmcnt(0)
	v_pk_add_f32 v[194:195], v[194:195], v[196:197]
	global_store_dwordx2 v[186:187], v[194:195], off
; __device__ __forceinline__ u32x4 pack8f(f32x4 a, f32x4 b) { u32x4 w; w.x = cvt_pk_bf16(a[0], a[1]); w.y = cvt_pk_bf16(a[2], a[3]); w.z = cvt_pk_bf16(b[0], b[1]); w.w = cvt_pk_bf16(b[2], b[3]); return w; }
;     __device__ __forceinline__ void operator()(const f32x4 (&acc)[2][2][4][2], const Unit& u, int wr, int wc, int fr, int fq, const EpiCtx& X) const {
;     ...
;             for (int m = 0; m < 4; ++m) {
;                 const int rl = ai * HALF + m * 16; const unsigned off = lo + (unsigned)(rl * 64) * 2u;
;                 const f32x4 o0a = acc[ai][0][m][0], o0b = acc[ai][0][m][1], o1a = acc[ai][1][m][0], o1b = acc[ai][1][m][1];
;                 const f32x4 ra_ = dpp_swap1(odd ? o0a : o1a), rb_ = dpp_swap1(odd ? o0b : o1b);
;                 const f32x4 pa[2] = {odd ? ra_ : o0a, odd ? o1a : ra_}, pb[2] = {odd ? rb_ : o0b, odd ? o1b : rb_};
; #pragma unroll
;                 for (int q = 0; q < 2; ++q) {
;                     const u32x4 w0 = raw[2 * m + q];
;                     const f32x4 r0 = (f32x4){bf_lo(w0.x), bf_hi(w0.x), bf_lo(w0.y), bf_hi(w0.y)}, r1 = (f32x4){bf_lo(w0.z), bf_hi(w0.z), bf_lo(w0.w), bf_hi(w0.w)};
;                     f32x4 y0, y1;
;                     if (RESN) { const f32x2 t = tbl[rl + q]; const float mu = t.x, ra = t.y * ALPHA; y0 = (r0 - mu) * ra * g0 + b0 + pa[q]; y1 = (r1 - mu) * ra * g1 + b1 + pb[q]; }
;                     else { y0 = r0 * ALPHA + pa[q]; y1 = r1 * ALPHA + pb[q]; }
;                     { const u32x4 w = pack8f(y0, y1); *(u32x4*)(xb + off + q * 128) = w;
;                         y0 = (f32x4){bf_lo(w.x), bf_hi(w.x), bf_lo(w.y), bf_hi(w.y)}; y1 = (f32x4){bf_lo(w.z), bf_hi(w.z), bf_lo(w.w), bf_hi(w.w)}; }
;                     float sa = ((y0[0] + y0[1]) + (y0[2] + y0[3])) + ((y1[0] + y1[1]) + (y1[2] + y1[3]));
;                     float sb = ((y0[0] * y0[0] + y0[1] * y0[1]) + (y0[2] * y0[2] + y0[3] * y0[3])) + ((y1[0] * y1[0] + y1[1] * y1[1]) + (y1[2] * y1[2] + y1[3] * y1[3]));
;                     sa += dpp_x1(sa);
;                     sb += dpp_x1(sb);
;                     sa += __shfl_xor(sa, 16); sa += __shfl_xor(sa, 32); sb += __shfl_xor(sb, 16); sb += __shfl_xor(sb, 32);
;                     if (fq == 0 && !odd) ps[(size_t)(rl + q) * 64] = (f32x2){sa, sb};
.LBB0_1699:
	s_or_b64 exec, exec, s[56:57]
	v_cndmask_b32_e64 v125, v125, v193, s[6:7]
	v_cndmask_b32_e64 v124, v124, v189, s[6:7]
	v_cndmask_b32_e64 v126, v126, v191, s[6:7]
	s_waitcnt vmcnt(12)
	v_lshlrev_b32_e32 v189, 16, v152
	v_and_b32_e32 v191, 0xffff0000, v152
	v_lshlrev_b32_e32 v193, 16, v153
	s_waitcnt lgkmcnt(1)
	v_and_b32_e32 v196, 0xffff0000, v153
	ds_read_b64 v[152:153], v201 offset:8
	v_cndmask_b32_e64 v127, v127, v209, s[6:7]
	v_cndmask_b32_e64 v120, v120, v210, s[6:7]
	v_cndmask_b32_e64 v122, v122, v211, s[6:7]
	v_lshlrev_b32_e32 v209, 16, v154
	v_and_b32_e32 v210, 0xffff0000, v154
	v_lshlrev_b32_e32 v211, 16, v155
	v_and_b32_e32 v155, 0xffff0000, v155
	s_waitcnt lgkmcnt(0)
	v_mul_f32_e32 v154, 0x3fb504f3, v153
	v_sub_f32_e32 v195, v191, v152
	v_sub_f32_e32 v194, v189, v152
	v_pk_mul_f32 v[194:195], v[194:195], v[154:155] op_sel_hi:[1,0]
	v_sub_f32_e32 v197, v196, v152
	v_pk_fma_f32 v[194:195], v[76:77], v[194:195], v[184:185]
	v_sub_f32_e32 v196, v193, v152
	v_pk_add_f32 v[124:125], v[124:125], v[194:195]
	v_sub_f32_e32 v195, v210, v152
	v_sub_f32_e32 v194, v209, v152
	v_sub_f32_e32 v153, v155, v152
	v_sub_f32_e32 v152, v211, v152
	v_pk_mul_f32 v[196:197], v[196:197], v[154:155] op_sel_hi:[1,0]
	v_pk_mul_f32 v[152:153], v[152:153], v[154:155] op_sel_hi:[1,0]
	v_pk_mul_f32 v[154:155], v[194:195], v[154:155] op_sel_hi:[1,0]
	v_cndmask_b32_e64 v121, v121, v212, s[6:7]
	v_cndmask_b32_e64 v123, v123, v213, s[6:7]
	v_pk_fma_f32 v[196:197], v[78:79], v[196:197], v[182:183]
	v_pk_fma_f32 v[154:155], v[72:73], v[154:155], v[180:181]
	v_pk_fma_f32 v[152:153], v[74:75], v[152:153], v[178:179]
	v_pk_add_f32 v[126:127], v[126:127], v[196:197]
	v_pk_add_f32 v[122:123], v[122:123], v[152:153]
	v_pk_add_f32 v[120:121], v[120:121], v[154:155]
	v_cvt_pk_bf16_f32 v124, v124, v125
	v_cvt_pk_bf16_f32 v125, v126, v127
	s_nop 0
	v_cvt_pk_bf16_f32 v126, v120, v121
	v_cvt_pk_bf16_f32 v127, v122, v123
	v_lshlrev_b32_e32 v120, 16, v124
	v_and_b32_e32 v122, 0xffff0000, v124
	v_lshlrev_b32_e32 v152, 16, v125
	v_and_b32_e32 v154, 0xffff0000, v125
	v_lshlrev_b32_e32 v194, 16, v126
	v_and_b32_e32 v196, 0xffff0000, v126
	v_lshlrev_b32_e32 v210, 16, v127
	v_and_b32_e32 v212, 0xffff0000, v127
	v_mul_f32_e32 v121, v120, v120
	v_mul_f32_e32 v123, v122, v122
	v_mul_f32_e32 v153, v152, v152
	v_mul_f32_e32 v155, v154, v154
	v_mul_f32_e32 v195, v194, v194
	v_mul_f32_e32 v197, v196, v196
	v_mul_f32_e32 v211, v210, v210
	v_mul_f32_e32 v213, v212, v212
	v_pk_add_f32 v[120:121], v[120:121], v[122:123]
	v_pk_add_f32 v[122:123], v[152:153], v[154:155]
	v_pk_add_f32 v[152:153], v[210:211], v[212:213]
	v_pk_add_f32 v[120:121], v[120:121], v[122:123]
	v_pk_add_f32 v[122:123], v[194:195], v[196:197]
	s_nop 0
	v_pk_add_f32 v[122:123], v[122:123], v[152:153]
	v_lshl_add_u64 v[152:153], s[16:17], 0, v[164:165]
	v_pk_add_f32 v[120:121], v[120:121], v[122:123]
	v_mov_b32_e32 v122, v165
	v_mov_b32_e32 v123, v165
	global_store_dwordx4 v[152:153], v[124:127], off offset:128
	v_mov_b32_dpp v122, v120 quad_perm:[1,0,3,2] row_mask:0xf bank_mask:0xf
	v_mov_b32_dpp v123, v121 quad_perm:[1,0,3,2] row_mask:0xf bank_mask:0xf
	v_pk_add_f32 v[120:121], v[120:121], v[122:123]
	ds_bpermute_b32 v122, v207, v120
	ds_bpermute_b32 v123, v207, v121
	s_waitcnt lgkmcnt(0)
	v_pk_add_f32 v[120:121], v[120:121], v[122:123]
	ds_bpermute_b32 v122, v208, v120
	ds_bpermute_b32 v123, v208, v121
	s_and_saveexec_b64 s[56:57], s[12:13]
	s_waitcnt lgkmcnt(0)
	v_pk_add_f32 v[120:121], v[120:121], v[122:123]
	global_store_dwordx2 v[186:187], v[120:121], off offset:512
.LBB0_1701:
	s_or_b64 exec, exec, s[56:57]
	s_waitcnt lgkmcnt(1)
	v_cndmask_b32_e64 v122, v116, v108, s[6:7]
	v_mov_b32_e32 v120, 0
	v_cndmask_b32_e64 v121, v117, v109, s[6:7]
	s_waitcnt lgkmcnt(0)
	v_cndmask_b32_e64 v123, v118, v110, s[6:7]
	v_mov_b32_dpp v120, v122 quad_perm:[1,0,3,2] row_mask:0xf bank_mask:0xf
	v_mov_b32_e32 v122, 0
	v_cndmask_b32_e64 v124, v119, v111, s[6:7]
	v_cndmask_b32_e64 v126, v112, v104, s[6:7]
	v_mov_b32_dpp v122, v121 quad_perm:[1,0,3,2] row_mask:0xf bank_mask:0xf
	v_mov_b32_e32 v121, 0
	v_cndmask_b32_e64 v125, v113, v105, s[6:7]
	v_cndmask_b32_e64 v127, v114, v106, s[6:7]
	v_mov_b32_dpp v121, v123 quad_perm:[1,0,3,2] row_mask:0xf bank_mask:0xf
	v_mov_b32_e32 v123, 0
	v_cndmask_b32_e64 v152, v115, v107, s[6:7]
	s_waitcnt vmcnt(13)
	v_and_b32_e32 v153, 0xffff0000, v148
	v_mov_b32_dpp v123, v124 quad_perm:[1,0,3,2] row_mask:0xf bank_mask:0xf
	v_mov_b32_e32 v124, 0
	v_lshlrev_b32_e32 v154, 16, v149
	v_and_b32_e32 v155, 0xffff0000, v149
	v_mov_b32_dpp v124, v126 quad_perm:[1,0,3,2] row_mask:0xf bank_mask:0xf
	v_mov_b32_e32 v126, 0
	v_lshlrev_b32_e32 v189, 16, v150
	v_and_b32_e32 v191, 0xffff0000, v150
	v_mov_b32_dpp v126, v125 quad_perm:[1,0,3,2] row_mask:0xf bank_mask:0xf
	v_mov_b32_e32 v125, 0
	v_lshlrev_b32_e32 v193, 16, v151
	v_and_b32_e32 v151, 0xffff0000, v151
	v_mov_b32_dpp v125, v127 quad_perm:[1,0,3,2] row_mask:0xf bank_mask:0xf
	v_mov_b32_e32 v127, 0
	v_cndmask_b32_e64 v117, v122, v117, s[6:7]
	v_cndmask_b32_e64 v116, v120, v116, s[6:7]
	v_mov_b32_dpp v127, v152 quad_perm:[1,0,3,2] row_mask:0xf bank_mask:0xf
	v_lshlrev_b32_e32 v152, 16, v148
	ds_read_b64 v[148:149], v201 offset:128
	v_cndmask_b32_e64 v119, v123, v119, s[6:7]
	v_cndmask_b32_e64 v118, v121, v118, s[6:7]
	v_cndmask_b32_e64 v113, v126, v113, s[6:7]
	v_cndmask_b32_e64 v112, v124, v112, s[6:7]
	s_waitcnt lgkmcnt(0)
; __device__ __forceinline__ u32x4 pack8f(f32x4 a, f32x4 b) { u32x4 w; w.x = cvt_pk_bf16(a[0], a[1]); w.y = cvt_pk_bf16(a[2], a[3]); w.z = cvt_pk_bf16(b[0], b[1]); w.w = cvt_pk_bf16(b[2], b[3]); return w; }
;     __device__ __forceinline__ void operator()(const f32x4 (&acc)[2][2][4][2], const Unit& u, int wr, int wc, int fr, int fq, const EpiCtx& X) const {
;     ...
;             for (int m = 0; m < 4; ++m) {
;                 const int rl = ai * HALF + m * 16; const unsigned off = lo + (unsigned)(rl * 64) * 2u;
;                 const f32x4 o0a = acc[ai][0][m][0], o0b = acc[ai][0][m][1], o1a = acc[ai][1][m][0], o1b = acc[ai][1][m][1];
;                 const f32x4 ra_ = dpp_swap1(odd ? o0a : o1a), rb_ = dpp_swap1(odd ? o0b : o1b);
;                 const f32x4 pa[2] = {odd ? ra_ : o0a, odd ? o1a : ra_}, pb[2] = {odd ? rb_ : o0b, odd ? o1b : rb_};
; #pragma unroll
;                 for (int q = 0; q < 2; ++q) {
;                     const u32x4 w0 = raw[2 * m + q];
;                     const f32x4 r0 = (f32x4){bf_lo(w0.x), bf_hi(w0.x), bf_lo(w0.y), bf_hi(w0.y)}, r1 = (f32x4){bf_lo(w0.z), bf_hi(w0.z), bf_lo(w0.w), bf_hi(w0.w)};
;                     f32x4 y0, y1;
;                     if (RESN) { const f32x2 t = tbl[rl + q]; const float mu = t.x, ra = t.y * ALPHA; y0 = (r0 - mu) * ra * g0 + b0 + pa[q]; y1 = (r1 - mu) * ra * g1 + b1 + pb[q]; }
;                     else { y0 = r0 * ALPHA + pa[q]; y1 = r1 * ALPHA + pb[q]; }
;                     { const u32x4 w = pack8f(y0, y1); *(u32x4*)(xb + off + q * 128) = w;
;                         y0 = (f32x4){bf_lo(w.x), bf_hi(w.x), bf_lo(w.y), bf_hi(w.y)}; y1 = (f32x4){bf_lo(w.z), bf_hi(w.z), bf_lo(w.w), bf_hi(w.w)}; }
;                     float sa = ((y0[0] + y0[1]) + (y0[2] + y0[3])) + ((y1[0] + y1[1]) + (y1[2] + y1[3]));
;                     float sb = ((y0[0] * y0[0] + y0[1] * y0[1]) + (y0[2] * y0[2] + y0[3] * y0[3])) + ((y1[0] * y1[0] + y1[1] * y1[1]) + (y1[2] * y1[2] + y1[3] * y1[3]));
;                     sa += dpp_x1(sa);
;                     sb += dpp_x1(sb);
;                     sa += __shfl_xor(sa, 16); sa += __shfl_xor(sa, 32); sb += __shfl_xor(sb, 16); sb += __shfl_xor(sb, 32);
;                     if (fq == 0 && !odd) ps[(size_t)(rl + q) * 64] = (f32x2){sa, sb};
	v_mul_f32_e32 v150, 0x3fb504f3, v149
	v_sub_f32_e32 v153, v153, v148
	v_sub_f32_e32 v152, v152, v148
	v_pk_mul_f32 v[152:153], v[152:153], v[150:151] op_sel_hi:[1,0]
	v_sub_f32_e32 v155, v155, v148
	v_pk_fma_f32 v[152:153], v[76:77], v[152:153], v[184:185]
	v_sub_f32_e32 v154, v154, v148
	v_pk_add_f32 v[116:117], v[116:117], v[152:153]
	v_sub_f32_e32 v153, v191, v148
	v_sub_f32_e32 v152, v189, v148
	v_sub_f32_e32 v149, v151, v148
	v_sub_f32_e32 v148, v193, v148
	v_pk_mul_f32 v[154:155], v[154:155], v[150:151] op_sel_hi:[1,0]
	v_pk_mul_f32 v[148:149], v[148:149], v[150:151] op_sel_hi:[1,0]
	v_pk_mul_f32 v[150:151], v[152:153], v[150:151] op_sel_hi:[1,0]
	v_cndmask_b32_e64 v115, v127, v115, s[6:7]
	v_cndmask_b32_e64 v114, v125, v114, s[6:7]
	v_pk_fma_f32 v[154:155], v[78:79], v[154:155], v[182:183]
	v_pk_fma_f32 v[150:151], v[72:73], v[150:151], v[180:181]
	v_pk_fma_f32 v[148:149], v[74:75], v[148:149], v[178:179]
	v_pk_add_f32 v[118:119], v[118:119], v[154:155]
	v_pk_add_f32 v[114:115], v[114:115], v[148:149]
	v_pk_add_f32 v[112:113], v[112:113], v[150:151]
	v_cvt_pk_bf16_f32 v148, v116, v117
	v_cvt_pk_bf16_f32 v149, v118, v119
	v_mov_b32_e32 v193, v165
	v_cvt_pk_bf16_f32 v150, v112, v113
	v_cvt_pk_bf16_f32 v151, v114, v115
	v_lshlrev_b32_e32 v112, 16, v148
	v_and_b32_e32 v114, 0xffff0000, v148
	v_lshlrev_b32_e32 v116, 16, v149
	v_and_b32_e32 v118, 0xffff0000, v149
	v_lshlrev_b32_e32 v152, 16, v150
	v_and_b32_e32 v154, 0xffff0000, v150
	v_lshlrev_b32_e32 v194, 16, v151
	v_and_b32_e32 v196, 0xffff0000, v151
	v_mul_f32_e32 v113, v112, v112
	v_mul_f32_e32 v115, v114, v114
	v_mul_f32_e32 v117, v116, v116
	v_mul_f32_e32 v119, v118, v118
	v_mul_f32_e32 v153, v152, v152
	v_mul_f32_e32 v155, v154, v154
	v_mul_f32_e32 v195, v194, v194
	v_mul_f32_e32 v197, v196, v196
	v_pk_add_f32 v[112:113], v[112:113], v[114:115]
	v_pk_add_f32 v[114:115], v[116:117], v[118:119]
	v_pk_add_f32 v[116:117], v[194:195], v[196:197]
	v_pk_add_f32 v[112:113], v[112:113], v[114:115]
	v_pk_add_f32 v[114:115], v[152:153], v[154:155]
	s_nop 0
	v_pk_add_f32 v[114:115], v[114:115], v[116:117]
	s_nop 0
	v_pk_add_f32 v[112:113], v[112:113], v[114:115]
	v_mov_b32_e32 v114, v165
	v_mov_b32_e32 v115, v165
	s_nop 0
	v_mov_b32_dpp v114, v112 quad_perm:[1,0,3,2] row_mask:0xf bank_mask:0xf
	v_mov_b32_dpp v115, v113 quad_perm:[1,0,3,2] row_mask:0xf bank_mask:0xf
	v_pk_add_f32 v[112:113], v[112:113], v[114:115]
	ds_bpermute_b32 v114, v207, v112
	ds_bpermute_b32 v115, v207, v113
	s_waitcnt lgkmcnt(0)
	v_pk_add_f32 v[114:115], v[112:113], v[114:115]
	ds_bpermute_b32 v116, v208, v114
	ds_bpermute_b32 v117, v208, v115
	v_lshl_add_u64 v[112:113], s[16:17], 0, v[192:193]
	global_store_dwordx4 v[112:113], v[148:151], off
	s_and_saveexec_b64 s[56:57], s[12:13]
	s_waitcnt lgkmcnt(0)
	v_pk_add_f32 v[114:115], v[114:115], v[116:117]
	v_add_co_u32_e32 v116, vcc, 0x2000, v186
	s_nop 1
	v_addc_co_u32_e32 v117, vcc, 0, v187, vcc
	global_store_dwordx2 v[116:117], v[114:115], off
.LBB0_1703:
	s_or_b64 exec, exec, s[56:57]
	ds_read_b64 v[114:115], v201 offset:136
	s_waitcnt lgkmcnt(1)
	s_waitcnt vmcnt(14)
	v_lshlrev_b32_e32 v117, 16, v144
	v_and_b32_e32 v118, 0xffff0000, v144
	v_cndmask_b32_e64 v109, v109, v122, s[6:7]
	v_cndmask_b32_e64 v108, v108, v120, s[6:7]
	s_waitcnt lgkmcnt(0)
	v_mul_f32_e32 v116, 0x3fb504f3, v115
	v_sub_f32_e32 v119, v118, v114
	v_sub_f32_e32 v118, v117, v114
	v_pk_mul_f32 v[118:119], v[118:119], v[116:117] op_sel_hi:[1,0]
	v_cndmask_b32_e64 v111, v111, v123, s[6:7]
	v_cndmask_b32_e64 v110, v110, v121, s[6:7]
	v_cndmask_b32_e64 v104, v104, v124, s[6:7]
	v_cndmask_b32_e64 v106, v106, v125, s[6:7]
	v_lshlrev_b32_e32 v120, 16, v145
	v_and_b32_e32 v121, 0xffff0000, v145
	v_lshlrev_b32_e32 v122, 16, v146
	v_and_b32_e32 v123, 0xffff0000, v146
	v_lshlrev_b32_e32 v124, 16, v147
	v_and_b32_e32 v125, 0xffff0000, v147
	v_pk_fma_f32 v[118:119], v[76:77], v[118:119], v[184:185]
	v_sub_f32_e32 v121, v121, v114
	v_sub_f32_e32 v120, v120, v114
	v_pk_add_f32 v[108:109], v[108:109], v[118:119]
	v_sub_f32_e32 v119, v123, v114
	v_sub_f32_e32 v118, v122, v114
	v_sub_f32_e32 v115, v125, v114
	v_sub_f32_e32 v114, v124, v114
	v_pk_mul_f32 v[120:121], v[120:121], v[116:117] op_sel_hi:[1,0]
	v_pk_mul_f32 v[114:115], v[114:115], v[116:117] op_sel_hi:[1,0]
	v_pk_mul_f32 v[116:117], v[118:119], v[116:117] op_sel_hi:[1,0]
	v_cndmask_b32_e64 v105, v105, v126, s[6:7]
	v_cndmask_b32_e64 v107, v107, v127, s[6:7]
	v_pk_fma_f32 v[120:121], v[78:79], v[120:121], v[182:183]
	v_pk_fma_f32 v[116:117], v[72:73], v[116:117], v[180:181]
	v_pk_fma_f32 v[114:115], v[74:75], v[114:115], v[178:179]
	v_pk_add_f32 v[110:111], v[110:111], v[120:121]
	v_pk_add_f32 v[106:107], v[106:107], v[114:115]
	v_pk_add_f32 v[104:105], v[104:105], v[116:117]
	v_cvt_pk_bf16_f32 v108, v108, v109
	v_cvt_pk_bf16_f32 v109, v110, v111
	s_nop 0
	v_cvt_pk_bf16_f32 v110, v104, v105
	v_cvt_pk_bf16_f32 v111, v106, v107
	v_lshlrev_b32_e32 v104, 16, v108
	v_and_b32_e32 v106, 0xffff0000, v108
	v_lshlrev_b32_e32 v114, 16, v109
	v_and_b32_e32 v116, 0xffff0000, v109
	v_lshlrev_b32_e32 v118, 16, v110
	v_and_b32_e32 v120, 0xffff0000, v110
	v_lshlrev_b32_e32 v122, 16, v111
	v_and_b32_e32 v124, 0xffff0000, v111
	v_mul_f32_e32 v105, v104, v104
	v_mul_f32_e32 v107, v106, v106
	v_mul_f32_e32 v115, v114, v114
	v_mul_f32_e32 v117, v116, v116
	v_mul_f32_e32 v119, v118, v118
	v_mul_f32_e32 v121, v120, v120
	v_mul_f32_e32 v123, v122, v122
	v_mul_f32_e32 v125, v124, v124
	v_pk_add_f32 v[104:105], v[104:105], v[106:107]
	v_pk_add_f32 v[106:107], v[114:115], v[116:117]
	v_pk_add_f32 v[114:115], v[122:123], v[124:125]
	v_pk_add_f32 v[104:105], v[104:105], v[106:107]
	v_pk_add_f32 v[106:107], v[118:119], v[120:121]
	global_store_dwordx4 v[112:113], v[108:111], off offset:128
	v_pk_add_f32 v[106:107], v[106:107], v[114:115]
	s_nop 0
	v_pk_add_f32 v[104:105], v[104:105], v[106:107]
	v_mov_b32_e32 v106, v165
	v_mov_b32_e32 v107, v165
	s_nop 0
	v_mov_b32_dpp v106, v104 quad_perm:[1,0,3,2] row_mask:0xf bank_mask:0xf
	v_mov_b32_dpp v107, v105 quad_perm:[1,0,3,2] row_mask:0xf bank_mask:0xf
	v_pk_add_f32 v[104:105], v[104:105], v[106:107]
	ds_bpermute_b32 v106, v207, v104
	ds_bpermute_b32 v107, v207, v105
	s_waitcnt lgkmcnt(0)
	v_pk_add_f32 v[104:105], v[104:105], v[106:107]
	ds_bpermute_b32 v106, v208, v104
	ds_bpermute_b32 v107, v208, v105
	s_and_saveexec_b64 s[56:57], s[12:13]
	s_waitcnt lgkmcnt(0)
	v_pk_add_f32 v[104:105], v[104:105], v[106:107]
	v_add_co_u32_e32 v106, vcc, 0x2000, v186
	s_nop 1
	v_addc_co_u32_e32 v107, vcc, 0, v187, vcc
	global_store_dwordx2 v[106:107], v[104:105], off offset:512
; __device__ __forceinline__ u32x4 pack8f(f32x4 a, f32x4 b) { u32x4 w; w.x = cvt_pk_bf16(a[0], a[1]); w.y = cvt_pk_bf16(a[2], a[3]); w.z = cvt_pk_bf16(b[0], b[1]); w.w = cvt_pk_bf16(b[2], b[3]); return w; }
;     __device__ __forceinline__ void operator()(const f32x4 (&acc)[2][2][4][2], const Unit& u, int wr, int wc, int fr, int fq, const EpiCtx& X) const {
;     ...
;             for (int m = 0; m < 4; ++m) {
;                 const int rl = ai * HALF + m * 16; const unsigned off = lo + (unsigned)(rl * 64) * 2u;
;                 const f32x4 o0a = acc[ai][0][m][0], o0b = acc[ai][0][m][1], o1a = acc[ai][1][m][0], o1b = acc[ai][1][m][1];
;                 const f32x4 ra_ = dpp_swap1(odd ? o0a : o1a), rb_ = dpp_swap1(odd ? o0b : o1b);
;                 const f32x4 pa[2] = {odd ? ra_ : o0a, odd ? o1a : ra_}, pb[2] = {odd ? rb_ : o0b, odd ? o1b : rb_};
; #pragma unroll
;                 for (int q = 0; q < 2; ++q) {
;                     const u32x4 w0 = raw[2 * m + q];
;                     const f32x4 r0 = (f32x4){bf_lo(w0.x), bf_hi(w0.x), bf_lo(w0.y), bf_hi(w0.y)}, r1 = (f32x4){bf_lo(w0.z), bf_hi(w0.z), bf_lo(w0.w), bf_hi(w0.w)};
;                     f32x4 y0, y1;
;                     if (RESN) { const f32x2 t = tbl[rl + q]; const float mu = t.x, ra = t.y * ALPHA; y0 = (r0 - mu) * ra * g0 + b0 + pa[q]; y1 = (r1 - mu) * ra * g1 + b1 + pb[q]; }
;                     else { y0 = r0 * ALPHA + pa[q]; y1 = r1 * ALPHA + pb[q]; }
;                     { const u32x4 w = pack8f(y0, y1); *(u32x4*)(xb + off + q * 128) = w;
;                         y0 = (f32x4){bf_lo(w.x), bf_hi(w.x), bf_lo(w.y), bf_hi(w.y)}; y1 = (f32x4){bf_lo(w.z), bf_hi(w.z), bf_lo(w.w), bf_hi(w.w)}; }
;                     float sa = ((y0[0] + y0[1]) + (y0[2] + y0[3])) + ((y1[0] + y1[1]) + (y1[2] + y1[3]));
;                     float sb = ((y0[0] * y0[0] + y0[1] * y0[1]) + (y0[2] * y0[2] + y0[3] * y0[3])) + ((y1[0] * y1[0] + y1[1] * y1[1]) + (y1[2] * y1[2] + y1[3] * y1[3]));
;                     sa += dpp_x1(sa);
;                     sb += dpp_x1(sb);
;                     sa += __shfl_xor(sa, 16); sa += __shfl_xor(sa, 32); sb += __shfl_xor(sb, 16); sb += __shfl_xor(sb, 32);
;                     if (fq == 0 && !odd) ps[(size_t)(rl + q) * 64] = (f32x2){sa, sb};
.LBB0_1705:
	s_or_b64 exec, exec, s[56:57]
	s_waitcnt lgkmcnt(1)
	v_cndmask_b32_e64 v106, v100, v92, s[6:7]
	v_mov_b32_e32 v104, 0
	v_cndmask_b32_e64 v105, v101, v93, s[6:7]
	s_waitcnt lgkmcnt(0)
	v_cndmask_b32_e64 v107, v102, v94, s[6:7]
	v_mov_b32_dpp v104, v106 quad_perm:[1,0,3,2] row_mask:0xf bank_mask:0xf
	v_mov_b32_e32 v106, 0
	v_cndmask_b32_e64 v108, v103, v95, s[6:7]
	v_cndmask_b32_e64 v110, v96, v88, s[6:7]
	v_mov_b32_dpp v106, v105 quad_perm:[1,0,3,2] row_mask:0xf bank_mask:0xf
	v_mov_b32_e32 v105, 0
	v_cndmask_b32_e64 v109, v97, v89, s[6:7]
	v_cndmask_b32_e64 v111, v98, v90, s[6:7]
	v_mov_b32_dpp v105, v107 quad_perm:[1,0,3,2] row_mask:0xf bank_mask:0xf
	v_mov_b32_e32 v107, 0
	v_cndmask_b32_e64 v112, v99, v91, s[6:7]
	s_waitcnt vmcnt(15)
	v_lshlrev_b32_e32 v115, 16, v140
	v_mov_b32_dpp v107, v108 quad_perm:[1,0,3,2] row_mask:0xf bank_mask:0xf
	v_mov_b32_e32 v108, 0
	v_and_b32_e32 v116, 0xffff0000, v140
	v_cndmask_b32_e64 v101, v106, v101, s[6:7]
	v_mov_b32_dpp v108, v110 quad_perm:[1,0,3,2] row_mask:0xf bank_mask:0xf
	v_mov_b32_e32 v110, 0
	v_cndmask_b32_e64 v100, v104, v100, s[6:7]
	v_lshlrev_b32_e32 v118, 16, v141
	v_mov_b32_dpp v110, v109 quad_perm:[1,0,3,2] row_mask:0xf bank_mask:0xf
	v_mov_b32_e32 v109, 0
	v_and_b32_e32 v119, 0xffff0000, v141
	v_lshlrev_b32_e32 v120, 16, v142
	v_mov_b32_dpp v109, v111 quad_perm:[1,0,3,2] row_mask:0xf bank_mask:0xf
	v_mov_b32_e32 v111, 0
	v_and_b32_e32 v121, 0xffff0000, v142
	v_lshlrev_b32_e32 v122, 16, v143
	v_mov_b32_dpp v111, v112 quad_perm:[1,0,3,2] row_mask:0xf bank_mask:0xf
	ds_read_b64 v[112:113], v201 offset:256
	v_and_b32_e32 v123, 0xffff0000, v143
	v_cndmask_b32_e64 v103, v107, v103, s[6:7]
	v_cndmask_b32_e64 v102, v105, v102, s[6:7]
	v_cndmask_b32_e64 v97, v110, v97, s[6:7]
	s_waitcnt lgkmcnt(0)
	v_mul_f32_e32 v114, 0x3fb504f3, v113
	v_sub_f32_e32 v117, v116, v112
	v_sub_f32_e32 v116, v115, v112
	v_pk_mul_f32 v[116:117], v[116:117], v[114:115] op_sel_hi:[1,0]
	v_sub_f32_e32 v119, v119, v112
	v_pk_fma_f32 v[116:117], v[76:77], v[116:117], v[184:185]
	v_sub_f32_e32 v118, v118, v112
	v_pk_add_f32 v[100:101], v[100:101], v[116:117]
	v_sub_f32_e32 v117, v121, v112
	v_sub_f32_e32 v116, v120, v112
	v_sub_f32_e32 v113, v123, v112
	v_sub_f32_e32 v112, v122, v112
	v_pk_mul_f32 v[118:119], v[118:119], v[114:115] op_sel_hi:[1,0]
	v_pk_mul_f32 v[112:113], v[112:113], v[114:115] op_sel_hi:[1,0]
	v_pk_mul_f32 v[114:115], v[116:117], v[114:115] op_sel_hi:[1,0]
	v_cndmask_b32_e64 v96, v108, v96, s[6:7]
	v_cndmask_b32_e64 v99, v111, v99, s[6:7]
	v_cndmask_b32_e64 v98, v109, v98, s[6:7]
	v_pk_fma_f32 v[118:119], v[78:79], v[118:119], v[182:183]
	v_pk_fma_f32 v[114:115], v[72:73], v[114:115], v[180:181]
	v_pk_fma_f32 v[112:113], v[74:75], v[112:113], v[178:179]
	v_pk_add_f32 v[102:103], v[102:103], v[118:119]
	v_pk_add_f32 v[98:99], v[98:99], v[112:113]
	v_pk_add_f32 v[96:97], v[96:97], v[114:115]
	v_cvt_pk_bf16_f32 v112, v100, v101
	v_cvt_pk_bf16_f32 v113, v102, v103
	v_mov_b32_e32 v191, v165
	v_cvt_pk_bf16_f32 v114, v96, v97
	v_cvt_pk_bf16_f32 v115, v98, v99
	v_lshlrev_b32_e32 v96, 16, v112
	v_and_b32_e32 v98, 0xffff0000, v112
	v_lshlrev_b32_e32 v100, 16, v113
	v_and_b32_e32 v102, 0xffff0000, v113
	v_lshlrev_b32_e32 v116, 16, v114
	v_and_b32_e32 v118, 0xffff0000, v114
	v_lshlrev_b32_e32 v120, 16, v115
	v_and_b32_e32 v122, 0xffff0000, v115
	v_mul_f32_e32 v97, v96, v96
	v_mul_f32_e32 v99, v98, v98
	v_mul_f32_e32 v101, v100, v100
	v_mul_f32_e32 v103, v102, v102
	v_mul_f32_e32 v117, v116, v116
	v_mul_f32_e32 v119, v118, v118
	v_mul_f32_e32 v121, v120, v120
	v_mul_f32_e32 v123, v122, v122
	v_pk_add_f32 v[96:97], v[96:97], v[98:99]
	v_pk_add_f32 v[98:99], v[100:101], v[102:103]
	v_pk_add_f32 v[100:101], v[120:121], v[122:123]
	v_pk_add_f32 v[96:97], v[96:97], v[98:99]
	v_pk_add_f32 v[98:99], v[116:117], v[118:119]
	s_nop 0
	v_pk_add_f32 v[98:99], v[98:99], v[100:101]
	s_nop 0
	v_pk_add_f32 v[96:97], v[96:97], v[98:99]
	v_mov_b32_e32 v98, v165
	v_mov_b32_e32 v99, v165
	s_nop 0
	v_mov_b32_dpp v98, v96 quad_perm:[1,0,3,2] row_mask:0xf bank_mask:0xf
	v_mov_b32_dpp v99, v97 quad_perm:[1,0,3,2] row_mask:0xf bank_mask:0xf
	v_pk_add_f32 v[96:97], v[96:97], v[98:99]
	ds_bpermute_b32 v98, v207, v96
	ds_bpermute_b32 v99, v207, v97
	s_waitcnt lgkmcnt(0)
	v_pk_add_f32 v[98:99], v[96:97], v[98:99]
	ds_bpermute_b32 v100, v208, v98
	ds_bpermute_b32 v101, v208, v99
	v_lshl_add_u64 v[96:97], s[16:17], 0, v[190:191]
	global_store_dwordx4 v[96:97], v[112:115], off
	s_and_saveexec_b64 s[56:57], s[12:13]
	s_waitcnt lgkmcnt(0)
	v_pk_add_f32 v[98:99], v[98:99], v[100:101]
	v_add_co_u32_e32 v100, vcc, 0x4000, v186
	s_nop 1
	v_addc_co_u32_e32 v101, vcc, 0, v187, vcc
	global_store_dwordx2 v[100:101], v[98:99], off
; __device__ __forceinline__ u32x4 pack8f(f32x4 a, f32x4 b) { u32x4 w; w.x = cvt_pk_bf16(a[0], a[1]); w.y = cvt_pk_bf16(a[2], a[3]); w.z = cvt_pk_bf16(b[0], b[1]); w.w = cvt_pk_bf16(b[2], b[3]); return w; }
;     __device__ __forceinline__ void operator()(const f32x4 (&acc)[2][2][4][2], const Unit& u, int wr, int wc, int fr, int fq, const EpiCtx& X) const {
;     ...
;             for (int m = 0; m < 4; ++m) {
;                 const int rl = ai * HALF + m * 16; const unsigned off = lo + (unsigned)(rl * 64) * 2u;
;                 const f32x4 o0a = acc[ai][0][m][0], o0b = acc[ai][0][m][1], o1a = acc[ai][1][m][0], o1b = acc[ai][1][m][1];
;                 const f32x4 ra_ = dpp_swap1(odd ? o0a : o1a), rb_ = dpp_swap1(odd ? o0b : o1b);
;                 const f32x4 pa[2] = {odd ? ra_ : o0a, odd ? o1a : ra_}, pb[2] = {odd ? rb_ : o0b, odd ? o1b : rb_};
; #pragma unroll
;                 for (int q = 0; q < 2; ++q) {
;                     const u32x4 w0 = raw[2 * m + q];
;                     const f32x4 r0 = (f32x4){bf_lo(w0.x), bf_hi(w0.x), bf_lo(w0.y), bf_hi(w0.y)}, r1 = (f32x4){bf_lo(w0.z), bf_hi(w0.z), bf_lo(w0.w), bf_hi(w0.w)};
;                     f32x4 y0, y1;
;                     if (RESN) { const f32x2 t = tbl[rl + q]; const float mu = t.x, ra = t.y * ALPHA; y0 = (r0 - mu) * ra * g0 + b0 + pa[q]; y1 = (r1 - mu) * ra * g1 + b1 + pb[q]; }
;                     else { y0 = r0 * ALPHA + pa[q]; y1 = r1 * ALPHA + pb[q]; }
;                     { const u32x4 w = pack8f(y0, y1); *(u32x4*)(xb + off + q * 128) = w;
;                         y0 = (f32x4){bf_lo(w.x), bf_hi(w.x), bf_lo(w.y), bf_hi(w.y)}; y1 = (f32x4){bf_lo(w.z), bf_hi(w.z), bf_lo(w.w), bf_hi(w.w)}; }
;                     float sa = ((y0[0] + y0[1]) + (y0[2] + y0[3])) + ((y1[0] + y1[1]) + (y1[2] + y1[3]));
;                     float sb = ((y0[0] * y0[0] + y0[1] * y0[1]) + (y0[2] * y0[2] + y0[3] * y0[3])) + ((y1[0] * y1[0] + y1[1] * y1[1]) + (y1[2] * y1[2] + y1[3] * y1[3]));
;                     sa += dpp_x1(sa);
;                     sb += dpp_x1(sb);
;                     sa += __shfl_xor(sa, 16); sa += __shfl_xor(sa, 32); sb += __shfl_xor(sb, 16); sb += __shfl_xor(sb, 32);
;                     if (fq == 0 && !odd) ps[(size_t)(rl + q) * 64] = (f32x2){sa, sb};
.LBB0_1707:
	s_or_b64 exec, exec, s[56:57]
	ds_read_b64 v[98:99], v201 offset:264
	s_waitcnt lgkmcnt(1)
	s_waitcnt vmcnt(16)
	v_lshlrev_b32_e32 v101, 16, v136
	v_and_b32_e32 v102, 0xffff0000, v136
	v_cndmask_b32_e64 v93, v93, v106, s[6:7]
	v_cndmask_b32_e64 v92, v92, v104, s[6:7]
	s_waitcnt lgkmcnt(0)
	v_mul_f32_e32 v100, 0x3fb504f3, v99
	v_sub_f32_e32 v103, v102, v98
	v_sub_f32_e32 v102, v101, v98
	v_pk_mul_f32 v[102:103], v[102:103], v[100:101] op_sel_hi:[1,0]
	v_cndmask_b32_e64 v95, v95, v107, s[6:7]
	v_cndmask_b32_e64 v94, v94, v105, s[6:7]
	v_cndmask_b32_e64 v88, v88, v108, s[6:7]
	v_cndmask_b32_e64 v90, v90, v109, s[6:7]
	v_lshlrev_b32_e32 v104, 16, v137
	v_and_b32_e32 v105, 0xffff0000, v137
	v_lshlrev_b32_e32 v106, 16, v138
	v_and_b32_e32 v107, 0xffff0000, v138
	v_lshlrev_b32_e32 v108, 16, v139
	v_and_b32_e32 v109, 0xffff0000, v139
	v_pk_fma_f32 v[102:103], v[76:77], v[102:103], v[184:185]
	v_sub_f32_e32 v105, v105, v98
	v_sub_f32_e32 v104, v104, v98
	v_pk_add_f32 v[92:93], v[92:93], v[102:103]
	v_sub_f32_e32 v103, v107, v98
	v_sub_f32_e32 v102, v106, v98
	v_sub_f32_e32 v99, v109, v98
	v_sub_f32_e32 v98, v108, v98
	v_pk_mul_f32 v[104:105], v[104:105], v[100:101] op_sel_hi:[1,0]
	v_pk_mul_f32 v[98:99], v[98:99], v[100:101] op_sel_hi:[1,0]
	v_pk_mul_f32 v[100:101], v[102:103], v[100:101] op_sel_hi:[1,0]
	v_cndmask_b32_e64 v89, v89, v110, s[6:7]
	v_cndmask_b32_e64 v91, v91, v111, s[6:7]
	v_pk_fma_f32 v[104:105], v[78:79], v[104:105], v[182:183]
	v_pk_fma_f32 v[100:101], v[72:73], v[100:101], v[180:181]
	v_pk_fma_f32 v[98:99], v[74:75], v[98:99], v[178:179]
	v_pk_add_f32 v[94:95], v[94:95], v[104:105]
	v_pk_add_f32 v[90:91], v[90:91], v[98:99]
	v_pk_add_f32 v[88:89], v[88:89], v[100:101]
	v_cvt_pk_bf16_f32 v92, v92, v93
	v_cvt_pk_bf16_f32 v93, v94, v95
	s_nop 0
	v_cvt_pk_bf16_f32 v94, v88, v89
	v_cvt_pk_bf16_f32 v95, v90, v91
	v_lshlrev_b32_e32 v88, 16, v92
	v_and_b32_e32 v90, 0xffff0000, v92
	v_lshlrev_b32_e32 v98, 16, v93
	v_and_b32_e32 v100, 0xffff0000, v93
	v_lshlrev_b32_e32 v102, 16, v94
	v_and_b32_e32 v104, 0xffff0000, v94
	v_lshlrev_b32_e32 v106, 16, v95
	v_and_b32_e32 v108, 0xffff0000, v95
	v_mul_f32_e32 v89, v88, v88
	v_mul_f32_e32 v91, v90, v90
	v_mul_f32_e32 v99, v98, v98
	v_mul_f32_e32 v101, v100, v100
	v_mul_f32_e32 v103, v102, v102
	v_mul_f32_e32 v105, v104, v104
	v_mul_f32_e32 v107, v106, v106
	v_mul_f32_e32 v109, v108, v108
	v_pk_add_f32 v[88:89], v[88:89], v[90:91]
	v_pk_add_f32 v[90:91], v[98:99], v[100:101]
	v_pk_add_f32 v[98:99], v[106:107], v[108:109]
	v_pk_add_f32 v[88:89], v[88:89], v[90:91]
	v_pk_add_f32 v[90:91], v[102:103], v[104:105]
	global_store_dwordx4 v[96:97], v[92:95], off offset:128
	v_pk_add_f32 v[90:91], v[90:91], v[98:99]
	s_nop 0
	v_pk_add_f32 v[88:89], v[88:89], v[90:91]
	v_mov_b32_e32 v90, v165
	v_mov_b32_e32 v91, v165
	s_nop 0
	v_mov_b32_dpp v90, v88 quad_perm:[1,0,3,2] row_mask:0xf bank_mask:0xf
	v_mov_b32_dpp v91, v89 quad_perm:[1,0,3,2] row_mask:0xf bank_mask:0xf
	v_pk_add_f32 v[88:89], v[88:89], v[90:91]
	ds_bpermute_b32 v90, v207, v88
	ds_bpermute_b32 v91, v207, v89
	s_waitcnt lgkmcnt(0)
	v_pk_add_f32 v[88:89], v[88:89], v[90:91]
	ds_bpermute_b32 v90, v208, v88
	ds_bpermute_b32 v91, v208, v89
	s_and_saveexec_b64 s[56:57], s[12:13]
	s_waitcnt lgkmcnt(0)
	v_pk_add_f32 v[88:89], v[88:89], v[90:91]
	v_add_co_u32_e32 v90, vcc, 0x4000, v186
	s_nop 1
	v_addc_co_u32_e32 v91, vcc, 0, v187, vcc
	global_store_dwordx2 v[90:91], v[88:89], off offset:512
.LBB0_1709:
	s_or_b64 exec, exec, s[56:57]
	s_waitcnt lgkmcnt(1)
	v_cndmask_b32_e64 v90, v84, v68, s[6:7]
	v_mov_b32_e32 v88, 0
	v_cndmask_b32_e64 v89, v85, v69, s[6:7]
	s_waitcnt lgkmcnt(0)
	v_cndmask_b32_e64 v91, v86, v70, s[6:7]
	v_mov_b32_dpp v88, v90 quad_perm:[1,0,3,2] row_mask:0xf bank_mask:0xf
	v_mov_b32_e32 v90, 0
	v_cndmask_b32_e64 v92, v87, v71, s[6:7]
	v_cndmask_b32_e64 v94, v80, v64, s[6:7]
	v_mov_b32_dpp v90, v89 quad_perm:[1,0,3,2] row_mask:0xf bank_mask:0xf
	v_mov_b32_e32 v89, 0
	v_cndmask_b32_e64 v93, v81, v65, s[6:7]
	v_cndmask_b32_e64 v95, v82, v66, s[6:7]
	v_mov_b32_dpp v89, v91 quad_perm:[1,0,3,2] row_mask:0xf bank_mask:0xf
	v_mov_b32_e32 v91, 0
	v_cndmask_b32_e64 v96, v83, v67, s[6:7]
	s_waitcnt vmcnt(17)
	v_lshlrev_b32_e32 v99, 16, v132
	v_mov_b32_dpp v91, v92 quad_perm:[1,0,3,2] row_mask:0xf bank_mask:0xf
	v_mov_b32_e32 v92, 0
	v_and_b32_e32 v100, 0xffff0000, v132
	v_cndmask_b32_e64 v85, v90, v85, s[6:7]
	v_mov_b32_dpp v92, v94 quad_perm:[1,0,3,2] row_mask:0xf bank_mask:0xf
	v_mov_b32_e32 v94, 0
	v_cndmask_b32_e64 v84, v88, v84, s[6:7]
	v_lshlrev_b32_e32 v102, 16, v133
	v_mov_b32_dpp v94, v93 quad_perm:[1,0,3,2] row_mask:0xf bank_mask:0xf
	v_mov_b32_e32 v93, 0
	v_and_b32_e32 v103, 0xffff0000, v133
	v_lshlrev_b32_e32 v104, 16, v134
	v_mov_b32_dpp v93, v95 quad_perm:[1,0,3,2] row_mask:0xf bank_mask:0xf
	v_mov_b32_e32 v95, 0
	v_and_b32_e32 v105, 0xffff0000, v134
	v_lshlrev_b32_e32 v106, 16, v135
	v_mov_b32_dpp v95, v96 quad_perm:[1,0,3,2] row_mask:0xf bank_mask:0xf
	ds_read_b64 v[96:97], v201 offset:384
	v_and_b32_e32 v107, 0xffff0000, v135
	v_cndmask_b32_e64 v87, v91, v87, s[6:7]
	v_cndmask_b32_e64 v86, v89, v86, s[6:7]
	v_cndmask_b32_e64 v81, v94, v81, s[6:7]
	s_waitcnt lgkmcnt(0)
; __device__ __forceinline__ u32x4 pack8f(f32x4 a, f32x4 b) { u32x4 w; w.x = cvt_pk_bf16(a[0], a[1]); w.y = cvt_pk_bf16(a[2], a[3]); w.z = cvt_pk_bf16(b[0], b[1]); w.w = cvt_pk_bf16(b[2], b[3]); return w; }
;     __device__ __forceinline__ void operator()(const f32x4 (&acc)[2][2][4][2], const Unit& u, int wr, int wc, int fr, int fq, const EpiCtx& X) const {
;     ...
;             for (int m = 0; m < 4; ++m) {
;                 const int rl = ai * HALF + m * 16; const unsigned off = lo + (unsigned)(rl * 64) * 2u;
;                 const f32x4 o0a = acc[ai][0][m][0], o0b = acc[ai][0][m][1], o1a = acc[ai][1][m][0], o1b = acc[ai][1][m][1];
;                 const f32x4 ra_ = dpp_swap1(odd ? o0a : o1a), rb_ = dpp_swap1(odd ? o0b : o1b);
;                 const f32x4 pa[2] = {odd ? ra_ : o0a, odd ? o1a : ra_}, pb[2] = {odd ? rb_ : o0b, odd ? o1b : rb_};
; #pragma unroll
;                 for (int q = 0; q < 2; ++q) {
;                     const u32x4 w0 = raw[2 * m + q];
;                     const f32x4 r0 = (f32x4){bf_lo(w0.x), bf_hi(w0.x), bf_lo(w0.y), bf_hi(w0.y)}, r1 = (f32x4){bf_lo(w0.z), bf_hi(w0.z), bf_lo(w0.w), bf_hi(w0.w)};
;                     f32x4 y0, y1;
;                     if (RESN) { const f32x2 t = tbl[rl + q]; const float mu = t.x, ra = t.y * ALPHA; y0 = (r0 - mu) * ra * g0 + b0 + pa[q]; y1 = (r1 - mu) * ra * g1 + b1 + pb[q]; }
;                     else { y0 = r0 * ALPHA + pa[q]; y1 = r1 * ALPHA + pb[q]; }
;                     { const u32x4 w = pack8f(y0, y1); *(u32x4*)(xb + off + q * 128) = w;
;                         y0 = (f32x4){bf_lo(w.x), bf_hi(w.x), bf_lo(w.y), bf_hi(w.y)}; y1 = (f32x4){bf_lo(w.z), bf_hi(w.z), bf_lo(w.w), bf_hi(w.w)}; }
;                     float sa = ((y0[0] + y0[1]) + (y0[2] + y0[3])) + ((y1[0] + y1[1]) + (y1[2] + y1[3]));
;                     float sb = ((y0[0] * y0[0] + y0[1] * y0[1]) + (y0[2] * y0[2] + y0[3] * y0[3])) + ((y1[0] * y1[0] + y1[1] * y1[1]) + (y1[2] * y1[2] + y1[3] * y1[3]));
;                     sa += dpp_x1(sa);
;                     sb += dpp_x1(sb);
;                     sa += __shfl_xor(sa, 16); sa += __shfl_xor(sa, 32); sb += __shfl_xor(sb, 16); sb += __shfl_xor(sb, 32);
;                     if (fq == 0 && !odd) ps[(size_t)(rl + q) * 64] = (f32x2){sa, sb};
	v_mul_f32_e32 v98, 0x3fb504f3, v97
	v_sub_f32_e32 v101, v100, v96
	v_sub_f32_e32 v100, v99, v96
	v_pk_mul_f32 v[100:101], v[100:101], v[98:99] op_sel_hi:[1,0]
	v_sub_f32_e32 v103, v103, v96
	v_pk_fma_f32 v[100:101], v[76:77], v[100:101], v[184:185]
	v_sub_f32_e32 v102, v102, v96
	v_pk_add_f32 v[84:85], v[84:85], v[100:101]
	v_sub_f32_e32 v101, v105, v96
	v_sub_f32_e32 v100, v104, v96
	v_sub_f32_e32 v97, v107, v96
	v_sub_f32_e32 v96, v106, v96
	v_pk_mul_f32 v[102:103], v[102:103], v[98:99] op_sel_hi:[1,0]
	v_pk_mul_f32 v[96:97], v[96:97], v[98:99] op_sel_hi:[1,0]
	v_pk_mul_f32 v[98:99], v[100:101], v[98:99] op_sel_hi:[1,0]
	v_cndmask_b32_e64 v80, v92, v80, s[6:7]
	v_cndmask_b32_e64 v83, v95, v83, s[6:7]
	v_cndmask_b32_e64 v82, v93, v82, s[6:7]
	v_pk_fma_f32 v[102:103], v[78:79], v[102:103], v[182:183]
	v_pk_fma_f32 v[98:99], v[72:73], v[98:99], v[180:181]
	v_pk_fma_f32 v[96:97], v[74:75], v[96:97], v[178:179]
	v_pk_add_f32 v[86:87], v[86:87], v[102:103]
	v_pk_add_f32 v[82:83], v[82:83], v[96:97]
	v_pk_add_f32 v[80:81], v[80:81], v[98:99]
	v_cvt_pk_bf16_f32 v96, v84, v85
	v_cvt_pk_bf16_f32 v97, v86, v87
	v_mov_b32_e32 v189, v165
	v_cvt_pk_bf16_f32 v98, v80, v81
	v_cvt_pk_bf16_f32 v99, v82, v83
	v_lshlrev_b32_e32 v80, 16, v96
	v_and_b32_e32 v82, 0xffff0000, v96
	v_lshlrev_b32_e32 v84, 16, v97
	v_and_b32_e32 v86, 0xffff0000, v97
	v_lshlrev_b32_e32 v100, 16, v98
	v_and_b32_e32 v102, 0xffff0000, v98
	v_lshlrev_b32_e32 v104, 16, v99
	v_and_b32_e32 v106, 0xffff0000, v99
	v_mul_f32_e32 v81, v80, v80
	v_mul_f32_e32 v83, v82, v82
	v_mul_f32_e32 v85, v84, v84
	v_mul_f32_e32 v87, v86, v86
	v_mul_f32_e32 v101, v100, v100
	v_mul_f32_e32 v103, v102, v102
	v_mul_f32_e32 v105, v104, v104
	v_mul_f32_e32 v107, v106, v106
	v_pk_add_f32 v[80:81], v[80:81], v[82:83]
	v_pk_add_f32 v[82:83], v[84:85], v[86:87]
	v_pk_add_f32 v[84:85], v[104:105], v[106:107]
	v_pk_add_f32 v[80:81], v[80:81], v[82:83]
	v_pk_add_f32 v[82:83], v[100:101], v[102:103]
	s_nop 0
	v_pk_add_f32 v[82:83], v[82:83], v[84:85]
	s_nop 0
	v_pk_add_f32 v[80:81], v[80:81], v[82:83]
	v_mov_b32_e32 v82, v165
	v_mov_b32_e32 v83, v165
	s_nop 0
	v_mov_b32_dpp v82, v80 quad_perm:[1,0,3,2] row_mask:0xf bank_mask:0xf
	v_mov_b32_dpp v83, v81 quad_perm:[1,0,3,2] row_mask:0xf bank_mask:0xf
	v_pk_add_f32 v[80:81], v[80:81], v[82:83]
	ds_bpermute_b32 v82, v207, v80
	ds_bpermute_b32 v83, v207, v81
	s_waitcnt lgkmcnt(0)
	v_pk_add_f32 v[82:83], v[80:81], v[82:83]
	ds_bpermute_b32 v84, v208, v82
	ds_bpermute_b32 v85, v208, v83
	v_lshl_add_u64 v[80:81], s[16:17], 0, v[188:189]
	global_store_dwordx4 v[80:81], v[96:99], off
	s_and_saveexec_b64 s[56:57], s[12:13]
	s_waitcnt lgkmcnt(0)
	v_pk_add_f32 v[82:83], v[82:83], v[84:85]
	v_add_co_u32_e32 v84, vcc, 0x6000, v186
	s_nop 1
	v_addc_co_u32_e32 v85, vcc, 0, v187, vcc
	global_store_dwordx2 v[84:85], v[82:83], off
.LBB0_1711:
	s_or_b64 exec, exec, s[56:57]
	ds_read_b64 v[82:83], v201 offset:392
	s_waitcnt lgkmcnt(1)
	s_waitcnt vmcnt(18)
	v_lshlrev_b32_e32 v85, 16, v128
	v_and_b32_e32 v86, 0xffff0000, v128
	v_cndmask_b32_e64 v69, v69, v90, s[6:7]
	v_cndmask_b32_e64 v68, v68, v88, s[6:7]
	s_waitcnt lgkmcnt(0)
	v_mul_f32_e32 v84, 0x3fb504f3, v83
	v_sub_f32_e32 v87, v86, v82
	v_sub_f32_e32 v86, v85, v82
	v_pk_mul_f32 v[86:87], v[86:87], v[84:85] op_sel_hi:[1,0]
	v_cndmask_b32_e64 v71, v71, v91, s[6:7]
	v_cndmask_b32_e64 v70, v70, v89, s[6:7]
	v_cndmask_b32_e64 v64, v64, v92, s[6:7]
	v_cndmask_b32_e64 v66, v66, v93, s[6:7]
	v_lshlrev_b32_e32 v88, 16, v129
	v_and_b32_e32 v89, 0xffff0000, v129
	v_lshlrev_b32_e32 v90, 16, v130
	v_and_b32_e32 v91, 0xffff0000, v130
	v_lshlrev_b32_e32 v92, 16, v131
	v_and_b32_e32 v93, 0xffff0000, v131
	v_pk_fma_f32 v[86:87], v[76:77], v[86:87], v[184:185]
	v_sub_f32_e32 v89, v89, v82
	v_sub_f32_e32 v88, v88, v82
	v_pk_add_f32 v[68:69], v[68:69], v[86:87]
	v_sub_f32_e32 v87, v91, v82
	v_sub_f32_e32 v86, v90, v82
	v_sub_f32_e32 v83, v93, v82
	v_sub_f32_e32 v82, v92, v82
	v_pk_mul_f32 v[88:89], v[88:89], v[84:85] op_sel_hi:[1,0]
	v_pk_mul_f32 v[82:83], v[82:83], v[84:85] op_sel_hi:[1,0]
	v_pk_mul_f32 v[84:85], v[86:87], v[84:85] op_sel_hi:[1,0]
	v_cndmask_b32_e64 v65, v65, v94, s[6:7]
	v_cndmask_b32_e64 v67, v67, v95, s[6:7]
	v_pk_fma_f32 v[88:89], v[78:79], v[88:89], v[182:183]
	v_pk_fma_f32 v[84:85], v[72:73], v[84:85], v[180:181]
	v_pk_fma_f32 v[82:83], v[74:75], v[82:83], v[178:179]
	v_pk_add_f32 v[70:71], v[70:71], v[88:89]
	v_pk_add_f32 v[66:67], v[66:67], v[82:83]
	v_pk_add_f32 v[64:65], v[64:65], v[84:85]
	v_cvt_pk_bf16_f32 v68, v68, v69
	v_cvt_pk_bf16_f32 v69, v70, v71
	s_nop 0
	v_cvt_pk_bf16_f32 v70, v64, v65
	v_cvt_pk_bf16_f32 v71, v66, v67
	v_lshlrev_b32_e32 v64, 16, v68
	v_and_b32_e32 v66, 0xffff0000, v68
	v_lshlrev_b32_e32 v82, 16, v69
	v_and_b32_e32 v84, 0xffff0000, v69
	v_lshlrev_b32_e32 v86, 16, v70
	v_and_b32_e32 v88, 0xffff0000, v70
	v_lshlrev_b32_e32 v90, 16, v71
	v_and_b32_e32 v92, 0xffff0000, v71
	v_mul_f32_e32 v65, v64, v64
	v_mul_f32_e32 v67, v66, v66
	v_mul_f32_e32 v83, v82, v82
	v_mul_f32_e32 v85, v84, v84
	v_mul_f32_e32 v87, v86, v86
	v_mul_f32_e32 v89, v88, v88
	v_mul_f32_e32 v91, v90, v90
	v_mul_f32_e32 v93, v92, v92
	v_pk_add_f32 v[64:65], v[64:65], v[66:67]
	v_pk_add_f32 v[66:67], v[82:83], v[84:85]
	v_pk_add_f32 v[82:83], v[90:91], v[92:93]
	v_pk_add_f32 v[64:65], v[64:65], v[66:67]
	v_pk_add_f32 v[66:67], v[86:87], v[88:89]
	global_store_dwordx4 v[80:81], v[68:71], off offset:128
	v_pk_add_f32 v[66:67], v[66:67], v[82:83]
	s_nop 0
	v_pk_add_f32 v[64:65], v[64:65], v[66:67]
	v_mov_b32_e32 v66, v165
	v_mov_b32_e32 v67, v165
	s_nop 0
	v_mov_b32_dpp v66, v64 quad_perm:[1,0,3,2] row_mask:0xf bank_mask:0xf
	v_mov_b32_dpp v67, v65 quad_perm:[1,0,3,2] row_mask:0xf bank_mask:0xf
	v_pk_add_f32 v[64:65], v[64:65], v[66:67]
	ds_bpermute_b32 v66, v207, v64
	ds_bpermute_b32 v67, v207, v65
	s_waitcnt lgkmcnt(0)
	v_pk_add_f32 v[64:65], v[64:65], v[66:67]
	ds_bpermute_b32 v66, v208, v64
	ds_bpermute_b32 v67, v208, v65
	s_and_saveexec_b64 s[56:57], s[12:13]
	s_waitcnt lgkmcnt(0)
	v_pk_add_f32 v[64:65], v[64:65], v[66:67]
	v_add_co_u32_e32 v66, vcc, 0x6000, v186
	s_nop 1
	v_addc_co_u32_e32 v67, vcc, 0, v187, vcc
	global_store_dwordx2 v[66:67], v[64:65], off offset:512
;     __device__ __forceinline__ void operator()(const f32x4 (&acc)[2][2][4][2], const Unit& u, int wr, int wc, int fr, int fq, const EpiCtx& X) const {
;     ...
;         for (int ai = 0; ai < 2; ++ai) {
;             u32x4 raw[8];
; #pragma unroll
;             for (int m = 0; m < 4; ++m) { const unsigned off = lo + (unsigned)((ai * HALF + m * 16) * 64) * 2u; raw[2 * m] = *(const u32x4*)(xb + off); raw[2 * m + 1] = *(const u32x4*)(xb + off + 128); }
; #pragma unroll
;             for (int m = 0; m < 4; ++m) {
;                 const int rl = ai * HALF + m * 16; const unsigned off = lo + (unsigned)(rl * 64) * 2u;
;                 const f32x4 o0a = acc[ai][0][m][0], o0b = acc[ai][0][m][1], o1a = acc[ai][1][m][0], o1b = acc[ai][1][m][1];
;                 const f32x4 ra_ = dpp_swap1(odd ? o0a : o1a), rb_ = dpp_swap1(odd ? o0b : o1b);
;                 const f32x4 pa[2] = {odd ? ra_ : o0a, odd ? o1a : ra_}, pb[2] = {odd ? rb_ : o0b, odd ? o1b : rb_};
; #pragma unroll
;                 for (int q = 0; q < 2; ++q) {
;                     const u32x4 w0 = raw[2 * m + q];
;                     const f32x4 r0 = (f32x4){bf_lo(w0.x), bf_hi(w0.x), bf_lo(w0.y), bf_hi(w0.y)}, r1 = (f32x4){bf_lo(w0.z), bf_hi(w0.z), bf_lo(w0.w), bf_hi(w0.w)};
;                     f32x4 y0, y1;
;                     if (RESN) { const f32x2 t = tbl[rl + q]; const float mu = t.x, ra = t.y * ALPHA; y0 = (r0 - mu) * ra * g0 + b0 + pa[q]; y1 = (r1 - mu) * ra * g1 + b1 + pb[q]; }
;                     else { y0 = r0 * ALPHA + pa[q]; y1 = r1 * ALPHA + pb[q]; }
;                     { const u32x4 w = pack8f(y0, y1); *(u32x4*)(xb + off + q * 128) = w;
;                         y0 = (f32x4){bf_lo(w.x), bf_hi(w.x), bf_lo(w.y), bf_hi(w.y)}; y1 = (f32x4){bf_lo(w.z), bf_hi(w.z), bf_lo(w.w), bf_hi(w.w)}; }
;                     float sa = ((y0[0] + y0[1]) + (y0[2] + y0[3])) + ((y1[0] + y1[1]) + (y1[2] + y1[3]));
;                     float sb = ((y0[0] * y0[0] + y0[1] * y0[1]) + (y0[2] * y0[2] + y0[3] * y0[3])) + ((y1[0] * y1[0] + y1[1] * y1[1]) + (y1[2] * y1[2] + y1[3] * y1[3]));
;                     sa += dpp_x1(sa);
;                     sb += dpp_x1(sb);
;                     sa += __shfl_xor(sa, 16); sa += __shfl_xor(sa, 32); sb += __shfl_xor(sb, 16); sb += __shfl_xor(sb, 32);
;                     if (fq == 0 && !odd) ps[(size_t)(rl + q) * 64] = (f32x2){sa, sb};
.LBB0_1713:
	s_or_b64 exec, exec, s[56:57]
	v_add_u32_e32 v104, 0x4000, v164
	s_waitcnt vmcnt(16)
	v_mov_b32_e32 v112, v230
	v_mov_b32_e32 v113, v231
	v_mov_b32_e32 v114, v232
	v_mov_b32_e32 v115, v233
	v_add_u32_e32 v102, 0x4800, v164
	v_add_u32_e32 v100, 0x5000, v164
	v_add_u32_e32 v164, 0x5800, v164
	v_mov_b32_e32 v96, v234
	v_mov_b32_e32 v97, v235
	v_mov_b32_e32 v98, v236
	v_mov_b32_e32 v99, v237
	v_mov_b32_e32 v92, v238
	v_mov_b32_e32 v93, v239
	v_mov_b32_e32 v94, v240
	v_mov_b32_e32 v95, v241
	v_mov_b32_e32 v88, v242
	v_mov_b32_e32 v89, v243
	v_mov_b32_e32 v90, v244
	v_mov_b32_e32 v91, v245
	global_load_dwordx4 v[84:87], v100, s[16:17]
	global_load_dwordx4 v[80:83], v100, s[16:17] offset:128
	global_load_dwordx4 v[68:71], v164, s[16:17]
	s_waitcnt lgkmcnt(0)
	global_load_dwordx4 v[64:67], v164, s[16:17] offset:128
	v_cndmask_b32_e64 v116, v62, v54, s[6:7]
	v_cndmask_b32_e64 v117, v61, v53, s[6:7]
	v_mov_b32_e32 v105, 0
	v_mov_b32_e32 v103, 0
	v_cndmask_b32_e64 v111, v63, v55, s[6:7]
	v_mov_b32_dpp v105, v117 quad_perm:[1,0,3,2] row_mask:0xf bank_mask:0xf
	v_mov_b32_dpp v103, v116 quad_perm:[1,0,3,2] row_mask:0xf bank_mask:0xf
	ds_read_b64 v[116:117], v201 offset:1024
	v_cndmask_b32_e64 v118, v60, v52, s[6:7]
	v_mov_b32_e32 v101, 0
	v_mov_b32_e32 v106, 0
	v_cndmask_b32_e64 v119, v59, v51, s[6:7]
	v_cndmask_b32_e64 v120, v58, v50, s[6:7]
	v_cndmask_b32_e64 v121, v57, v49, s[6:7]
	v_cndmask_b32_e64 v122, v56, v48, s[6:7]
	v_mov_b32_e32 v107, 0
	v_mov_b32_e32 v109, 0
	v_mov_b32_e32 v108, 0
	v_mov_b32_e32 v110, 0
	v_mov_b32_dpp v101, v118 quad_perm:[1,0,3,2] row_mask:0xf bank_mask:0xf
	v_mov_b32_dpp v106, v111 quad_perm:[1,0,3,2] row_mask:0xf bank_mask:0xf
	v_mov_b32_dpp v107, v122 quad_perm:[1,0,3,2] row_mask:0xf bank_mask:0xf
	v_mov_b32_dpp v109, v121 quad_perm:[1,0,3,2] row_mask:0xf bank_mask:0xf
	v_mov_b32_dpp v108, v120 quad_perm:[1,0,3,2] row_mask:0xf bank_mask:0xf
	v_mov_b32_dpp v110, v119 quad_perm:[1,0,3,2] row_mask:0xf bank_mask:0xf
	s_waitcnt lgkmcnt(0)
	v_mul_f32_e32 v118, 0x3fb504f3, v117
	v_cndmask_b32_e64 v61, v105, v61, s[6:7]
	v_cndmask_b32_e64 v60, v101, v60, s[6:7]
	v_cndmask_b32_e64 v63, v106, v63, s[6:7]
	v_cndmask_b32_e64 v62, v103, v62, s[6:7]
	v_cndmask_b32_e64 v57, v109, v57, s[6:7]
	v_cndmask_b32_e64 v56, v107, v56, s[6:7]
	v_cndmask_b32_e64 v59, v110, v59, s[6:7]
	v_cndmask_b32_e64 v58, v108, v58, s[6:7]
	v_lshlrev_b32_e32 v111, 16, v112
	v_and_b32_e32 v112, 0xffff0000, v112
	v_lshlrev_b32_e32 v117, 16, v113
	v_and_b32_e32 v119, 0xffff0000, v113
	v_lshlrev_b32_e32 v120, 16, v114
	v_and_b32_e32 v121, 0xffff0000, v114
	v_lshlrev_b32_e32 v122, 16, v115
	v_and_b32_e32 v123, 0xffff0000, v115
	v_sub_f32_e32 v113, v112, v116
	v_sub_f32_e32 v112, v111, v116
	v_sub_f32_e32 v115, v119, v116
	v_sub_f32_e32 v114, v117, v116
	v_sub_f32_e32 v121, v121, v116
	v_sub_f32_e32 v120, v120, v116
	v_sub_f32_e32 v117, v123, v116
	v_sub_f32_e32 v116, v122, v116
	v_pk_mul_f32 v[114:115], v[114:115], v[118:119] op_sel_hi:[1,0]
	v_pk_mul_f32 v[112:113], v[112:113], v[118:119] op_sel_hi:[1,0]
	v_pk_mul_f32 v[116:117], v[116:117], v[118:119] op_sel_hi:[1,0]
	v_pk_mul_f32 v[118:119], v[120:121], v[118:119] op_sel_hi:[1,0]
	v_pk_fma_f32 v[112:113], v[76:77], v[112:113], v[184:185]
	v_pk_fma_f32 v[114:115], v[78:79], v[114:115], v[182:183]
	v_pk_fma_f32 v[118:119], v[72:73], v[118:119], v[180:181]
	v_pk_fma_f32 v[116:117], v[74:75], v[116:117], v[178:179]
	v_pk_add_f32 v[62:63], v[62:63], v[114:115]
	v_pk_add_f32 v[60:61], v[60:61], v[112:113]
	v_pk_add_f32 v[58:59], v[58:59], v[116:117]
	v_pk_add_f32 v[56:57], v[56:57], v[118:119]
	v_cvt_pk_bf16_f32 v60, v60, v61
	v_cvt_pk_bf16_f32 v61, v62, v63
	s_nop 0
	v_cvt_pk_bf16_f32 v62, v56, v57
	v_cvt_pk_bf16_f32 v63, v58, v59
	v_lshlrev_b32_e32 v56, 16, v60
	v_and_b32_e32 v58, 0xffff0000, v60
	v_lshlrev_b32_e32 v112, 16, v61
	v_and_b32_e32 v114, 0xffff0000, v61
	v_lshlrev_b32_e32 v116, 16, v62
	v_and_b32_e32 v118, 0xffff0000, v62
	v_lshlrev_b32_e32 v120, 16, v63
	v_and_b32_e32 v122, 0xffff0000, v63
	v_mul_f32_e32 v57, v56, v56
	v_mul_f32_e32 v59, v58, v58
	v_mul_f32_e32 v113, v112, v112
	v_mul_f32_e32 v115, v114, v114
	v_mul_f32_e32 v117, v116, v116
	v_mul_f32_e32 v119, v118, v118
	v_mul_f32_e32 v121, v120, v120
	v_mul_f32_e32 v123, v122, v122
	v_pk_add_f32 v[56:57], v[56:57], v[58:59]
	v_pk_add_f32 v[58:59], v[112:113], v[114:115]
	v_pk_add_f32 v[112:113], v[120:121], v[122:123]
	v_pk_add_f32 v[56:57], v[56:57], v[58:59]
	v_pk_add_f32 v[58:59], v[116:117], v[118:119]
	global_store_dwordx4 v104, v[60:63], s[16:17]
	v_pk_add_f32 v[58:59], v[58:59], v[112:113]
	s_nop 0
	v_pk_add_f32 v[56:57], v[56:57], v[58:59]
	v_mov_b32_e32 v58, v165
	v_mov_b32_e32 v59, v165
	s_nop 0
	v_mov_b32_dpp v58, v56 quad_perm:[1,0,3,2] row_mask:0xf bank_mask:0xf
	v_mov_b32_dpp v59, v57 quad_perm:[1,0,3,2] row_mask:0xf bank_mask:0xf
	v_pk_add_f32 v[56:57], v[56:57], v[58:59]
	ds_bpermute_b32 v58, v207, v56
	ds_bpermute_b32 v59, v207, v57
	s_waitcnt lgkmcnt(0)
	v_pk_add_f32 v[56:57], v[56:57], v[58:59]
	ds_bpermute_b32 v58, v208, v56
	ds_bpermute_b32 v59, v208, v57
	s_and_saveexec_b64 s[56:57], s[12:13]
	s_cbranch_execz .LBB0_1715
	s_waitcnt lgkmcnt(0)
	v_pk_add_f32 v[56:57], v[56:57], v[58:59]
	v_add_co_u32_e32 v58, vcc, 0x10000, v186
	s_nop 1
	v_addc_co_u32_e32 v59, vcc, 0, v187, vcc
	global_store_dwordx2 v[58:59], v[56:57], off
